# per-MFMA-block s_setprio flips removed from the GEMM K-loops (on top of the LayerNorm / swa_attn / ret_core edits)
# speedup vs baseline: 1.0056x; 1.0056x over previous
.LBB0_344:
	s_add_i32 s30, s8, 2
	s_add_u32 s9, s12, 0xfff80080
	s_addc_u32 s16, s13, -1
	s_add_i32 s31, 0, 0x10000
	s_cmp_eq_u32 s60, s8
	s_cselect_b32 s17, s53, s16
	s_cselect_b32 s16, s52, s9
	s_cselect_b32 s9, s2, s10
	s_cselect_b32 s8, s3, s7
	s_add_i32 s33, 0, 0x14000
	v_add_u32_e32 v140, s31, v162
	v_add_u32_e32 v168, s33, v162
	ds_read_b128 v[128:131], v140
	ds_read_b128 v[132:135], v140 offset:1024
	ds_read_b128 v[136:139], v140 offset:2048
	ds_read_b128 v[140:143], v140 offset:3072
	ds_read_b128 v[154:157], v168
	ds_read_b128 v[158:161], v168 offset:1024
	ds_read_b128 v[164:167], v168 offset:2048
	ds_read_b128 v[168:171], v168 offset:3072
	v_lshl_add_u64 v[204:205], s[12:13], 0, v[150:151]
	s_add_i32 m0, s28, 0xc000
	ds_read_b128 v[172:175], v163
	ds_read_b128 v[176:179], v163 offset:1024
	ds_read_b128 v[180:183], v163 offset:2048
	ds_read_b128 v[184:187], v163 offset:3072
	ds_read_b128 v[188:191], v163 offset:4096
	ds_read_b128 v[192:195], v163 offset:5120
	ds_read_b128 v[196:199], v163 offset:6144
	ds_read_b128 v[200:203], v163 offset:7168
	global_load_lds_dwordx4 v[204:205], off
	v_lshl_add_u64 v[204:205], s[12:13], 0, v[152:153]
	s_add_i32 m0, s28, 0xe000
	s_nop 0
	global_load_lds_dwordx4 v[204:205], off
	s_waitcnt vmcnt(8)
	s_waitcnt lgkmcnt(0)
	s_barrier
	s_waitcnt lgkmcnt(0)
	v_mfma_f32_16x16x32_bf16 v[112:115], v[128:131], v[172:175], v[112:115]
	v_mfma_f32_16x16x32_bf16 v[116:119], v[136:139], v[172:175], v[116:119]
	v_mfma_f32_16x16x32_bf16 v[96:99], v[128:131], v[180:183], v[96:99]
	v_mfma_f32_16x16x32_bf16 v[100:103], v[136:139], v[180:183], v[100:103]
	v_mfma_f32_16x16x32_bf16 v[80:83], v[128:131], v[188:191], v[80:83]
	v_mfma_f32_16x16x32_bf16 v[84:87], v[136:139], v[188:191], v[84:87]
	v_mfma_f32_16x16x32_bf16 v[48:51], v[128:131], v[196:199], v[48:51]
	v_mfma_f32_16x16x32_bf16 v[52:55], v[136:139], v[196:199], v[52:55]
	v_mfma_f32_16x16x32_bf16 v[112:115], v[132:135], v[176:179], v[112:115]
	v_mfma_f32_16x16x32_bf16 v[116:119], v[140:143], v[176:179], v[116:119]
	v_mfma_f32_16x16x32_bf16 v[96:99], v[132:135], v[184:187], v[96:99]
	v_mfma_f32_16x16x32_bf16 v[100:103], v[140:143], v[184:187], v[100:103]
	v_mfma_f32_16x16x32_bf16 v[80:83], v[132:135], v[192:195], v[80:83]
	v_mfma_f32_16x16x32_bf16 v[84:87], v[140:143], v[192:195], v[84:87]
	v_mfma_f32_16x16x32_bf16 v[48:51], v[132:135], v[200:203], v[48:51]
	v_mfma_f32_16x16x32_bf16 v[52:55], v[140:143], v[200:203], v[52:55]
	v_mfma_f32_16x16x32_bf16 v[120:123], v[154:157], v[172:175], v[120:123]
	v_mfma_f32_16x16x32_bf16 v[124:127], v[164:167], v[172:175], v[124:127]
	v_mfma_f32_16x16x32_bf16 v[104:107], v[154:157], v[180:183], v[104:107]
	v_mfma_f32_16x16x32_bf16 v[108:111], v[164:167], v[180:183], v[108:111]
	v_mfma_f32_16x16x32_bf16 v[88:91], v[154:157], v[188:191], v[88:91]
	v_mfma_f32_16x16x32_bf16 v[92:95], v[164:167], v[188:191], v[92:95]
	v_mfma_f32_16x16x32_bf16 v[64:67], v[154:157], v[196:199], v[64:67]
	v_mfma_f32_16x16x32_bf16 v[68:71], v[164:167], v[196:199], v[68:71]
	v_mfma_f32_16x16x32_bf16 v[120:123], v[158:161], v[176:179], v[120:123]
	v_mfma_f32_16x16x32_bf16 v[124:127], v[168:171], v[176:179], v[124:127]
	v_mfma_f32_16x16x32_bf16 v[104:107], v[158:161], v[184:187], v[104:107]
	v_mfma_f32_16x16x32_bf16 v[108:111], v[168:171], v[184:187], v[108:111]
	v_mfma_f32_16x16x32_bf16 v[88:91], v[158:161], v[192:195], v[88:91]
	v_mfma_f32_16x16x32_bf16 v[92:95], v[168:171], v[192:195], v[92:95]
	v_mfma_f32_16x16x32_bf16 v[64:67], v[158:161], v[200:203], v[64:67]
	v_mfma_f32_16x16x32_bf16 v[68:71], v[168:171], v[200:203], v[68:71]
	s_barrier
	s_add_i32 s31, s31, s26
	v_lshl_add_u64 v[204:205], s[8:9], 0, v[224:225]
	s_mov_b32 m0, s31
	ds_read_b128 v[172:175], v163 offset:16384
	ds_read_b128 v[176:179], v163 offset:17408
	ds_read_b128 v[180:183], v163 offset:18432
	ds_read_b128 v[184:187], v163 offset:19456
	ds_read_b128 v[188:191], v163 offset:20480
	ds_read_b128 v[192:195], v163 offset:21504
	ds_read_b128 v[196:199], v163 offset:22528
	ds_read_b128 v[200:203], v163 offset:23552
	global_load_lds_dwordx4 v[204:205], off
	s_add_i32 m0, s31, 0x2000
	s_add_u32 s40, s8, 0x80000
	v_lshl_add_u64 v[206:207], s[8:9], 0, v[144:145]
	s_addc_u32 s41, s9, 0
	s_add_i32 s31, s33, s26
	global_load_lds_dwordx4 v[206:207], off
	v_lshl_add_u64 v[208:209], s[40:41], 0, v[224:225]
	s_mov_b32 m0, s31
	v_lshl_add_u64 v[210:211], s[16:17], 0, v[146:147]
	global_load_lds_dwordx4 v[208:209], off
	v_lshl_add_u64 v[208:209], s[40:41], 0, v[144:145]
	s_add_i32 m0, s31, 0x2000
	s_nop 0
	global_load_lds_dwordx4 v[208:209], off
	v_lshl_add_u64 v[208:209], s[16:17], 0, v[148:149]
	s_mov_b32 m0, s28
	s_nop 0
	global_load_lds_dwordx4 v[208:209], off
	s_mov_b32 m0, s29
	s_nop 0
	global_load_lds_dwordx4 v[210:211], off
	s_waitcnt vmcnt(8)
	s_waitcnt lgkmcnt(0)
	s_barrier
	s_waitcnt lgkmcnt(0)
	v_mfma_f32_16x16x32_bf16 v[56:59], v[128:131], v[172:175], v[56:59]
	v_mfma_f32_16x16x32_bf16 v[60:63], v[136:139], v[172:175], v[60:63]
	v_mfma_f32_16x16x32_bf16 v[32:35], v[128:131], v[180:183], v[32:35]
	v_mfma_f32_16x16x32_bf16 v[36:39], v[136:139], v[180:183], v[36:39]
	v_mfma_f32_16x16x32_bf16 v[16:19], v[128:131], v[188:191], v[16:19]
	v_mfma_f32_16x16x32_bf16 v[20:23], v[136:139], v[188:191], v[20:23]
	v_mfma_f32_16x16x32_bf16 v[0:3], v[128:131], v[196:199], v[0:3]
	v_mfma_f32_16x16x32_bf16 v[4:7], v[136:139], v[196:199], v[4:7]
	v_mfma_f32_16x16x32_bf16 v[56:59], v[132:135], v[176:179], v[56:59]
	v_mfma_f32_16x16x32_bf16 v[60:63], v[140:143], v[176:179], v[60:63]
	v_mfma_f32_16x16x32_bf16 v[32:35], v[132:135], v[184:187], v[32:35]
	v_mfma_f32_16x16x32_bf16 v[36:39], v[140:143], v[184:187], v[36:39]
	v_mfma_f32_16x16x32_bf16 v[16:19], v[132:135], v[192:195], v[16:19]
	v_mfma_f32_16x16x32_bf16 v[20:23], v[140:143], v[192:195], v[20:23]
	v_mfma_f32_16x16x32_bf16 v[0:3], v[132:135], v[200:203], v[0:3]
	v_mfma_f32_16x16x32_bf16 v[4:7], v[140:143], v[200:203], v[4:7]
	v_mfma_f32_16x16x32_bf16 v[72:75], v[154:157], v[172:175], v[72:75]
	v_mfma_f32_16x16x32_bf16 v[76:79], v[164:167], v[172:175], v[76:79]
	v_mfma_f32_16x16x32_bf16 v[40:43], v[154:157], v[180:183], v[40:43]
	v_mfma_f32_16x16x32_bf16 v[44:47], v[164:167], v[180:183], v[44:47]
	v_mfma_f32_16x16x32_bf16 v[24:27], v[154:157], v[188:191], v[24:27]
	v_mfma_f32_16x16x32_bf16 v[28:31], v[164:167], v[188:191], v[28:31]
	v_mfma_f32_16x16x32_bf16 v[8:11], v[154:157], v[196:199], v[8:11]
	v_mfma_f32_16x16x32_bf16 v[12:15], v[164:167], v[196:199], v[12:15]
	v_mfma_f32_16x16x32_bf16 v[72:75], v[158:161], v[176:179], v[72:75]
	v_mfma_f32_16x16x32_bf16 v[76:79], v[168:171], v[176:179], v[76:79]
	v_mfma_f32_16x16x32_bf16 v[40:43], v[158:161], v[184:187], v[40:43]
	v_mfma_f32_16x16x32_bf16 v[44:47], v[168:171], v[184:187], v[44:47]
	v_mfma_f32_16x16x32_bf16 v[24:27], v[158:161], v[192:195], v[24:27]
	v_mfma_f32_16x16x32_bf16 v[28:31], v[168:171], v[192:195], v[28:31]
	v_mfma_f32_16x16x32_bf16 v[8:11], v[158:161], v[200:203], v[8:11]
	v_mfma_f32_16x16x32_bf16 v[12:15], v[168:171], v[200:203], v[12:15]
	s_barrier
	s_add_i32 s31, 0, 0x18000
	s_add_i32 s33, 0, 0x1c000
	v_add_u32_e32 v140, s31, v162
	v_add_u32_e32 v168, s33, v162
	ds_read_b128 v[128:131], v140
	ds_read_b128 v[132:135], v140 offset:1024
	ds_read_b128 v[136:139], v140 offset:2048
	ds_read_b128 v[140:143], v140 offset:3072
	ds_read_b128 v[154:157], v168
	ds_read_b128 v[158:161], v168 offset:1024
	ds_read_b128 v[164:167], v168 offset:2048
	ds_read_b128 v[168:171], v168 offset:3072
	s_add_u32 s16, s16, 0x80000
	s_addc_u32 s17, s17, 0
	s_mov_b32 m0, s34
	v_lshl_add_u64 v[212:213], s[16:17], 0, v[148:149]
	ds_read_b128 v[172:175], v163 offset:32768
	ds_read_b128 v[176:179], v163 offset:33792
	ds_read_b128 v[180:183], v163 offset:34816
	ds_read_b128 v[184:187], v163 offset:35840
	ds_read_b128 v[188:191], v163 offset:36864
	ds_read_b128 v[192:195], v163 offset:37888
	ds_read_b128 v[196:199], v163 offset:38912
	ds_read_b128 v[200:203], v163 offset:39936
	global_load_lds_dwordx4 v[212:213], off
	v_lshl_add_u64 v[212:213], s[16:17], 0, v[146:147]
	s_mov_b32 m0, s35
	s_nop 0
	global_load_lds_dwordx4 v[212:213], off
	s_waitcnt vmcnt(8)
	s_waitcnt lgkmcnt(0)
	s_barrier
	s_waitcnt lgkmcnt(0)
	v_mfma_f32_16x16x32_bf16 v[112:115], v[128:131], v[172:175], v[112:115]
	v_mfma_f32_16x16x32_bf16 v[116:119], v[136:139], v[172:175], v[116:119]
	v_mfma_f32_16x16x32_bf16 v[96:99], v[128:131], v[180:183], v[96:99]
	v_mfma_f32_16x16x32_bf16 v[100:103], v[136:139], v[180:183], v[100:103]
	v_mfma_f32_16x16x32_bf16 v[80:83], v[128:131], v[188:191], v[80:83]
	v_mfma_f32_16x16x32_bf16 v[84:87], v[136:139], v[188:191], v[84:87]
	v_mfma_f32_16x16x32_bf16 v[48:51], v[128:131], v[196:199], v[48:51]
	v_mfma_f32_16x16x32_bf16 v[52:55], v[136:139], v[196:199], v[52:55]
	v_mfma_f32_16x16x32_bf16 v[112:115], v[132:135], v[176:179], v[112:115]
	v_mfma_f32_16x16x32_bf16 v[116:119], v[140:143], v[176:179], v[116:119]
	v_mfma_f32_16x16x32_bf16 v[96:99], v[132:135], v[184:187], v[96:99]
	v_mfma_f32_16x16x32_bf16 v[100:103], v[140:143], v[184:187], v[100:103]
	v_mfma_f32_16x16x32_bf16 v[80:83], v[132:135], v[192:195], v[80:83]
	v_mfma_f32_16x16x32_bf16 v[84:87], v[140:143], v[192:195], v[84:87]
	v_mfma_f32_16x16x32_bf16 v[48:51], v[132:135], v[200:203], v[48:51]
	v_mfma_f32_16x16x32_bf16 v[52:55], v[140:143], v[200:203], v[52:55]
	v_mfma_f32_16x16x32_bf16 v[120:123], v[154:157], v[172:175], v[120:123]
	v_mfma_f32_16x16x32_bf16 v[124:127], v[164:167], v[172:175], v[124:127]
	v_mfma_f32_16x16x32_bf16 v[104:107], v[154:157], v[180:183], v[104:107]
	v_mfma_f32_16x16x32_bf16 v[108:111], v[164:167], v[180:183], v[108:111]
	v_mfma_f32_16x16x32_bf16 v[88:91], v[154:157], v[188:191], v[88:91]
	v_mfma_f32_16x16x32_bf16 v[92:95], v[164:167], v[188:191], v[92:95]
	v_mfma_f32_16x16x32_bf16 v[64:67], v[154:157], v[196:199], v[64:67]
	v_mfma_f32_16x16x32_bf16 v[68:71], v[164:167], v[196:199], v[68:71]
	v_mfma_f32_16x16x32_bf16 v[120:123], v[158:161], v[176:179], v[120:123]
	v_mfma_f32_16x16x32_bf16 v[124:127], v[168:171], v[176:179], v[124:127]
	v_mfma_f32_16x16x32_bf16 v[104:107], v[158:161], v[184:187], v[104:107]
	v_mfma_f32_16x16x32_bf16 v[108:111], v[168:171], v[184:187], v[108:111]
	v_mfma_f32_16x16x32_bf16 v[88:91], v[158:161], v[192:195], v[88:91]
	v_mfma_f32_16x16x32_bf16 v[92:95], v[168:171], v[192:195], v[92:95]
	v_mfma_f32_16x16x32_bf16 v[64:67], v[158:161], v[200:203], v[64:67]
	v_mfma_f32_16x16x32_bf16 v[68:71], v[168:171], v[200:203], v[68:71]
	s_barrier
	s_add_i32 s16, s31, s26
	v_lshl_add_u64 v[204:205], v[204:205], 0, s[24:25]
	s_mov_b32 m0, s16
	ds_read_b128 v[172:175], v163 offset:49152
	ds_read_b128 v[176:179], v163 offset:50176
	ds_read_b128 v[180:183], v163 offset:51200
	ds_read_b128 v[184:187], v163 offset:52224
	ds_read_b128 v[188:191], v163 offset:53248
	ds_read_b128 v[192:195], v163 offset:54272
	ds_read_b128 v[196:199], v163 offset:55296
	ds_read_b128 v[200:203], v163 offset:56320
	global_load_lds_dwordx4 v[204:205], off
	s_add_i32 m0, s16, 0x2000
	s_add_u32 s8, s8, 0x80080
	v_lshl_add_u64 v[204:205], v[206:207], 0, s[24:25]
	s_addc_u32 s9, s9, 0
	s_add_i32 s16, s33, s26
	global_load_lds_dwordx4 v[204:205], off
	v_lshl_add_u64 v[204:205], s[8:9], 0, v[224:225]
	s_mov_b32 m0, s16
	s_nop 0
	global_load_lds_dwordx4 v[204:205], off
	v_lshl_add_u64 v[204:205], s[8:9], 0, v[144:145]
	s_add_i32 m0, s16, 0x2000
	s_nop 0
	global_load_lds_dwordx4 v[204:205], off
	v_lshl_add_u64 v[204:205], v[208:209], 0, s[24:25]
	s_mov_b32 m0, s58
	s_nop 0
	global_load_lds_dwordx4 v[204:205], off
	v_lshl_add_u64 v[204:205], v[210:211], 0, s[24:25]
	s_mov_b32 m0, s59
	s_nop 0
	global_load_lds_dwordx4 v[204:205], off
	s_waitcnt vmcnt(8)
	s_waitcnt lgkmcnt(0)
	s_barrier
	s_waitcnt lgkmcnt(0)
	v_mfma_f32_16x16x32_bf16 v[56:59], v[128:131], v[172:175], v[56:59]
	v_mfma_f32_16x16x32_bf16 v[60:63], v[136:139], v[172:175], v[60:63]
	v_mfma_f32_16x16x32_bf16 v[32:35], v[128:131], v[180:183], v[32:35]
	v_mfma_f32_16x16x32_bf16 v[36:39], v[136:139], v[180:183], v[36:39]
	v_mfma_f32_16x16x32_bf16 v[16:19], v[128:131], v[188:191], v[16:19]
	v_mfma_f32_16x16x32_bf16 v[20:23], v[136:139], v[188:191], v[20:23]
	v_mfma_f32_16x16x32_bf16 v[0:3], v[128:131], v[196:199], v[0:3]
	v_mfma_f32_16x16x32_bf16 v[4:7], v[136:139], v[196:199], v[4:7]
	v_mfma_f32_16x16x32_bf16 v[56:59], v[132:135], v[176:179], v[56:59]
	v_mfma_f32_16x16x32_bf16 v[60:63], v[140:143], v[176:179], v[60:63]
	v_mfma_f32_16x16x32_bf16 v[32:35], v[132:135], v[184:187], v[32:35]
	v_mfma_f32_16x16x32_bf16 v[36:39], v[140:143], v[184:187], v[36:39]
	v_mfma_f32_16x16x32_bf16 v[16:19], v[132:135], v[192:195], v[16:19]
	v_mfma_f32_16x16x32_bf16 v[20:23], v[140:143], v[192:195], v[20:23]
	v_mfma_f32_16x16x32_bf16 v[0:3], v[132:135], v[200:203], v[0:3]
	v_mfma_f32_16x16x32_bf16 v[4:7], v[140:143], v[200:203], v[4:7]
	v_mfma_f32_16x16x32_bf16 v[72:75], v[154:157], v[172:175], v[72:75]
	v_mfma_f32_16x16x32_bf16 v[76:79], v[164:167], v[172:175], v[76:79]
	v_mfma_f32_16x16x32_bf16 v[40:43], v[154:157], v[180:183], v[40:43]
	v_mfma_f32_16x16x32_bf16 v[44:47], v[164:167], v[180:183], v[44:47]
	v_mfma_f32_16x16x32_bf16 v[24:27], v[154:157], v[188:191], v[24:27]
	v_mfma_f32_16x16x32_bf16 v[28:31], v[164:167], v[188:191], v[28:31]
	v_mfma_f32_16x16x32_bf16 v[8:11], v[154:157], v[196:199], v[8:11]
	v_mfma_f32_16x16x32_bf16 v[12:15], v[164:167], v[196:199], v[12:15]
	v_mfma_f32_16x16x32_bf16 v[72:75], v[158:161], v[176:179], v[72:75]
	v_mfma_f32_16x16x32_bf16 v[76:79], v[168:171], v[176:179], v[76:79]
	v_mfma_f32_16x16x32_bf16 v[40:43], v[158:161], v[184:187], v[40:43]
	v_mfma_f32_16x16x32_bf16 v[44:47], v[168:171], v[184:187], v[44:47]
	v_mfma_f32_16x16x32_bf16 v[24:27], v[158:161], v[192:195], v[24:27]
	v_mfma_f32_16x16x32_bf16 v[28:31], v[168:171], v[192:195], v[28:31]
	v_mfma_f32_16x16x32_bf16 v[8:11], v[158:161], v[200:203], v[8:11]
	v_mfma_f32_16x16x32_bf16 v[12:15], v[168:171], v[200:203], v[12:15]
	s_barrier
	s_add_u32 s12, s12, 0x100
	s_addc_u32 s13, s13, 0
	s_add_u32 s7, s7, 0x100
	s_addc_u32 s10, s10, 0
	s_cmp_ge_i32 s30, s57
	s_mov_b32 s8, s30
	s_cbranch_scc0 .LBB0_344

.LBB0_920:
	s_add_i32 s33, s8, 2
	s_add_u32 s9, s12, 0xffff0080
	s_addc_u32 s20, s13, -1
	s_add_i32 s61, 0, 0x10000
	s_cmp_eq_u32 s59, s8
	s_cselect_b32 s21, s3, s20
	s_cselect_b32 s20, s7, s9
	s_cselect_b32 s9, s23, s31
	s_cselect_b32 s8, s27, s30
	s_add_i32 s64, 0, 0x14000
	v_add_u32_e32 v150, s61, v170
	v_add_u32_e32 v166, s64, v170
	ds_read_b128 v[128:131], v150
	ds_read_b128 v[132:135], v150 offset:1024
	ds_read_b128 v[146:149], v150 offset:2048
	ds_read_b128 v[150:153], v150 offset:3072
	ds_read_b128 v[154:157], v166
	ds_read_b128 v[158:161], v166 offset:1024
	ds_read_b128 v[162:165], v166 offset:2048
	ds_read_b128 v[166:169], v166 offset:3072
	v_lshl_add_u64 v[204:205], s[12:13], 0, v[142:143]
	s_add_i32 m0, s49, 0xc000
	ds_read_b128 v[172:175], v171
	ds_read_b128 v[176:179], v171 offset:1024
	ds_read_b128 v[180:183], v171 offset:2048
	ds_read_b128 v[184:187], v171 offset:3072
	ds_read_b128 v[188:191], v171 offset:4096
	ds_read_b128 v[192:195], v171 offset:5120
	ds_read_b128 v[196:199], v171 offset:6144
	ds_read_b128 v[200:203], v171 offset:7168
	global_load_lds_dwordx4 v[204:205], off
	v_lshl_add_u64 v[204:205], s[12:13], 0, v[144:145]
	s_add_i32 m0, s49, 0xe000
	s_nop 0
	global_load_lds_dwordx4 v[204:205], off
	s_waitcnt vmcnt(8)
	s_waitcnt lgkmcnt(0)
	s_barrier
	s_waitcnt lgkmcnt(0)
	v_mfma_f32_16x16x32_bf16 v[120:123], v[128:131], v[172:175], v[120:123]
	v_mfma_f32_16x16x32_bf16 v[124:127], v[146:149], v[172:175], v[124:127]
	v_mfma_f32_16x16x32_bf16 v[116:119], v[128:131], v[180:183], v[116:119]
	v_mfma_f32_16x16x32_bf16 v[112:115], v[146:149], v[180:183], v[112:115]
	v_mfma_f32_16x16x32_bf16 v[108:111], v[128:131], v[188:191], v[108:111]
	v_mfma_f32_16x16x32_bf16 v[104:107], v[146:149], v[188:191], v[104:107]
	v_mfma_f32_16x16x32_bf16 v[100:103], v[128:131], v[196:199], v[100:103]
	v_mfma_f32_16x16x32_bf16 v[96:99], v[146:149], v[196:199], v[96:99]
	v_mfma_f32_16x16x32_bf16 v[120:123], v[132:135], v[176:179], v[120:123]
	v_mfma_f32_16x16x32_bf16 v[124:127], v[150:153], v[176:179], v[124:127]
	v_mfma_f32_16x16x32_bf16 v[116:119], v[132:135], v[184:187], v[116:119]
	v_mfma_f32_16x16x32_bf16 v[112:115], v[150:153], v[184:187], v[112:115]
	v_mfma_f32_16x16x32_bf16 v[108:111], v[132:135], v[192:195], v[108:111]
	v_mfma_f32_16x16x32_bf16 v[104:107], v[150:153], v[192:195], v[104:107]
	v_mfma_f32_16x16x32_bf16 v[100:103], v[132:135], v[200:203], v[100:103]
	v_mfma_f32_16x16x32_bf16 v[96:99], v[150:153], v[200:203], v[96:99]
	v_mfma_f32_16x16x32_bf16 v[60:63], v[154:157], v[172:175], v[60:63]
	v_mfma_f32_16x16x32_bf16 v[56:59], v[162:165], v[172:175], v[56:59]
	v_mfma_f32_16x16x32_bf16 v[52:55], v[154:157], v[180:183], v[52:55]
	v_mfma_f32_16x16x32_bf16 v[48:51], v[162:165], v[180:183], v[48:51]
	v_mfma_f32_16x16x32_bf16 v[44:47], v[154:157], v[188:191], v[44:47]
	v_mfma_f32_16x16x32_bf16 v[40:43], v[162:165], v[188:191], v[40:43]
	v_mfma_f32_16x16x32_bf16 v[36:39], v[154:157], v[196:199], v[36:39]
	v_mfma_f32_16x16x32_bf16 v[32:35], v[162:165], v[196:199], v[32:35]
	v_mfma_f32_16x16x32_bf16 v[60:63], v[158:161], v[176:179], v[60:63]
	v_mfma_f32_16x16x32_bf16 v[56:59], v[166:169], v[176:179], v[56:59]
	v_mfma_f32_16x16x32_bf16 v[52:55], v[158:161], v[184:187], v[52:55]
	v_mfma_f32_16x16x32_bf16 v[48:51], v[166:169], v[184:187], v[48:51]
	v_mfma_f32_16x16x32_bf16 v[44:47], v[158:161], v[192:195], v[44:47]
	v_mfma_f32_16x16x32_bf16 v[40:43], v[166:169], v[192:195], v[40:43]
	v_mfma_f32_16x16x32_bf16 v[36:39], v[158:161], v[200:203], v[36:39]
	v_mfma_f32_16x16x32_bf16 v[32:35], v[166:169], v[200:203], v[32:35]
	s_barrier
	s_add_i32 s61, s61, s35
	v_lshl_add_u64 v[204:205], s[8:9], 0, v[224:225]
	s_mov_b32 m0, s61
	ds_read_b128 v[172:175], v171 offset:16384
	ds_read_b128 v[176:179], v171 offset:17408
	ds_read_b128 v[180:183], v171 offset:18432
	ds_read_b128 v[184:187], v171 offset:19456
	ds_read_b128 v[188:191], v171 offset:20480
	ds_read_b128 v[192:195], v171 offset:21504
	ds_read_b128 v[196:199], v171 offset:22528
	ds_read_b128 v[200:203], v171 offset:23552
	global_load_lds_dwordx4 v[204:205], off
	s_add_i32 m0, s61, 0x2000
	s_add_u32 s62, s8, 0x10000
	v_lshl_add_u64 v[206:207], s[8:9], 0, v[136:137]
	s_addc_u32 s63, s9, 0
	s_add_i32 s61, s64, s35
	global_load_lds_dwordx4 v[206:207], off
	v_lshl_add_u64 v[208:209], s[62:63], 0, v[224:225]
	s_mov_b32 m0, s61
	v_lshl_add_u64 v[210:211], s[20:21], 0, v[138:139]
	global_load_lds_dwordx4 v[208:209], off
	v_lshl_add_u64 v[208:209], s[62:63], 0, v[136:137]
	s_add_i32 m0, s61, 0x2000
	s_nop 0
	global_load_lds_dwordx4 v[208:209], off
	v_lshl_add_u64 v[208:209], s[20:21], 0, v[140:141]
	s_mov_b32 m0, s49
	s_nop 0
	global_load_lds_dwordx4 v[208:209], off
	s_mov_b32 m0, s50
	s_nop 0
	global_load_lds_dwordx4 v[210:211], off
	s_waitcnt vmcnt(8)
	s_waitcnt lgkmcnt(0)
	s_barrier
	s_waitcnt lgkmcnt(0)
	v_mfma_f32_16x16x32_bf16 v[92:95], v[128:131], v[172:175], v[92:95]
	v_mfma_f32_16x16x32_bf16 v[88:91], v[146:149], v[172:175], v[88:91]
	v_mfma_f32_16x16x32_bf16 v[84:87], v[128:131], v[180:183], v[84:87]
	v_mfma_f32_16x16x32_bf16 v[80:83], v[146:149], v[180:183], v[80:83]
	v_mfma_f32_16x16x32_bf16 v[76:79], v[128:131], v[188:191], v[76:79]
	v_mfma_f32_16x16x32_bf16 v[72:75], v[146:149], v[188:191], v[72:75]
	v_mfma_f32_16x16x32_bf16 v[68:71], v[128:131], v[196:199], v[68:71]
	v_mfma_f32_16x16x32_bf16 v[64:67], v[146:149], v[196:199], v[64:67]
	v_mfma_f32_16x16x32_bf16 v[92:95], v[132:135], v[176:179], v[92:95]
	v_mfma_f32_16x16x32_bf16 v[88:91], v[150:153], v[176:179], v[88:91]
	v_mfma_f32_16x16x32_bf16 v[84:87], v[132:135], v[184:187], v[84:87]
	v_mfma_f32_16x16x32_bf16 v[80:83], v[150:153], v[184:187], v[80:83]
	v_mfma_f32_16x16x32_bf16 v[76:79], v[132:135], v[192:195], v[76:79]
	v_mfma_f32_16x16x32_bf16 v[72:75], v[150:153], v[192:195], v[72:75]
	v_mfma_f32_16x16x32_bf16 v[68:71], v[132:135], v[200:203], v[68:71]
	v_mfma_f32_16x16x32_bf16 v[64:67], v[150:153], v[200:203], v[64:67]
	v_mfma_f32_16x16x32_bf16 v[28:31], v[154:157], v[172:175], v[28:31]
	v_mfma_f32_16x16x32_bf16 v[24:27], v[162:165], v[172:175], v[24:27]
	v_mfma_f32_16x16x32_bf16 v[20:23], v[154:157], v[180:183], v[20:23]
	v_mfma_f32_16x16x32_bf16 v[16:19], v[162:165], v[180:183], v[16:19]
	v_mfma_f32_16x16x32_bf16 v[12:15], v[154:157], v[188:191], v[12:15]
	v_mfma_f32_16x16x32_bf16 v[8:11], v[162:165], v[188:191], v[8:11]
	v_mfma_f32_16x16x32_bf16 v[4:7], v[154:157], v[196:199], v[4:7]
	v_mfma_f32_16x16x32_bf16 v[0:3], v[162:165], v[196:199], v[0:3]
	v_mfma_f32_16x16x32_bf16 v[28:31], v[158:161], v[176:179], v[28:31]
	v_mfma_f32_16x16x32_bf16 v[24:27], v[166:169], v[176:179], v[24:27]
	v_mfma_f32_16x16x32_bf16 v[20:23], v[158:161], v[184:187], v[20:23]
	v_mfma_f32_16x16x32_bf16 v[16:19], v[166:169], v[184:187], v[16:19]
	v_mfma_f32_16x16x32_bf16 v[12:15], v[158:161], v[192:195], v[12:15]
	v_mfma_f32_16x16x32_bf16 v[8:11], v[166:169], v[192:195], v[8:11]
	v_mfma_f32_16x16x32_bf16 v[4:7], v[158:161], v[200:203], v[4:7]
	v_mfma_f32_16x16x32_bf16 v[0:3], v[166:169], v[200:203], v[0:3]
	s_barrier
	s_add_i32 s61, 0, 0x18000
	s_add_i32 s62, 0, 0x1c000
	v_add_u32_e32 v150, s61, v170
	v_add_u32_e32 v166, s62, v170
	ds_read_b128 v[128:131], v150
	ds_read_b128 v[132:135], v150 offset:1024
	ds_read_b128 v[146:149], v150 offset:2048
	ds_read_b128 v[150:153], v150 offset:3072
	ds_read_b128 v[154:157], v166
	ds_read_b128 v[158:161], v166 offset:1024
	ds_read_b128 v[162:165], v166 offset:2048
	ds_read_b128 v[166:169], v166 offset:3072
	s_add_u32 s20, s20, 0x10000
	s_addc_u32 s21, s21, 0
	s_mov_b32 m0, s51
	v_lshl_add_u64 v[212:213], s[20:21], 0, v[140:141]
	ds_read_b128 v[172:175], v171 offset:32768
	ds_read_b128 v[176:179], v171 offset:33792
	ds_read_b128 v[180:183], v171 offset:34816
	ds_read_b128 v[184:187], v171 offset:35840
	ds_read_b128 v[188:191], v171 offset:36864
	ds_read_b128 v[192:195], v171 offset:37888
	ds_read_b128 v[196:199], v171 offset:38912
	ds_read_b128 v[200:203], v171 offset:39936
	global_load_lds_dwordx4 v[212:213], off
	v_lshl_add_u64 v[212:213], s[20:21], 0, v[138:139]
	s_mov_b32 m0, s52
	s_nop 0
	global_load_lds_dwordx4 v[212:213], off
	s_waitcnt vmcnt(8)
	s_waitcnt lgkmcnt(0)
	s_barrier
	s_waitcnt lgkmcnt(0)
	v_mfma_f32_16x16x32_bf16 v[120:123], v[128:131], v[172:175], v[120:123]
	v_mfma_f32_16x16x32_bf16 v[124:127], v[146:149], v[172:175], v[124:127]
	v_mfma_f32_16x16x32_bf16 v[116:119], v[128:131], v[180:183], v[116:119]
	v_mfma_f32_16x16x32_bf16 v[112:115], v[146:149], v[180:183], v[112:115]
	v_mfma_f32_16x16x32_bf16 v[108:111], v[128:131], v[188:191], v[108:111]
	v_mfma_f32_16x16x32_bf16 v[104:107], v[146:149], v[188:191], v[104:107]
	v_mfma_f32_16x16x32_bf16 v[100:103], v[128:131], v[196:199], v[100:103]
	v_mfma_f32_16x16x32_bf16 v[96:99], v[146:149], v[196:199], v[96:99]
	v_mfma_f32_16x16x32_bf16 v[120:123], v[132:135], v[176:179], v[120:123]
	v_mfma_f32_16x16x32_bf16 v[124:127], v[150:153], v[176:179], v[124:127]
	v_mfma_f32_16x16x32_bf16 v[116:119], v[132:135], v[184:187], v[116:119]
	v_mfma_f32_16x16x32_bf16 v[112:115], v[150:153], v[184:187], v[112:115]
	v_mfma_f32_16x16x32_bf16 v[108:111], v[132:135], v[192:195], v[108:111]
	v_mfma_f32_16x16x32_bf16 v[104:107], v[150:153], v[192:195], v[104:107]
	v_mfma_f32_16x16x32_bf16 v[100:103], v[132:135], v[200:203], v[100:103]
	v_mfma_f32_16x16x32_bf16 v[96:99], v[150:153], v[200:203], v[96:99]
	v_mfma_f32_16x16x32_bf16 v[60:63], v[154:157], v[172:175], v[60:63]
	v_mfma_f32_16x16x32_bf16 v[56:59], v[162:165], v[172:175], v[56:59]
	v_mfma_f32_16x16x32_bf16 v[52:55], v[154:157], v[180:183], v[52:55]
	v_mfma_f32_16x16x32_bf16 v[48:51], v[162:165], v[180:183], v[48:51]
	v_mfma_f32_16x16x32_bf16 v[44:47], v[154:157], v[188:191], v[44:47]
	v_mfma_f32_16x16x32_bf16 v[40:43], v[162:165], v[188:191], v[40:43]
	v_mfma_f32_16x16x32_bf16 v[36:39], v[154:157], v[196:199], v[36:39]
	v_mfma_f32_16x16x32_bf16 v[32:35], v[162:165], v[196:199], v[32:35]
	v_mfma_f32_16x16x32_bf16 v[60:63], v[158:161], v[176:179], v[60:63]
	v_mfma_f32_16x16x32_bf16 v[56:59], v[166:169], v[176:179], v[56:59]
	v_mfma_f32_16x16x32_bf16 v[52:55], v[158:161], v[184:187], v[52:55]
	v_mfma_f32_16x16x32_bf16 v[48:51], v[166:169], v[184:187], v[48:51]
	v_mfma_f32_16x16x32_bf16 v[44:47], v[158:161], v[192:195], v[44:47]
	v_mfma_f32_16x16x32_bf16 v[40:43], v[166:169], v[192:195], v[40:43]
	v_mfma_f32_16x16x32_bf16 v[36:39], v[158:161], v[200:203], v[36:39]
	v_mfma_f32_16x16x32_bf16 v[32:35], v[166:169], v[200:203], v[32:35]
	s_barrier
	s_add_i32 s20, s61, s35
	v_lshl_add_u64 v[204:205], v[204:205], 0, s[24:25]
	s_mov_b32 m0, s20
	ds_read_b128 v[172:175], v171 offset:49152
	ds_read_b128 v[176:179], v171 offset:50176
	ds_read_b128 v[180:183], v171 offset:51200
	ds_read_b128 v[184:187], v171 offset:52224
	ds_read_b128 v[188:191], v171 offset:53248
	ds_read_b128 v[192:195], v171 offset:54272
	ds_read_b128 v[196:199], v171 offset:55296
	ds_read_b128 v[200:203], v171 offset:56320
	global_load_lds_dwordx4 v[204:205], off
	s_add_i32 m0, s20, 0x2000
	s_add_u32 s8, s8, 0x10080
	v_lshl_add_u64 v[204:205], v[206:207], 0, s[24:25]
	s_addc_u32 s9, s9, 0
	s_add_i32 s20, s62, s35
	global_load_lds_dwordx4 v[204:205], off
	v_lshl_add_u64 v[204:205], s[8:9], 0, v[224:225]
	s_mov_b32 m0, s20
	s_nop 0
	global_load_lds_dwordx4 v[204:205], off
	v_lshl_add_u64 v[204:205], s[8:9], 0, v[136:137]
	s_add_i32 m0, s20, 0x2000
	s_nop 0
	global_load_lds_dwordx4 v[204:205], off
	v_lshl_add_u64 v[204:205], v[208:209], 0, s[24:25]
	s_mov_b32 m0, s57
	s_nop 0
	global_load_lds_dwordx4 v[204:205], off
	v_lshl_add_u64 v[204:205], v[210:211], 0, s[24:25]
	s_mov_b32 m0, s58
	s_nop 0
	global_load_lds_dwordx4 v[204:205], off
	s_waitcnt vmcnt(8)
	s_waitcnt lgkmcnt(0)
	s_barrier
	s_waitcnt lgkmcnt(0)
	v_mfma_f32_16x16x32_bf16 v[92:95], v[128:131], v[172:175], v[92:95]
	v_mfma_f32_16x16x32_bf16 v[88:91], v[146:149], v[172:175], v[88:91]
	v_mfma_f32_16x16x32_bf16 v[84:87], v[128:131], v[180:183], v[84:87]
	v_mfma_f32_16x16x32_bf16 v[80:83], v[146:149], v[180:183], v[80:83]
	v_mfma_f32_16x16x32_bf16 v[76:79], v[128:131], v[188:191], v[76:79]
	v_mfma_f32_16x16x32_bf16 v[72:75], v[146:149], v[188:191], v[72:75]
	v_mfma_f32_16x16x32_bf16 v[68:71], v[128:131], v[196:199], v[68:71]
	v_mfma_f32_16x16x32_bf16 v[64:67], v[146:149], v[196:199], v[64:67]
	v_mfma_f32_16x16x32_bf16 v[92:95], v[132:135], v[176:179], v[92:95]
	v_mfma_f32_16x16x32_bf16 v[88:91], v[150:153], v[176:179], v[88:91]
	v_mfma_f32_16x16x32_bf16 v[84:87], v[132:135], v[184:187], v[84:87]
	v_mfma_f32_16x16x32_bf16 v[80:83], v[150:153], v[184:187], v[80:83]
	v_mfma_f32_16x16x32_bf16 v[76:79], v[132:135], v[192:195], v[76:79]
	v_mfma_f32_16x16x32_bf16 v[72:75], v[150:153], v[192:195], v[72:75]
	v_mfma_f32_16x16x32_bf16 v[68:71], v[132:135], v[200:203], v[68:71]
	v_mfma_f32_16x16x32_bf16 v[64:67], v[150:153], v[200:203], v[64:67]
	v_mfma_f32_16x16x32_bf16 v[28:31], v[154:157], v[172:175], v[28:31]
	v_mfma_f32_16x16x32_bf16 v[24:27], v[162:165], v[172:175], v[24:27]
	v_mfma_f32_16x16x32_bf16 v[20:23], v[154:157], v[180:183], v[20:23]
	v_mfma_f32_16x16x32_bf16 v[16:19], v[162:165], v[180:183], v[16:19]
	v_mfma_f32_16x16x32_bf16 v[12:15], v[154:157], v[188:191], v[12:15]
	v_mfma_f32_16x16x32_bf16 v[8:11], v[162:165], v[188:191], v[8:11]
	v_mfma_f32_16x16x32_bf16 v[4:7], v[154:157], v[196:199], v[4:7]
	v_mfma_f32_16x16x32_bf16 v[0:3], v[162:165], v[196:199], v[0:3]
	v_mfma_f32_16x16x32_bf16 v[28:31], v[158:161], v[176:179], v[28:31]
	v_mfma_f32_16x16x32_bf16 v[24:27], v[166:169], v[176:179], v[24:27]
	v_mfma_f32_16x16x32_bf16 v[20:23], v[158:161], v[184:187], v[20:23]
	v_mfma_f32_16x16x32_bf16 v[16:19], v[166:169], v[184:187], v[16:19]
	v_mfma_f32_16x16x32_bf16 v[12:15], v[158:161], v[192:195], v[12:15]
	v_mfma_f32_16x16x32_bf16 v[8:11], v[166:169], v[192:195], v[8:11]
	v_mfma_f32_16x16x32_bf16 v[4:7], v[158:161], v[200:203], v[4:7]
	v_mfma_f32_16x16x32_bf16 v[0:3], v[166:169], v[200:203], v[0:3]
	s_barrier
	s_add_u32 s12, s12, 0x100
	s_addc_u32 s13, s13, 0
	s_add_u32 s30, s30, 0x100
	s_addc_u32 s31, s31, 0
	s_cmp_ge_i32 s33, s56
	s_mov_b32 s8, s33
	s_cbranch_scc0 .LBB0_920
	v_readlane_b32 s64, v253, 21
	v_readlane_b32 s63, v253, 24
	v_readlane_b32 s65, v253, 22

.LBB0_1313:
	s_add_i32 s56, s8, 2
	s_add_u32 s9, s12, 0xfff80080
	s_addc_u32 s28, s13, -1
	s_add_i32 s57, 0, 0x10000
	s_cmp_eq_u32 s48, s8
	s_cselect_b32 s29, s27, s28
	s_cselect_b32 s28, s35, s9
	v_add_u32_e32 v138, s57, v139
	s_cselect_b32 s9, s52, s55
	s_cselect_b32 s8, s53, s54
	s_add_i32 s60, 0, 0x14000
	ds_read_b128 v[140:143], v138
	ds_read_b128 v[146:149], v138 offset:1024
	ds_read_b128 v[150:153], v138 offset:2048
	ds_read_b128 v[154:157], v138 offset:3072
	v_add_u32_e32 v138, s60, v139
	ds_read_b128 v[158:161], v138
	ds_read_b128 v[162:165], v138 offset:1024
	ds_read_b128 v[166:169], v138 offset:2048
	ds_read_b128 v[170:173], v138 offset:3072
	v_lshl_add_u64 v[206:207], s[12:13], 0, v[134:135]
	s_add_i32 m0, s31, 0xc000
	ds_read_b128 v[174:177], v144
	ds_read_b128 v[178:181], v144 offset:1024
	ds_read_b128 v[182:185], v144 offset:2048
	ds_read_b128 v[186:189], v144 offset:3072
	ds_read_b128 v[190:193], v144 offset:4096
	ds_read_b128 v[194:197], v144 offset:5120
	ds_read_b128 v[198:201], v144 offset:6144
	ds_read_b128 v[202:205], v144 offset:7168
	global_load_lds_dwordx4 v[206:207], off
	v_lshl_add_u64 v[206:207], s[12:13], 0, v[136:137]
	s_add_i32 m0, s31, 0xe000
	s_nop 0
	global_load_lds_dwordx4 v[206:207], off
	s_waitcnt vmcnt(8)
	s_waitcnt lgkmcnt(0)
	s_barrier
	s_waitcnt lgkmcnt(0)
	v_mfma_f32_16x16x32_bf16 v[116:119], v[140:143], v[174:177], v[116:119]
	v_mfma_f32_16x16x32_bf16 v[112:115], v[150:153], v[174:177], v[112:115]
	v_mfma_f32_16x16x32_bf16 v[100:103], v[140:143], v[182:185], v[100:103]
	v_mfma_f32_16x16x32_bf16 v[96:99], v[150:153], v[182:185], v[96:99]
	v_mfma_f32_16x16x32_bf16 v[84:87], v[140:143], v[190:193], v[84:87]
	v_mfma_f32_16x16x32_bf16 v[80:83], v[150:153], v[190:193], v[80:83]
	v_mfma_f32_16x16x32_bf16 v[68:71], v[140:143], v[198:201], v[68:71]
	v_mfma_f32_16x16x32_bf16 v[60:63], v[150:153], v[198:201], v[60:63]
	v_mfma_f32_16x16x32_bf16 v[116:119], v[146:149], v[178:181], v[116:119]
	v_mfma_f32_16x16x32_bf16 v[112:115], v[154:157], v[178:181], v[112:115]
	v_mfma_f32_16x16x32_bf16 v[100:103], v[146:149], v[186:189], v[100:103]
	v_mfma_f32_16x16x32_bf16 v[96:99], v[154:157], v[186:189], v[96:99]
	v_mfma_f32_16x16x32_bf16 v[84:87], v[146:149], v[194:197], v[84:87]
	v_mfma_f32_16x16x32_bf16 v[80:83], v[154:157], v[194:197], v[80:83]
	v_mfma_f32_16x16x32_bf16 v[68:71], v[146:149], v[202:205], v[68:71]
	v_mfma_f32_16x16x32_bf16 v[60:63], v[154:157], v[202:205], v[60:63]
	v_mfma_f32_16x16x32_bf16 v[124:127], v[158:161], v[174:177], v[124:127]
	v_mfma_f32_16x16x32_bf16 v[120:123], v[166:169], v[174:177], v[120:123]
	v_mfma_f32_16x16x32_bf16 v[108:111], v[158:161], v[182:185], v[108:111]
	v_mfma_f32_16x16x32_bf16 v[104:107], v[166:169], v[182:185], v[104:107]
	v_mfma_f32_16x16x32_bf16 v[92:95], v[158:161], v[190:193], v[92:95]
	v_mfma_f32_16x16x32_bf16 v[88:91], v[166:169], v[190:193], v[88:91]
	v_mfma_f32_16x16x32_bf16 v[76:79], v[158:161], v[198:201], v[76:79]
	v_mfma_f32_16x16x32_bf16 v[72:75], v[166:169], v[198:201], v[72:75]
	v_mfma_f32_16x16x32_bf16 v[124:127], v[162:165], v[178:181], v[124:127]
	v_mfma_f32_16x16x32_bf16 v[120:123], v[170:173], v[178:181], v[120:123]
	v_mfma_f32_16x16x32_bf16 v[108:111], v[162:165], v[186:189], v[108:111]
	v_mfma_f32_16x16x32_bf16 v[104:107], v[170:173], v[186:189], v[104:107]
	v_mfma_f32_16x16x32_bf16 v[92:95], v[162:165], v[194:197], v[92:95]
	v_mfma_f32_16x16x32_bf16 v[88:91], v[170:173], v[194:197], v[88:91]
	v_mfma_f32_16x16x32_bf16 v[76:79], v[162:165], v[202:205], v[76:79]
	v_mfma_f32_16x16x32_bf16 v[72:75], v[170:173], v[202:205], v[72:75]
	s_barrier
	s_add_i32 s57, s57, s10
	v_lshl_add_u64 v[206:207], s[8:9], 0, v[224:225]
	s_mov_b32 m0, s57
	ds_read_b128 v[174:177], v144 offset:16384
	ds_read_b128 v[178:181], v144 offset:17408
	ds_read_b128 v[182:185], v144 offset:18432
	ds_read_b128 v[186:189], v144 offset:19456
	ds_read_b128 v[190:193], v144 offset:20480
	ds_read_b128 v[194:197], v144 offset:21504
	ds_read_b128 v[198:201], v144 offset:22528
	ds_read_b128 v[202:205], v144 offset:23552
	global_load_lds_dwordx4 v[206:207], off
	s_add_i32 m0, s57, 0x2000
	s_add_u32 s58, s8, 0x80000
	v_lshl_add_u64 v[208:209], s[8:9], 0, v[128:129]
	s_addc_u32 s59, s9, 0
	s_add_i32 s57, s60, s10
	global_load_lds_dwordx4 v[208:209], off
	v_lshl_add_u64 v[210:211], s[58:59], 0, v[224:225]
	s_mov_b32 m0, s57
	v_lshl_add_u64 v[212:213], s[28:29], 0, v[130:131]
	global_load_lds_dwordx4 v[210:211], off
	v_lshl_add_u64 v[210:211], s[58:59], 0, v[128:129]
	s_add_i32 m0, s57, 0x2000
	s_nop 0
	global_load_lds_dwordx4 v[210:211], off
	v_lshl_add_u64 v[210:211], s[28:29], 0, v[132:133]
	s_mov_b32 m0, s31
	s_nop 0
	global_load_lds_dwordx4 v[210:211], off
	s_mov_b32 m0, s33
	s_nop 0
	global_load_lds_dwordx4 v[212:213], off
	s_waitcnt vmcnt(8)
	s_waitcnt lgkmcnt(0)
	s_barrier
	s_waitcnt lgkmcnt(0)
	v_mfma_f32_16x16x32_bf16 v[52:55], v[140:143], v[174:177], v[52:55]
	v_mfma_f32_16x16x32_bf16 v[48:51], v[150:153], v[174:177], v[48:51]
	v_mfma_f32_16x16x32_bf16 v[36:39], v[140:143], v[182:185], v[36:39]
	v_mfma_f32_16x16x32_bf16 v[32:35], v[150:153], v[182:185], v[32:35]
	v_mfma_f32_16x16x32_bf16 v[20:23], v[140:143], v[190:193], v[20:23]
	v_mfma_f32_16x16x32_bf16 v[16:19], v[150:153], v[190:193], v[16:19]
	v_mfma_f32_16x16x32_bf16 v[4:7], v[140:143], v[198:201], v[4:7]
	v_mfma_f32_16x16x32_bf16 v[0:3], v[150:153], v[198:201], v[0:3]
	v_mfma_f32_16x16x32_bf16 v[52:55], v[146:149], v[178:181], v[52:55]
	v_mfma_f32_16x16x32_bf16 v[48:51], v[154:157], v[178:181], v[48:51]
	v_mfma_f32_16x16x32_bf16 v[36:39], v[146:149], v[186:189], v[36:39]
	v_mfma_f32_16x16x32_bf16 v[32:35], v[154:157], v[186:189], v[32:35]
	v_mfma_f32_16x16x32_bf16 v[20:23], v[146:149], v[194:197], v[20:23]
	v_mfma_f32_16x16x32_bf16 v[16:19], v[154:157], v[194:197], v[16:19]
	v_mfma_f32_16x16x32_bf16 v[4:7], v[146:149], v[202:205], v[4:7]
	v_mfma_f32_16x16x32_bf16 v[0:3], v[154:157], v[202:205], v[0:3]
	v_mfma_f32_16x16x32_bf16 v[64:67], v[158:161], v[174:177], v[64:67]
	v_mfma_f32_16x16x32_bf16 v[56:59], v[166:169], v[174:177], v[56:59]
	v_mfma_f32_16x16x32_bf16 v[44:47], v[158:161], v[182:185], v[44:47]
	v_mfma_f32_16x16x32_bf16 v[40:43], v[166:169], v[182:185], v[40:43]
	v_mfma_f32_16x16x32_bf16 v[28:31], v[158:161], v[190:193], v[28:31]
	v_mfma_f32_16x16x32_bf16 v[24:27], v[166:169], v[190:193], v[24:27]
	v_mfma_f32_16x16x32_bf16 v[8:11], v[158:161], v[198:201], v[8:11]
	v_mfma_f32_16x16x32_bf16 v[12:15], v[166:169], v[198:201], v[12:15]
	v_mfma_f32_16x16x32_bf16 v[64:67], v[162:165], v[178:181], v[64:67]
	v_mfma_f32_16x16x32_bf16 v[56:59], v[170:173], v[178:181], v[56:59]
	v_mfma_f32_16x16x32_bf16 v[44:47], v[162:165], v[186:189], v[44:47]
	v_mfma_f32_16x16x32_bf16 v[40:43], v[170:173], v[186:189], v[40:43]
	v_mfma_f32_16x16x32_bf16 v[28:31], v[162:165], v[194:197], v[28:31]
	v_mfma_f32_16x16x32_bf16 v[24:27], v[170:173], v[194:197], v[24:27]
	v_mfma_f32_16x16x32_bf16 v[8:11], v[162:165], v[202:205], v[8:11]
	v_mfma_f32_16x16x32_bf16 v[12:15], v[170:173], v[202:205], v[12:15]
	s_barrier
	s_add_i32 s57, 0, 0x18000
	v_add_u32_e32 v138, s57, v139
	s_add_i32 s58, 0, 0x1c000
	ds_read_b128 v[140:143], v138
	ds_read_b128 v[146:149], v138 offset:1024
	ds_read_b128 v[150:153], v138 offset:2048
	ds_read_b128 v[154:157], v138 offset:3072
	v_add_u32_e32 v138, s58, v139
	ds_read_b128 v[158:161], v138
	ds_read_b128 v[162:165], v138 offset:1024
	ds_read_b128 v[166:169], v138 offset:2048
	ds_read_b128 v[170:173], v138 offset:3072
	s_add_u32 s28, s28, 0x80000
	s_addc_u32 s29, s29, 0
	s_mov_b32 m0, s42
	v_lshl_add_u64 v[214:215], s[28:29], 0, v[132:133]
	ds_read_b128 v[174:177], v144 offset:32768
	ds_read_b128 v[178:181], v144 offset:33792
	ds_read_b128 v[182:185], v144 offset:34816
	ds_read_b128 v[186:189], v144 offset:35840
	ds_read_b128 v[190:193], v144 offset:36864
	ds_read_b128 v[194:197], v144 offset:37888
	ds_read_b128 v[198:201], v144 offset:38912
	ds_read_b128 v[202:205], v144 offset:39936
	global_load_lds_dwordx4 v[214:215], off
	v_lshl_add_u64 v[214:215], s[28:29], 0, v[130:131]
	s_mov_b32 m0, s43
	s_nop 0
	global_load_lds_dwordx4 v[214:215], off
	s_waitcnt vmcnt(8)
	s_waitcnt lgkmcnt(0)
	s_barrier
	s_waitcnt lgkmcnt(0)
	v_mfma_f32_16x16x32_bf16 v[116:119], v[140:143], v[174:177], v[116:119]
	v_mfma_f32_16x16x32_bf16 v[112:115], v[150:153], v[174:177], v[112:115]
	v_mfma_f32_16x16x32_bf16 v[100:103], v[140:143], v[182:185], v[100:103]
	v_mfma_f32_16x16x32_bf16 v[96:99], v[150:153], v[182:185], v[96:99]
	v_mfma_f32_16x16x32_bf16 v[84:87], v[140:143], v[190:193], v[84:87]
	v_mfma_f32_16x16x32_bf16 v[80:83], v[150:153], v[190:193], v[80:83]
	v_mfma_f32_16x16x32_bf16 v[68:71], v[140:143], v[198:201], v[68:71]
	v_mfma_f32_16x16x32_bf16 v[60:63], v[150:153], v[198:201], v[60:63]
	v_mfma_f32_16x16x32_bf16 v[116:119], v[146:149], v[178:181], v[116:119]
	v_mfma_f32_16x16x32_bf16 v[112:115], v[154:157], v[178:181], v[112:115]
	v_mfma_f32_16x16x32_bf16 v[100:103], v[146:149], v[186:189], v[100:103]
	v_mfma_f32_16x16x32_bf16 v[96:99], v[154:157], v[186:189], v[96:99]
	v_mfma_f32_16x16x32_bf16 v[84:87], v[146:149], v[194:197], v[84:87]
	v_mfma_f32_16x16x32_bf16 v[80:83], v[154:157], v[194:197], v[80:83]
	v_mfma_f32_16x16x32_bf16 v[68:71], v[146:149], v[202:205], v[68:71]
	v_mfma_f32_16x16x32_bf16 v[60:63], v[154:157], v[202:205], v[60:63]
	v_mfma_f32_16x16x32_bf16 v[124:127], v[158:161], v[174:177], v[124:127]
	v_mfma_f32_16x16x32_bf16 v[120:123], v[166:169], v[174:177], v[120:123]
	v_mfma_f32_16x16x32_bf16 v[108:111], v[158:161], v[182:185], v[108:111]
	v_mfma_f32_16x16x32_bf16 v[104:107], v[166:169], v[182:185], v[104:107]
	v_mfma_f32_16x16x32_bf16 v[92:95], v[158:161], v[190:193], v[92:95]
	v_mfma_f32_16x16x32_bf16 v[88:91], v[166:169], v[190:193], v[88:91]
	v_mfma_f32_16x16x32_bf16 v[76:79], v[158:161], v[198:201], v[76:79]
	v_mfma_f32_16x16x32_bf16 v[72:75], v[166:169], v[198:201], v[72:75]
	v_mfma_f32_16x16x32_bf16 v[124:127], v[162:165], v[178:181], v[124:127]
	v_mfma_f32_16x16x32_bf16 v[120:123], v[170:173], v[178:181], v[120:123]
	v_mfma_f32_16x16x32_bf16 v[108:111], v[162:165], v[186:189], v[108:111]
	v_mfma_f32_16x16x32_bf16 v[104:107], v[170:173], v[186:189], v[104:107]
	v_mfma_f32_16x16x32_bf16 v[92:95], v[162:165], v[194:197], v[92:95]
	v_mfma_f32_16x16x32_bf16 v[88:91], v[170:173], v[194:197], v[88:91]
	v_mfma_f32_16x16x32_bf16 v[76:79], v[162:165], v[202:205], v[76:79]
	v_mfma_f32_16x16x32_bf16 v[72:75], v[170:173], v[202:205], v[72:75]
	s_barrier
	s_add_i32 s28, s57, s10
	v_lshl_add_u64 v[206:207], v[206:207], 0, s[24:25]
	s_mov_b32 m0, s28
	ds_read_b128 v[174:177], v144 offset:49152
	ds_read_b128 v[178:181], v144 offset:50176
	ds_read_b128 v[182:185], v144 offset:51200
	ds_read_b128 v[186:189], v144 offset:52224
	ds_read_b128 v[190:193], v144 offset:53248
	ds_read_b128 v[194:197], v144 offset:54272
	ds_read_b128 v[198:201], v144 offset:55296
	ds_read_b128 v[202:205], v144 offset:56320
	global_load_lds_dwordx4 v[206:207], off
	s_add_i32 m0, s28, 0x2000
	s_add_u32 s8, s8, 0x80080
	v_lshl_add_u64 v[206:207], v[208:209], 0, s[24:25]
	s_addc_u32 s9, s9, 0
	s_add_i32 s28, s58, s10
	global_load_lds_dwordx4 v[206:207], off
	v_lshl_add_u64 v[206:207], s[8:9], 0, v[224:225]
	s_mov_b32 m0, s28
	s_nop 0
	global_load_lds_dwordx4 v[206:207], off
	v_lshl_add_u64 v[206:207], s[8:9], 0, v[128:129]
	s_add_i32 m0, s28, 0x2000
	s_nop 0
	global_load_lds_dwordx4 v[206:207], off
	v_lshl_add_u64 v[206:207], v[210:211], 0, s[24:25]
	s_mov_b32 m0, s46
	s_nop 0
	global_load_lds_dwordx4 v[206:207], off
	v_lshl_add_u64 v[206:207], v[212:213], 0, s[24:25]
	s_mov_b32 m0, s47
	s_nop 0
	global_load_lds_dwordx4 v[206:207], off
	s_waitcnt vmcnt(8)
	s_waitcnt lgkmcnt(0)
	s_barrier
	s_waitcnt lgkmcnt(0)
	v_mfma_f32_16x16x32_bf16 v[52:55], v[140:143], v[174:177], v[52:55]
	v_mfma_f32_16x16x32_bf16 v[48:51], v[150:153], v[174:177], v[48:51]
	v_mfma_f32_16x16x32_bf16 v[36:39], v[140:143], v[182:185], v[36:39]
	v_mfma_f32_16x16x32_bf16 v[32:35], v[150:153], v[182:185], v[32:35]
	v_mfma_f32_16x16x32_bf16 v[20:23], v[140:143], v[190:193], v[20:23]
	v_mfma_f32_16x16x32_bf16 v[16:19], v[150:153], v[190:193], v[16:19]
	v_mfma_f32_16x16x32_bf16 v[4:7], v[140:143], v[198:201], v[4:7]
	v_mfma_f32_16x16x32_bf16 v[0:3], v[150:153], v[198:201], v[0:3]
	v_mfma_f32_16x16x32_bf16 v[52:55], v[146:149], v[178:181], v[52:55]
	v_mfma_f32_16x16x32_bf16 v[48:51], v[154:157], v[178:181], v[48:51]
	v_mfma_f32_16x16x32_bf16 v[36:39], v[146:149], v[186:189], v[36:39]
	v_mfma_f32_16x16x32_bf16 v[32:35], v[154:157], v[186:189], v[32:35]
	v_mfma_f32_16x16x32_bf16 v[20:23], v[146:149], v[194:197], v[20:23]
	v_mfma_f32_16x16x32_bf16 v[16:19], v[154:157], v[194:197], v[16:19]
	v_mfma_f32_16x16x32_bf16 v[4:7], v[146:149], v[202:205], v[4:7]
	v_mfma_f32_16x16x32_bf16 v[0:3], v[154:157], v[202:205], v[0:3]
	v_mfma_f32_16x16x32_bf16 v[64:67], v[158:161], v[174:177], v[64:67]
	v_mfma_f32_16x16x32_bf16 v[56:59], v[166:169], v[174:177], v[56:59]
	v_mfma_f32_16x16x32_bf16 v[44:47], v[158:161], v[182:185], v[44:47]
	v_mfma_f32_16x16x32_bf16 v[40:43], v[166:169], v[182:185], v[40:43]
	v_mfma_f32_16x16x32_bf16 v[28:31], v[158:161], v[190:193], v[28:31]
	v_mfma_f32_16x16x32_bf16 v[24:27], v[166:169], v[190:193], v[24:27]
	v_mfma_f32_16x16x32_bf16 v[8:11], v[158:161], v[198:201], v[8:11]
	v_mfma_f32_16x16x32_bf16 v[12:15], v[166:169], v[198:201], v[12:15]
	v_mfma_f32_16x16x32_bf16 v[64:67], v[162:165], v[178:181], v[64:67]
	v_mfma_f32_16x16x32_bf16 v[56:59], v[170:173], v[178:181], v[56:59]
	v_mfma_f32_16x16x32_bf16 v[44:47], v[162:165], v[186:189], v[44:47]
	v_mfma_f32_16x16x32_bf16 v[40:43], v[170:173], v[186:189], v[40:43]
	v_mfma_f32_16x16x32_bf16 v[28:31], v[162:165], v[194:197], v[28:31]
	v_mfma_f32_16x16x32_bf16 v[24:27], v[170:173], v[194:197], v[24:27]
	v_mfma_f32_16x16x32_bf16 v[8:11], v[162:165], v[202:205], v[8:11]
	v_mfma_f32_16x16x32_bf16 v[12:15], v[170:173], v[202:205], v[12:15]
	s_barrier
	s_add_u32 s12, s12, 0x100
	s_addc_u32 s13, s13, 0
	s_add_u32 s54, s54, 0x100
	s_addc_u32 s55, s55, 0
	s_cmp_ge_i32 s56, s45
	s_mov_b32 s8, s56
	s_cbranch_scc0 .LBB0_1313
	s_mov_b32 s53, 0x5040100
	s_mov_b64 s[56:57], 0x400000
	s_mov_b64 s[58:59], 0x3fffff
	s_mov_b64 s[60:61], 0x20000

.LBB0_1626:
	s_add_i32 s33, s8, 2
	s_add_u32 s9, s12, 0xfff80080
	s_addc_u32 s28, s13, -1
	s_add_i32 s40, 0, 0x10000
	s_cmp_eq_u32 s68, s8
	s_cselect_b32 s29, s3, s28
	s_cselect_b32 s28, s7, s9
	s_cselect_b32 s9, s10, s31
	s_cselect_b32 s8, s21, s30
	s_add_i32 s43, 0, 0x14000
	v_add_u32_e32 v140, s40, v200
	v_add_u32_e32 v156, s43, v200
	ds_read_b128 v[128:131], v140
	ds_read_b128 v[132:135], v140 offset:1024
	ds_read_b128 v[136:139], v140 offset:2048
	ds_read_b128 v[140:143], v140 offset:3072
	ds_read_b128 v[144:147], v156
	ds_read_b128 v[148:151], v156 offset:1024
	ds_read_b128 v[152:155], v156 offset:2048
	ds_read_b128 v[156:159], v156 offset:3072
	v_lshl_add_u64 v[206:207], s[12:13], 0, v[184:185]
	s_add_i32 m0, s56, 0xc000
	ds_read_b128 v[160:163], v201
	ds_read_b128 v[164:167], v201 offset:1024
	ds_read_b128 v[168:171], v201 offset:2048
	ds_read_b128 v[172:175], v201 offset:3072
	ds_read_b128 v[188:191], v201 offset:4096
	ds_read_b128 v[192:195], v201 offset:5120
	ds_read_b128 v[196:199], v201 offset:6144
	ds_read_b128 v[202:205], v201 offset:7168
	global_load_lds_dwordx4 v[206:207], off
	v_lshl_add_u64 v[206:207], s[12:13], 0, v[186:187]
	s_add_i32 m0, s56, 0xe000
	s_nop 0
	global_load_lds_dwordx4 v[206:207], off
	s_waitcnt vmcnt(8)
	s_waitcnt lgkmcnt(0)
	s_barrier
	s_waitcnt lgkmcnt(0)
	v_mfma_f32_16x16x32_bf16 v[112:115], v[128:131], v[160:163], v[112:115]
	v_mfma_f32_16x16x32_bf16 v[116:119], v[136:139], v[160:163], v[116:119]
	v_mfma_f32_16x16x32_bf16 v[100:103], v[128:131], v[168:171], v[100:103]
	v_mfma_f32_16x16x32_bf16 v[96:99], v[136:139], v[168:171], v[96:99]
	v_mfma_f32_16x16x32_bf16 v[84:87], v[128:131], v[188:191], v[84:87]
	v_mfma_f32_16x16x32_bf16 v[80:83], v[136:139], v[188:191], v[80:83]
	v_mfma_f32_16x16x32_bf16 v[68:71], v[128:131], v[196:199], v[68:71]
	v_mfma_f32_16x16x32_bf16 v[64:67], v[136:139], v[196:199], v[64:67]
	v_mfma_f32_16x16x32_bf16 v[112:115], v[132:135], v[164:167], v[112:115]
	v_mfma_f32_16x16x32_bf16 v[116:119], v[140:143], v[164:167], v[116:119]
	v_mfma_f32_16x16x32_bf16 v[100:103], v[132:135], v[172:175], v[100:103]
	v_mfma_f32_16x16x32_bf16 v[96:99], v[140:143], v[172:175], v[96:99]
	v_mfma_f32_16x16x32_bf16 v[84:87], v[132:135], v[192:195], v[84:87]
	v_mfma_f32_16x16x32_bf16 v[80:83], v[140:143], v[192:195], v[80:83]
	v_mfma_f32_16x16x32_bf16 v[68:71], v[132:135], v[202:205], v[68:71]
	v_mfma_f32_16x16x32_bf16 v[64:67], v[140:143], v[202:205], v[64:67]
	v_mfma_f32_16x16x32_bf16 v[120:123], v[144:147], v[160:163], v[120:123]
	v_mfma_f32_16x16x32_bf16 v[124:127], v[152:155], v[160:163], v[124:127]
	v_mfma_f32_16x16x32_bf16 v[108:111], v[144:147], v[168:171], v[108:111]
	v_mfma_f32_16x16x32_bf16 v[104:107], v[152:155], v[168:171], v[104:107]
	v_mfma_f32_16x16x32_bf16 v[92:95], v[144:147], v[188:191], v[92:95]
	v_mfma_f32_16x16x32_bf16 v[88:91], v[152:155], v[188:191], v[88:91]
	v_mfma_f32_16x16x32_bf16 v[76:79], v[144:147], v[196:199], v[76:79]
	v_mfma_f32_16x16x32_bf16 v[72:75], v[152:155], v[196:199], v[72:75]
	v_mfma_f32_16x16x32_bf16 v[120:123], v[148:151], v[164:167], v[120:123]
	v_mfma_f32_16x16x32_bf16 v[124:127], v[156:159], v[164:167], v[124:127]
	v_mfma_f32_16x16x32_bf16 v[108:111], v[148:151], v[172:175], v[108:111]
	v_mfma_f32_16x16x32_bf16 v[104:107], v[156:159], v[172:175], v[104:107]
	v_mfma_f32_16x16x32_bf16 v[92:95], v[148:151], v[192:195], v[92:95]
	v_mfma_f32_16x16x32_bf16 v[88:91], v[156:159], v[192:195], v[88:91]
	v_mfma_f32_16x16x32_bf16 v[76:79], v[148:151], v[202:205], v[76:79]
	v_mfma_f32_16x16x32_bf16 v[72:75], v[156:159], v[202:205], v[72:75]
	s_barrier
	s_add_i32 s40, s40, s54
	v_lshl_add_u64 v[206:207], s[8:9], 0, v[180:181]
	s_mov_b32 m0, s40
	ds_read_b128 v[160:163], v201 offset:16384
	ds_read_b128 v[164:167], v201 offset:17408
	ds_read_b128 v[168:171], v201 offset:18432
	ds_read_b128 v[172:175], v201 offset:19456
	ds_read_b128 v[188:191], v201 offset:20480
	ds_read_b128 v[192:195], v201 offset:21504
	ds_read_b128 v[196:199], v201 offset:22528
	ds_read_b128 v[202:205], v201 offset:23552
	global_load_lds_dwordx4 v[206:207], off
	s_add_i32 m0, s40, 0x2000
	s_add_u32 s40, s8, 0x80000
	v_lshl_add_u64 v[208:209], s[8:9], 0, v[176:177]
	s_addc_u32 s41, s9, 0
	s_add_i32 s43, s43, s54
	global_load_lds_dwordx4 v[208:209], off
	v_lshl_add_u64 v[210:211], s[40:41], 0, v[180:181]
	s_mov_b32 m0, s43
	v_lshl_add_u64 v[212:213], s[28:29], 0, v[178:179]
	global_load_lds_dwordx4 v[210:211], off
	v_lshl_add_u64 v[210:211], s[40:41], 0, v[176:177]
	s_add_i32 m0, s43, 0x2000
	s_nop 0
	global_load_lds_dwordx4 v[210:211], off
	v_lshl_add_u64 v[210:211], s[28:29], 0, v[182:183]
	s_mov_b32 m0, s56
	s_nop 0
	global_load_lds_dwordx4 v[210:211], off
	s_mov_b32 m0, s57
	s_nop 0
	global_load_lds_dwordx4 v[212:213], off
	s_waitcnt vmcnt(8)
	s_waitcnt lgkmcnt(0)
	s_barrier
	s_waitcnt lgkmcnt(0)
	v_mfma_f32_16x16x32_bf16 v[52:55], v[128:131], v[160:163], v[52:55]
	v_mfma_f32_16x16x32_bf16 v[48:51], v[136:139], v[160:163], v[48:51]
	v_mfma_f32_16x16x32_bf16 v[36:39], v[128:131], v[168:171], v[36:39]
	v_mfma_f32_16x16x32_bf16 v[32:35], v[136:139], v[168:171], v[32:35]
	v_mfma_f32_16x16x32_bf16 v[20:23], v[128:131], v[188:191], v[20:23]
	v_mfma_f32_16x16x32_bf16 v[16:19], v[136:139], v[188:191], v[16:19]
	v_mfma_f32_16x16x32_bf16 v[4:7], v[128:131], v[196:199], v[4:7]
	v_mfma_f32_16x16x32_bf16 v[0:3], v[136:139], v[196:199], v[0:3]
	v_mfma_f32_16x16x32_bf16 v[52:55], v[132:135], v[164:167], v[52:55]
	v_mfma_f32_16x16x32_bf16 v[48:51], v[140:143], v[164:167], v[48:51]
	v_mfma_f32_16x16x32_bf16 v[36:39], v[132:135], v[172:175], v[36:39]
	v_mfma_f32_16x16x32_bf16 v[32:35], v[140:143], v[172:175], v[32:35]
	v_mfma_f32_16x16x32_bf16 v[20:23], v[132:135], v[192:195], v[20:23]
	v_mfma_f32_16x16x32_bf16 v[16:19], v[140:143], v[192:195], v[16:19]
	v_mfma_f32_16x16x32_bf16 v[4:7], v[132:135], v[202:205], v[4:7]
	v_mfma_f32_16x16x32_bf16 v[0:3], v[140:143], v[202:205], v[0:3]
	v_mfma_f32_16x16x32_bf16 v[60:63], v[144:147], v[160:163], v[60:63]
	v_mfma_f32_16x16x32_bf16 v[56:59], v[152:155], v[160:163], v[56:59]
	v_mfma_f32_16x16x32_bf16 v[44:47], v[144:147], v[168:171], v[44:47]
	v_mfma_f32_16x16x32_bf16 v[40:43], v[152:155], v[168:171], v[40:43]
	v_mfma_f32_16x16x32_bf16 v[28:31], v[144:147], v[188:191], v[28:31]
	v_mfma_f32_16x16x32_bf16 v[24:27], v[152:155], v[188:191], v[24:27]
	v_mfma_f32_16x16x32_bf16 v[8:11], v[144:147], v[196:199], v[8:11]
	v_mfma_f32_16x16x32_bf16 v[12:15], v[152:155], v[196:199], v[12:15]
	v_mfma_f32_16x16x32_bf16 v[60:63], v[148:151], v[164:167], v[60:63]
	v_mfma_f32_16x16x32_bf16 v[56:59], v[156:159], v[164:167], v[56:59]
	v_mfma_f32_16x16x32_bf16 v[44:47], v[148:151], v[172:175], v[44:47]
	v_mfma_f32_16x16x32_bf16 v[40:43], v[156:159], v[172:175], v[40:43]
	v_mfma_f32_16x16x32_bf16 v[28:31], v[148:151], v[192:195], v[28:31]
	v_mfma_f32_16x16x32_bf16 v[24:27], v[156:159], v[192:195], v[24:27]
	v_mfma_f32_16x16x32_bf16 v[8:11], v[148:151], v[202:205], v[8:11]
	v_mfma_f32_16x16x32_bf16 v[12:15], v[156:159], v[202:205], v[12:15]
	s_barrier
	s_add_i32 s40, 0, 0x18000
	s_add_i32 s41, 0, 0x1c000
	v_add_u32_e32 v140, s40, v200
	v_add_u32_e32 v156, s41, v200
	ds_read_b128 v[128:131], v140
	ds_read_b128 v[132:135], v140 offset:1024
	ds_read_b128 v[136:139], v140 offset:2048
	ds_read_b128 v[140:143], v140 offset:3072
	ds_read_b128 v[144:147], v156
	ds_read_b128 v[148:151], v156 offset:1024
	ds_read_b128 v[152:155], v156 offset:2048
	ds_read_b128 v[156:159], v156 offset:3072
	s_add_u32 s28, s28, 0x80000
	s_addc_u32 s29, s29, 0
	s_mov_b32 m0, s58
	v_lshl_add_u64 v[214:215], s[28:29], 0, v[182:183]
	ds_read_b128 v[160:163], v201 offset:32768
	ds_read_b128 v[164:167], v201 offset:33792
	ds_read_b128 v[168:171], v201 offset:34816
	ds_read_b128 v[172:175], v201 offset:35840
	ds_read_b128 v[188:191], v201 offset:36864
	ds_read_b128 v[192:195], v201 offset:37888
	ds_read_b128 v[196:199], v201 offset:38912
	ds_read_b128 v[202:205], v201 offset:39936
	global_load_lds_dwordx4 v[214:215], off
	v_lshl_add_u64 v[214:215], s[28:29], 0, v[178:179]
	s_mov_b32 m0, s59
	s_nop 0
	global_load_lds_dwordx4 v[214:215], off
	s_waitcnt vmcnt(8)
	s_waitcnt lgkmcnt(0)
	s_barrier
	s_waitcnt lgkmcnt(0)
	v_mfma_f32_16x16x32_bf16 v[112:115], v[128:131], v[160:163], v[112:115]
	v_mfma_f32_16x16x32_bf16 v[116:119], v[136:139], v[160:163], v[116:119]
	v_mfma_f32_16x16x32_bf16 v[100:103], v[128:131], v[168:171], v[100:103]
	v_mfma_f32_16x16x32_bf16 v[96:99], v[136:139], v[168:171], v[96:99]
	v_mfma_f32_16x16x32_bf16 v[84:87], v[128:131], v[188:191], v[84:87]
	v_mfma_f32_16x16x32_bf16 v[80:83], v[136:139], v[188:191], v[80:83]
	v_mfma_f32_16x16x32_bf16 v[68:71], v[128:131], v[196:199], v[68:71]
	v_mfma_f32_16x16x32_bf16 v[64:67], v[136:139], v[196:199], v[64:67]
	v_mfma_f32_16x16x32_bf16 v[112:115], v[132:135], v[164:167], v[112:115]
	v_mfma_f32_16x16x32_bf16 v[116:119], v[140:143], v[164:167], v[116:119]
	v_mfma_f32_16x16x32_bf16 v[100:103], v[132:135], v[172:175], v[100:103]
	v_mfma_f32_16x16x32_bf16 v[96:99], v[140:143], v[172:175], v[96:99]
	v_mfma_f32_16x16x32_bf16 v[84:87], v[132:135], v[192:195], v[84:87]
	v_mfma_f32_16x16x32_bf16 v[80:83], v[140:143], v[192:195], v[80:83]
	v_mfma_f32_16x16x32_bf16 v[68:71], v[132:135], v[202:205], v[68:71]
	v_mfma_f32_16x16x32_bf16 v[64:67], v[140:143], v[202:205], v[64:67]
	v_mfma_f32_16x16x32_bf16 v[120:123], v[144:147], v[160:163], v[120:123]
	v_mfma_f32_16x16x32_bf16 v[124:127], v[152:155], v[160:163], v[124:127]
	v_mfma_f32_16x16x32_bf16 v[108:111], v[144:147], v[168:171], v[108:111]
	v_mfma_f32_16x16x32_bf16 v[104:107], v[152:155], v[168:171], v[104:107]
	v_mfma_f32_16x16x32_bf16 v[92:95], v[144:147], v[188:191], v[92:95]
	v_mfma_f32_16x16x32_bf16 v[88:91], v[152:155], v[188:191], v[88:91]
	v_mfma_f32_16x16x32_bf16 v[76:79], v[144:147], v[196:199], v[76:79]
	v_mfma_f32_16x16x32_bf16 v[72:75], v[152:155], v[196:199], v[72:75]
	v_mfma_f32_16x16x32_bf16 v[120:123], v[148:151], v[164:167], v[120:123]
	v_mfma_f32_16x16x32_bf16 v[124:127], v[156:159], v[164:167], v[124:127]
	v_mfma_f32_16x16x32_bf16 v[108:111], v[148:151], v[172:175], v[108:111]
	v_mfma_f32_16x16x32_bf16 v[104:107], v[156:159], v[172:175], v[104:107]
	v_mfma_f32_16x16x32_bf16 v[92:95], v[148:151], v[192:195], v[92:95]
	v_mfma_f32_16x16x32_bf16 v[88:91], v[156:159], v[192:195], v[88:91]
	v_mfma_f32_16x16x32_bf16 v[76:79], v[148:151], v[202:205], v[76:79]
	v_mfma_f32_16x16x32_bf16 v[72:75], v[156:159], v[202:205], v[72:75]
	s_barrier
	s_add_i32 s28, s40, s54
	v_lshl_add_u64 v[206:207], v[206:207], 0, s[24:25]
	s_mov_b32 m0, s28
	ds_read_b128 v[160:163], v201 offset:49152
	ds_read_b128 v[164:167], v201 offset:50176
	ds_read_b128 v[168:171], v201 offset:51200
	ds_read_b128 v[172:175], v201 offset:52224
	ds_read_b128 v[188:191], v201 offset:53248
	ds_read_b128 v[192:195], v201 offset:54272
	ds_read_b128 v[196:199], v201 offset:55296
	ds_read_b128 v[202:205], v201 offset:56320
	global_load_lds_dwordx4 v[206:207], off
	s_add_i32 m0, s28, 0x2000
	s_add_u32 s8, s8, 0x80080
	v_lshl_add_u64 v[206:207], v[208:209], 0, s[24:25]
	s_addc_u32 s9, s9, 0
	s_add_i32 s28, s41, s54
	global_load_lds_dwordx4 v[206:207], off
	v_lshl_add_u64 v[206:207], s[8:9], 0, v[180:181]
	s_mov_b32 m0, s28
	s_nop 0
	global_load_lds_dwordx4 v[206:207], off
	v_lshl_add_u64 v[206:207], s[8:9], 0, v[176:177]
	s_add_i32 m0, s28, 0x2000
	s_nop 0
	global_load_lds_dwordx4 v[206:207], off
	v_lshl_add_u64 v[206:207], v[210:211], 0, s[24:25]
	s_mov_b32 m0, s66
	s_nop 0
	global_load_lds_dwordx4 v[206:207], off
	v_lshl_add_u64 v[206:207], v[212:213], 0, s[24:25]
	s_mov_b32 m0, s67
	s_nop 0
	global_load_lds_dwordx4 v[206:207], off
	s_waitcnt vmcnt(8)
	s_waitcnt lgkmcnt(0)
	s_barrier
	s_waitcnt lgkmcnt(0)
	v_mfma_f32_16x16x32_bf16 v[52:55], v[128:131], v[160:163], v[52:55]
	v_mfma_f32_16x16x32_bf16 v[48:51], v[136:139], v[160:163], v[48:51]
	v_mfma_f32_16x16x32_bf16 v[36:39], v[128:131], v[168:171], v[36:39]
	v_mfma_f32_16x16x32_bf16 v[32:35], v[136:139], v[168:171], v[32:35]
	v_mfma_f32_16x16x32_bf16 v[20:23], v[128:131], v[188:191], v[20:23]
	v_mfma_f32_16x16x32_bf16 v[16:19], v[136:139], v[188:191], v[16:19]
	v_mfma_f32_16x16x32_bf16 v[4:7], v[128:131], v[196:199], v[4:7]
	v_mfma_f32_16x16x32_bf16 v[0:3], v[136:139], v[196:199], v[0:3]
	v_mfma_f32_16x16x32_bf16 v[52:55], v[132:135], v[164:167], v[52:55]
	v_mfma_f32_16x16x32_bf16 v[48:51], v[140:143], v[164:167], v[48:51]
	v_mfma_f32_16x16x32_bf16 v[36:39], v[132:135], v[172:175], v[36:39]
	v_mfma_f32_16x16x32_bf16 v[32:35], v[140:143], v[172:175], v[32:35]
	v_mfma_f32_16x16x32_bf16 v[20:23], v[132:135], v[192:195], v[20:23]
	v_mfma_f32_16x16x32_bf16 v[16:19], v[140:143], v[192:195], v[16:19]
	v_mfma_f32_16x16x32_bf16 v[4:7], v[132:135], v[202:205], v[4:7]
	v_mfma_f32_16x16x32_bf16 v[0:3], v[140:143], v[202:205], v[0:3]
	v_mfma_f32_16x16x32_bf16 v[60:63], v[144:147], v[160:163], v[60:63]
	v_mfma_f32_16x16x32_bf16 v[56:59], v[152:155], v[160:163], v[56:59]
	v_mfma_f32_16x16x32_bf16 v[44:47], v[144:147], v[168:171], v[44:47]
	v_mfma_f32_16x16x32_bf16 v[40:43], v[152:155], v[168:171], v[40:43]
	v_mfma_f32_16x16x32_bf16 v[28:31], v[144:147], v[188:191], v[28:31]
	v_mfma_f32_16x16x32_bf16 v[24:27], v[152:155], v[188:191], v[24:27]
	v_mfma_f32_16x16x32_bf16 v[8:11], v[144:147], v[196:199], v[8:11]
	v_mfma_f32_16x16x32_bf16 v[12:15], v[152:155], v[196:199], v[12:15]
	v_mfma_f32_16x16x32_bf16 v[60:63], v[148:151], v[164:167], v[60:63]
	v_mfma_f32_16x16x32_bf16 v[56:59], v[156:159], v[164:167], v[56:59]
	v_mfma_f32_16x16x32_bf16 v[44:47], v[148:151], v[172:175], v[44:47]
	v_mfma_f32_16x16x32_bf16 v[40:43], v[156:159], v[172:175], v[40:43]
	v_mfma_f32_16x16x32_bf16 v[28:31], v[148:151], v[192:195], v[28:31]
	v_mfma_f32_16x16x32_bf16 v[24:27], v[156:159], v[192:195], v[24:27]
	v_mfma_f32_16x16x32_bf16 v[8:11], v[148:151], v[202:205], v[8:11]
	v_mfma_f32_16x16x32_bf16 v[12:15], v[156:159], v[202:205], v[12:15]
	s_barrier
	s_add_u32 s12, s12, 0x100
	s_addc_u32 s13, s13, 0
	s_add_u32 s30, s30, 0x100
	s_addc_u32 s31, s31, 0
	s_cmp_ge_i32 s33, s65
	s_mov_b32 s8, s33
	s_cbranch_scc0 .LBB0_1626

.LBB0_1667:
	s_add_i32 s56, s8, 2
	s_add_u32 s9, s12, 0xfff80080
	s_addc_u32 s28, s13, -1
	s_add_i32 s57, 0, 0x10000
	s_cmp_eq_u32 s48, s8
	s_cselect_b32 s29, s27, s28
	s_cselect_b32 s28, s35, s9
	s_cselect_b32 s9, s52, s55
	s_cselect_b32 s8, s53, s54
	s_add_i32 s60, 0, 0x14000
	v_add_u32_e32 v152, s57, v138
	v_add_u32_e32 v168, s60, v138
	ds_read_b128 v[140:143], v152
	ds_read_b128 v[144:147], v152 offset:1024
	ds_read_b128 v[148:151], v152 offset:2048
	ds_read_b128 v[152:155], v152 offset:3072
	ds_read_b128 v[156:159], v168
	ds_read_b128 v[160:163], v168 offset:1024
	ds_read_b128 v[164:167], v168 offset:2048
	ds_read_b128 v[168:171], v168 offset:3072
	v_lshl_add_u64 v[204:205], s[12:13], 0, v[134:135]
	s_add_i32 m0, s31, 0xc000
	ds_read_b128 v[172:175], v139
	ds_read_b128 v[176:179], v139 offset:1024
	ds_read_b128 v[180:183], v139 offset:2048
	ds_read_b128 v[184:187], v139 offset:3072
	ds_read_b128 v[188:191], v139 offset:4096
	ds_read_b128 v[192:195], v139 offset:5120
	ds_read_b128 v[196:199], v139 offset:6144
	ds_read_b128 v[200:203], v139 offset:7168
	global_load_lds_dwordx4 v[204:205], off
	v_lshl_add_u64 v[204:205], s[12:13], 0, v[136:137]
	s_add_i32 m0, s31, 0xe000
	s_nop 0
	global_load_lds_dwordx4 v[204:205], off
	s_waitcnt vmcnt(8)
	s_waitcnt lgkmcnt(0)
	s_barrier
	s_waitcnt lgkmcnt(0)
	v_mfma_f32_16x16x32_bf16 v[112:115], v[140:143], v[172:175], v[112:115]
	v_mfma_f32_16x16x32_bf16 v[116:119], v[148:151], v[172:175], v[116:119]
	v_mfma_f32_16x16x32_bf16 v[96:99], v[140:143], v[180:183], v[96:99]
	v_mfma_f32_16x16x32_bf16 v[100:103], v[148:151], v[180:183], v[100:103]
	v_mfma_f32_16x16x32_bf16 v[80:83], v[140:143], v[188:191], v[80:83]
	v_mfma_f32_16x16x32_bf16 v[84:87], v[148:151], v[188:191], v[84:87]
	v_mfma_f32_16x16x32_bf16 v[48:51], v[140:143], v[196:199], v[48:51]
	v_mfma_f32_16x16x32_bf16 v[52:55], v[148:151], v[196:199], v[52:55]
	v_mfma_f32_16x16x32_bf16 v[112:115], v[144:147], v[176:179], v[112:115]
	v_mfma_f32_16x16x32_bf16 v[116:119], v[152:155], v[176:179], v[116:119]
	v_mfma_f32_16x16x32_bf16 v[96:99], v[144:147], v[184:187], v[96:99]
	v_mfma_f32_16x16x32_bf16 v[100:103], v[152:155], v[184:187], v[100:103]
	v_mfma_f32_16x16x32_bf16 v[80:83], v[144:147], v[192:195], v[80:83]
	v_mfma_f32_16x16x32_bf16 v[84:87], v[152:155], v[192:195], v[84:87]
	v_mfma_f32_16x16x32_bf16 v[48:51], v[144:147], v[200:203], v[48:51]
	v_mfma_f32_16x16x32_bf16 v[52:55], v[152:155], v[200:203], v[52:55]
	v_mfma_f32_16x16x32_bf16 v[120:123], v[156:159], v[172:175], v[120:123]
	v_mfma_f32_16x16x32_bf16 v[124:127], v[164:167], v[172:175], v[124:127]
	v_mfma_f32_16x16x32_bf16 v[104:107], v[156:159], v[180:183], v[104:107]
	v_mfma_f32_16x16x32_bf16 v[108:111], v[164:167], v[180:183], v[108:111]
	v_mfma_f32_16x16x32_bf16 v[88:91], v[156:159], v[188:191], v[88:91]
	v_mfma_f32_16x16x32_bf16 v[92:95], v[164:167], v[188:191], v[92:95]
	v_mfma_f32_16x16x32_bf16 v[64:67], v[156:159], v[196:199], v[64:67]
	v_mfma_f32_16x16x32_bf16 v[68:71], v[164:167], v[196:199], v[68:71]
	v_mfma_f32_16x16x32_bf16 v[120:123], v[160:163], v[176:179], v[120:123]
	v_mfma_f32_16x16x32_bf16 v[124:127], v[168:171], v[176:179], v[124:127]
	v_mfma_f32_16x16x32_bf16 v[104:107], v[160:163], v[184:187], v[104:107]
	v_mfma_f32_16x16x32_bf16 v[108:111], v[168:171], v[184:187], v[108:111]
	v_mfma_f32_16x16x32_bf16 v[88:91], v[160:163], v[192:195], v[88:91]
	v_mfma_f32_16x16x32_bf16 v[92:95], v[168:171], v[192:195], v[92:95]
	v_mfma_f32_16x16x32_bf16 v[64:67], v[160:163], v[200:203], v[64:67]
	v_mfma_f32_16x16x32_bf16 v[68:71], v[168:171], v[200:203], v[68:71]
	s_barrier
	s_add_i32 s57, s57, s10
	v_lshl_add_u64 v[204:205], s[8:9], 0, v[224:225]
	s_mov_b32 m0, s57
	ds_read_b128 v[172:175], v139 offset:16384
	ds_read_b128 v[176:179], v139 offset:17408
	ds_read_b128 v[180:183], v139 offset:18432
	ds_read_b128 v[184:187], v139 offset:19456
	ds_read_b128 v[188:191], v139 offset:20480
	ds_read_b128 v[192:195], v139 offset:21504
	ds_read_b128 v[196:199], v139 offset:22528
	ds_read_b128 v[200:203], v139 offset:23552
	global_load_lds_dwordx4 v[204:205], off
	s_add_i32 m0, s57, 0x2000
	s_add_u32 s58, s8, 0x80000
	v_lshl_add_u64 v[206:207], s[8:9], 0, v[128:129]
	s_addc_u32 s59, s9, 0
	s_add_i32 s57, s60, s10
	global_load_lds_dwordx4 v[206:207], off
	v_lshl_add_u64 v[208:209], s[58:59], 0, v[224:225]
	s_mov_b32 m0, s57
	v_lshl_add_u64 v[210:211], s[28:29], 0, v[130:131]
	global_load_lds_dwordx4 v[208:209], off
	v_lshl_add_u64 v[208:209], s[58:59], 0, v[128:129]
	s_add_i32 m0, s57, 0x2000
	s_nop 0
	global_load_lds_dwordx4 v[208:209], off
	v_lshl_add_u64 v[208:209], s[28:29], 0, v[132:133]
	s_mov_b32 m0, s31
	s_nop 0
	global_load_lds_dwordx4 v[208:209], off
	s_mov_b32 m0, s33
	s_nop 0
	global_load_lds_dwordx4 v[210:211], off
	s_waitcnt vmcnt(8)
	s_waitcnt lgkmcnt(0)
	s_barrier
	s_waitcnt lgkmcnt(0)
	v_mfma_f32_16x16x32_bf16 v[56:59], v[140:143], v[172:175], v[56:59]
	v_mfma_f32_16x16x32_bf16 v[60:63], v[148:151], v[172:175], v[60:63]
	v_mfma_f32_16x16x32_bf16 v[32:35], v[140:143], v[180:183], v[32:35]
	v_mfma_f32_16x16x32_bf16 v[36:39], v[148:151], v[180:183], v[36:39]
	v_mfma_f32_16x16x32_bf16 v[16:19], v[140:143], v[188:191], v[16:19]
	v_mfma_f32_16x16x32_bf16 v[20:23], v[148:151], v[188:191], v[20:23]
	v_mfma_f32_16x16x32_bf16 v[0:3], v[140:143], v[196:199], v[0:3]
	v_mfma_f32_16x16x32_bf16 v[4:7], v[148:151], v[196:199], v[4:7]
	v_mfma_f32_16x16x32_bf16 v[56:59], v[144:147], v[176:179], v[56:59]
	v_mfma_f32_16x16x32_bf16 v[60:63], v[152:155], v[176:179], v[60:63]
	v_mfma_f32_16x16x32_bf16 v[32:35], v[144:147], v[184:187], v[32:35]
	v_mfma_f32_16x16x32_bf16 v[36:39], v[152:155], v[184:187], v[36:39]
	v_mfma_f32_16x16x32_bf16 v[16:19], v[144:147], v[192:195], v[16:19]
	v_mfma_f32_16x16x32_bf16 v[20:23], v[152:155], v[192:195], v[20:23]
	v_mfma_f32_16x16x32_bf16 v[0:3], v[144:147], v[200:203], v[0:3]
	v_mfma_f32_16x16x32_bf16 v[4:7], v[152:155], v[200:203], v[4:7]
	v_mfma_f32_16x16x32_bf16 v[72:75], v[156:159], v[172:175], v[72:75]
	v_mfma_f32_16x16x32_bf16 v[76:79], v[164:167], v[172:175], v[76:79]
	v_mfma_f32_16x16x32_bf16 v[40:43], v[156:159], v[180:183], v[40:43]
	v_mfma_f32_16x16x32_bf16 v[44:47], v[164:167], v[180:183], v[44:47]
	v_mfma_f32_16x16x32_bf16 v[24:27], v[156:159], v[188:191], v[24:27]
	v_mfma_f32_16x16x32_bf16 v[28:31], v[164:167], v[188:191], v[28:31]
	v_mfma_f32_16x16x32_bf16 v[8:11], v[156:159], v[196:199], v[8:11]
	v_mfma_f32_16x16x32_bf16 v[12:15], v[164:167], v[196:199], v[12:15]
	v_mfma_f32_16x16x32_bf16 v[72:75], v[160:163], v[176:179], v[72:75]
	v_mfma_f32_16x16x32_bf16 v[76:79], v[168:171], v[176:179], v[76:79]
	v_mfma_f32_16x16x32_bf16 v[40:43], v[160:163], v[184:187], v[40:43]
	v_mfma_f32_16x16x32_bf16 v[44:47], v[168:171], v[184:187], v[44:47]
	v_mfma_f32_16x16x32_bf16 v[24:27], v[160:163], v[192:195], v[24:27]
	v_mfma_f32_16x16x32_bf16 v[28:31], v[168:171], v[192:195], v[28:31]
	v_mfma_f32_16x16x32_bf16 v[8:11], v[160:163], v[200:203], v[8:11]
	v_mfma_f32_16x16x32_bf16 v[12:15], v[168:171], v[200:203], v[12:15]
	s_barrier
	s_add_i32 s57, 0, 0x18000
	s_add_i32 s58, 0, 0x1c000
	v_add_u32_e32 v152, s57, v138
	v_add_u32_e32 v168, s58, v138
	ds_read_b128 v[140:143], v152
	ds_read_b128 v[144:147], v152 offset:1024
	ds_read_b128 v[148:151], v152 offset:2048
	ds_read_b128 v[152:155], v152 offset:3072
	ds_read_b128 v[156:159], v168
	ds_read_b128 v[160:163], v168 offset:1024
	ds_read_b128 v[164:167], v168 offset:2048
	ds_read_b128 v[168:171], v168 offset:3072
	s_add_u32 s28, s28, 0x80000
	s_addc_u32 s29, s29, 0
	s_mov_b32 m0, s42
	v_lshl_add_u64 v[212:213], s[28:29], 0, v[132:133]
	ds_read_b128 v[172:175], v139 offset:32768
	ds_read_b128 v[176:179], v139 offset:33792
	ds_read_b128 v[180:183], v139 offset:34816
	ds_read_b128 v[184:187], v139 offset:35840
	ds_read_b128 v[188:191], v139 offset:36864
	ds_read_b128 v[192:195], v139 offset:37888
	ds_read_b128 v[196:199], v139 offset:38912
	ds_read_b128 v[200:203], v139 offset:39936
	global_load_lds_dwordx4 v[212:213], off
	v_lshl_add_u64 v[212:213], s[28:29], 0, v[130:131]
	s_mov_b32 m0, s43
	s_nop 0
	global_load_lds_dwordx4 v[212:213], off
	s_waitcnt vmcnt(8)
	s_waitcnt lgkmcnt(0)
	s_barrier
	s_waitcnt lgkmcnt(0)
	v_mfma_f32_16x16x32_bf16 v[112:115], v[140:143], v[172:175], v[112:115]
	v_mfma_f32_16x16x32_bf16 v[116:119], v[148:151], v[172:175], v[116:119]
	v_mfma_f32_16x16x32_bf16 v[96:99], v[140:143], v[180:183], v[96:99]
	v_mfma_f32_16x16x32_bf16 v[100:103], v[148:151], v[180:183], v[100:103]
	v_mfma_f32_16x16x32_bf16 v[80:83], v[140:143], v[188:191], v[80:83]
	v_mfma_f32_16x16x32_bf16 v[84:87], v[148:151], v[188:191], v[84:87]
	v_mfma_f32_16x16x32_bf16 v[48:51], v[140:143], v[196:199], v[48:51]
	v_mfma_f32_16x16x32_bf16 v[52:55], v[148:151], v[196:199], v[52:55]
	v_mfma_f32_16x16x32_bf16 v[112:115], v[144:147], v[176:179], v[112:115]
	v_mfma_f32_16x16x32_bf16 v[116:119], v[152:155], v[176:179], v[116:119]
	v_mfma_f32_16x16x32_bf16 v[96:99], v[144:147], v[184:187], v[96:99]
	v_mfma_f32_16x16x32_bf16 v[100:103], v[152:155], v[184:187], v[100:103]
	v_mfma_f32_16x16x32_bf16 v[80:83], v[144:147], v[192:195], v[80:83]
	v_mfma_f32_16x16x32_bf16 v[84:87], v[152:155], v[192:195], v[84:87]
	v_mfma_f32_16x16x32_bf16 v[48:51], v[144:147], v[200:203], v[48:51]
	v_mfma_f32_16x16x32_bf16 v[52:55], v[152:155], v[200:203], v[52:55]
	v_mfma_f32_16x16x32_bf16 v[120:123], v[156:159], v[172:175], v[120:123]
	v_mfma_f32_16x16x32_bf16 v[124:127], v[164:167], v[172:175], v[124:127]
	v_mfma_f32_16x16x32_bf16 v[104:107], v[156:159], v[180:183], v[104:107]
	v_mfma_f32_16x16x32_bf16 v[108:111], v[164:167], v[180:183], v[108:111]
	v_mfma_f32_16x16x32_bf16 v[88:91], v[156:159], v[188:191], v[88:91]
	v_mfma_f32_16x16x32_bf16 v[92:95], v[164:167], v[188:191], v[92:95]
	v_mfma_f32_16x16x32_bf16 v[64:67], v[156:159], v[196:199], v[64:67]
	v_mfma_f32_16x16x32_bf16 v[68:71], v[164:167], v[196:199], v[68:71]
	v_mfma_f32_16x16x32_bf16 v[120:123], v[160:163], v[176:179], v[120:123]
	v_mfma_f32_16x16x32_bf16 v[124:127], v[168:171], v[176:179], v[124:127]
	v_mfma_f32_16x16x32_bf16 v[104:107], v[160:163], v[184:187], v[104:107]
	v_mfma_f32_16x16x32_bf16 v[108:111], v[168:171], v[184:187], v[108:111]
	v_mfma_f32_16x16x32_bf16 v[88:91], v[160:163], v[192:195], v[88:91]
	v_mfma_f32_16x16x32_bf16 v[92:95], v[168:171], v[192:195], v[92:95]
	v_mfma_f32_16x16x32_bf16 v[64:67], v[160:163], v[200:203], v[64:67]
	v_mfma_f32_16x16x32_bf16 v[68:71], v[168:171], v[200:203], v[68:71]
	s_barrier
	s_add_i32 s28, s57, s10
	v_lshl_add_u64 v[204:205], v[204:205], 0, s[24:25]
	s_mov_b32 m0, s28
	ds_read_b128 v[172:175], v139 offset:49152
	ds_read_b128 v[176:179], v139 offset:50176
	ds_read_b128 v[180:183], v139 offset:51200
	ds_read_b128 v[184:187], v139 offset:52224
	ds_read_b128 v[188:191], v139 offset:53248
	ds_read_b128 v[192:195], v139 offset:54272
	ds_read_b128 v[196:199], v139 offset:55296
	ds_read_b128 v[200:203], v139 offset:56320
	global_load_lds_dwordx4 v[204:205], off
	s_add_i32 m0, s28, 0x2000
	s_add_u32 s8, s8, 0x80080
	v_lshl_add_u64 v[204:205], v[206:207], 0, s[24:25]
	s_addc_u32 s9, s9, 0
	s_add_i32 s28, s58, s10
	global_load_lds_dwordx4 v[204:205], off
	v_lshl_add_u64 v[204:205], s[8:9], 0, v[224:225]
	s_mov_b32 m0, s28
	s_nop 0
	global_load_lds_dwordx4 v[204:205], off
	v_lshl_add_u64 v[204:205], s[8:9], 0, v[128:129]
	s_add_i32 m0, s28, 0x2000
	s_nop 0
	global_load_lds_dwordx4 v[204:205], off
	v_lshl_add_u64 v[204:205], v[208:209], 0, s[24:25]
	s_mov_b32 m0, s46
	s_nop 0
	global_load_lds_dwordx4 v[204:205], off
	v_lshl_add_u64 v[204:205], v[210:211], 0, s[24:25]
	s_mov_b32 m0, s47
	s_nop 0
	global_load_lds_dwordx4 v[204:205], off
	s_waitcnt vmcnt(8)
	s_waitcnt lgkmcnt(0)
	s_barrier
	s_waitcnt lgkmcnt(0)
	v_mfma_f32_16x16x32_bf16 v[56:59], v[140:143], v[172:175], v[56:59]
	v_mfma_f32_16x16x32_bf16 v[60:63], v[148:151], v[172:175], v[60:63]
	v_mfma_f32_16x16x32_bf16 v[32:35], v[140:143], v[180:183], v[32:35]
	v_mfma_f32_16x16x32_bf16 v[36:39], v[148:151], v[180:183], v[36:39]
	v_mfma_f32_16x16x32_bf16 v[16:19], v[140:143], v[188:191], v[16:19]
	v_mfma_f32_16x16x32_bf16 v[20:23], v[148:151], v[188:191], v[20:23]
	v_mfma_f32_16x16x32_bf16 v[0:3], v[140:143], v[196:199], v[0:3]
	v_mfma_f32_16x16x32_bf16 v[4:7], v[148:151], v[196:199], v[4:7]
	v_mfma_f32_16x16x32_bf16 v[56:59], v[144:147], v[176:179], v[56:59]
	v_mfma_f32_16x16x32_bf16 v[60:63], v[152:155], v[176:179], v[60:63]
	v_mfma_f32_16x16x32_bf16 v[32:35], v[144:147], v[184:187], v[32:35]
	v_mfma_f32_16x16x32_bf16 v[36:39], v[152:155], v[184:187], v[36:39]
	v_mfma_f32_16x16x32_bf16 v[16:19], v[144:147], v[192:195], v[16:19]
	v_mfma_f32_16x16x32_bf16 v[20:23], v[152:155], v[192:195], v[20:23]
	v_mfma_f32_16x16x32_bf16 v[0:3], v[144:147], v[200:203], v[0:3]
	v_mfma_f32_16x16x32_bf16 v[4:7], v[152:155], v[200:203], v[4:7]
	v_mfma_f32_16x16x32_bf16 v[72:75], v[156:159], v[172:175], v[72:75]
	v_mfma_f32_16x16x32_bf16 v[76:79], v[164:167], v[172:175], v[76:79]
	v_mfma_f32_16x16x32_bf16 v[40:43], v[156:159], v[180:183], v[40:43]
	v_mfma_f32_16x16x32_bf16 v[44:47], v[164:167], v[180:183], v[44:47]
	v_mfma_f32_16x16x32_bf16 v[24:27], v[156:159], v[188:191], v[24:27]
	v_mfma_f32_16x16x32_bf16 v[28:31], v[164:167], v[188:191], v[28:31]
	v_mfma_f32_16x16x32_bf16 v[8:11], v[156:159], v[196:199], v[8:11]
	v_mfma_f32_16x16x32_bf16 v[12:15], v[164:167], v[196:199], v[12:15]
	v_mfma_f32_16x16x32_bf16 v[72:75], v[160:163], v[176:179], v[72:75]
	v_mfma_f32_16x16x32_bf16 v[76:79], v[168:171], v[176:179], v[76:79]
	v_mfma_f32_16x16x32_bf16 v[40:43], v[160:163], v[184:187], v[40:43]
	v_mfma_f32_16x16x32_bf16 v[44:47], v[168:171], v[184:187], v[44:47]
	v_mfma_f32_16x16x32_bf16 v[24:27], v[160:163], v[192:195], v[24:27]
	v_mfma_f32_16x16x32_bf16 v[28:31], v[168:171], v[192:195], v[28:31]
	v_mfma_f32_16x16x32_bf16 v[8:11], v[160:163], v[200:203], v[8:11]
	v_mfma_f32_16x16x32_bf16 v[12:15], v[168:171], v[200:203], v[12:15]
	s_barrier
	s_add_u32 s12, s12, 0x100
	s_addc_u32 s13, s13, 0
	s_add_u32 s54, s54, 0x100
	s_addc_u32 s55, s55, 0
	s_cmp_ge_i32 s56, s45
	s_mov_b32 s8, s56
	s_cbranch_scc0 .LBB0_1667
	s_mov_b32 s53, 0x5040100
	s_mov_b64 s[56:57], 0x400000
	s_mov_b64 s[58:59], 0x3fffff
	s_mov_b64 s[60:61], 0x20000

.LBB0_1892:
	s_add_i32 s33, s8, 2
	s_add_u32 s35, s12, 0x80
	s_addc_u32 s9, s13, 0
	s_add_i32 s37, 0, 0x10000
	s_cmp_eq_u32 s61, s8
	s_cselect_b32 s9, s3, s9
	s_cselect_b32 s8, s7, s35
	s_cselect_b32 s65, s28, s31
	s_cselect_b32 s64, s29, s30
	s_add_i32 s35, 0, 0x14000
	v_add_u32_e32 v140, s37, v214
	v_add_u32_e32 v156, s35, v214
	ds_read_b128 v[128:131], v140
	ds_read_b128 v[132:135], v140 offset:1024
	ds_read_b128 v[136:139], v140 offset:2048
	ds_read_b128 v[140:143], v140 offset:3072
	ds_read_b128 v[144:147], v156
	ds_read_b128 v[148:151], v156 offset:1024
	ds_read_b128 v[152:155], v156 offset:2048
	ds_read_b128 v[156:159], v156 offset:3072
	v_lshl_add_u64 v[202:203], s[12:13], 0, v[194:195]
	s_add_i32 m0, s53, 0xc000
	ds_read_b128 v[160:163], v215
	ds_read_b128 v[164:167], v215 offset:1024
	ds_read_b128 v[168:171], v215 offset:2048
	ds_read_b128 v[172:175], v215 offset:3072
	ds_read_b128 v[176:179], v215 offset:4096
	ds_read_b128 v[180:183], v215 offset:5120
	ds_read_b128 v[184:187], v215 offset:6144
	ds_read_b128 v[198:201], v215 offset:7168
	global_load_lds_dwordx4 v[202:203], off
	v_lshl_add_u64 v[202:203], s[12:13], 0, v[196:197]
	s_add_i32 m0, s53, 0xe000
	s_nop 0
	global_load_lds_dwordx4 v[202:203], off
	s_waitcnt vmcnt(8)
	s_waitcnt lgkmcnt(0)
	s_barrier
	s_waitcnt lgkmcnt(0)
	v_mfma_f32_16x16x32_bf16 v[124:127], v[128:131], v[160:163], v[124:127]
	v_mfma_f32_16x16x32_bf16 v[120:123], v[136:139], v[160:163], v[120:123]
	v_mfma_f32_16x16x32_bf16 v[108:111], v[128:131], v[168:171], v[108:111]
	v_mfma_f32_16x16x32_bf16 v[104:107], v[136:139], v[168:171], v[104:107]
	v_mfma_f32_16x16x32_bf16 v[92:95], v[128:131], v[176:179], v[92:95]
	v_mfma_f32_16x16x32_bf16 v[88:91], v[136:139], v[176:179], v[88:91]
	v_mfma_f32_16x16x32_bf16 v[76:79], v[128:131], v[184:187], v[76:79]
	v_mfma_f32_16x16x32_bf16 v[72:75], v[136:139], v[184:187], v[72:75]
	v_mfma_f32_16x16x32_bf16 v[124:127], v[132:135], v[164:167], v[124:127]
	v_mfma_f32_16x16x32_bf16 v[120:123], v[140:143], v[164:167], v[120:123]
	v_mfma_f32_16x16x32_bf16 v[108:111], v[132:135], v[172:175], v[108:111]
	v_mfma_f32_16x16x32_bf16 v[104:107], v[140:143], v[172:175], v[104:107]
	v_mfma_f32_16x16x32_bf16 v[92:95], v[132:135], v[180:183], v[92:95]
	v_mfma_f32_16x16x32_bf16 v[88:91], v[140:143], v[180:183], v[88:91]
	v_mfma_f32_16x16x32_bf16 v[76:79], v[132:135], v[198:201], v[76:79]
	v_mfma_f32_16x16x32_bf16 v[72:75], v[140:143], v[198:201], v[72:75]
	v_mfma_f32_16x16x32_bf16 v[116:119], v[144:147], v[160:163], v[116:119]
	v_mfma_f32_16x16x32_bf16 v[112:115], v[152:155], v[160:163], v[112:115]
	v_mfma_f32_16x16x32_bf16 v[100:103], v[144:147], v[168:171], v[100:103]
	v_mfma_f32_16x16x32_bf16 v[96:99], v[152:155], v[168:171], v[96:99]
	v_mfma_f32_16x16x32_bf16 v[84:87], v[144:147], v[176:179], v[84:87]
	v_mfma_f32_16x16x32_bf16 v[80:83], v[152:155], v[176:179], v[80:83]
	v_mfma_f32_16x16x32_bf16 v[68:71], v[144:147], v[184:187], v[68:71]
	v_mfma_f32_16x16x32_bf16 v[64:67], v[152:155], v[184:187], v[64:67]
	v_mfma_f32_16x16x32_bf16 v[116:119], v[148:151], v[164:167], v[116:119]
	v_mfma_f32_16x16x32_bf16 v[112:115], v[156:159], v[164:167], v[112:115]
	v_mfma_f32_16x16x32_bf16 v[100:103], v[148:151], v[172:175], v[100:103]
	v_mfma_f32_16x16x32_bf16 v[96:99], v[156:159], v[172:175], v[96:99]
	v_mfma_f32_16x16x32_bf16 v[84:87], v[148:151], v[180:183], v[84:87]
	v_mfma_f32_16x16x32_bf16 v[80:83], v[156:159], v[180:183], v[80:83]
	v_mfma_f32_16x16x32_bf16 v[68:71], v[148:151], v[198:201], v[68:71]
	v_mfma_f32_16x16x32_bf16 v[64:67], v[156:159], v[198:201], v[64:67]
	s_barrier
	s_add_i32 s37, s37, s50
	v_lshl_add_u64 v[202:203], s[64:65], 0, v[224:225]
	s_mov_b32 m0, s37
	ds_read_b128 v[160:163], v215 offset:16384
	ds_read_b128 v[164:167], v215 offset:17408
	ds_read_b128 v[168:171], v215 offset:18432
	ds_read_b128 v[172:175], v215 offset:19456
	ds_read_b128 v[176:179], v215 offset:20480
	ds_read_b128 v[180:183], v215 offset:21504
	ds_read_b128 v[184:187], v215 offset:22528
	ds_read_b128 v[198:201], v215 offset:23552
	global_load_lds_dwordx4 v[202:203], off
	s_add_i32 m0, s37, 0x2000
	v_lshl_add_u64 v[204:205], s[64:65], 0, v[188:189]
	s_add_u32 s64, s64, s10
	s_addc_u32 s65, s65, 0
	s_add_i32 s35, s35, s50
	global_load_lds_dwordx4 v[204:205], off
	v_lshl_add_u64 v[206:207], s[64:65], 0, v[224:225]
	s_mov_b32 m0, s35
	v_lshl_add_u64 v[208:209], s[64:65], 0, v[188:189]
	global_load_lds_dwordx4 v[206:207], off
	s_add_i32 m0, s35, 0x2000
	v_lshl_add_u64 v[210:211], s[8:9], 0, v[192:193]
	global_load_lds_dwordx4 v[208:209], off
	s_mov_b32 m0, s53
	v_lshl_add_u64 v[212:213], s[8:9], 0, v[190:191]
	global_load_lds_dwordx4 v[210:211], off
	s_mov_b32 m0, s54
	s_nop 0
	global_load_lds_dwordx4 v[212:213], off
	s_waitcnt vmcnt(8)
	s_waitcnt lgkmcnt(0)
	s_barrier
	s_waitcnt lgkmcnt(0)
	v_mfma_f32_16x16x32_bf16 v[60:63], v[128:131], v[160:163], v[60:63]
	v_mfma_f32_16x16x32_bf16 v[56:59], v[136:139], v[160:163], v[56:59]
	v_mfma_f32_16x16x32_bf16 v[44:47], v[128:131], v[168:171], v[44:47]
	v_mfma_f32_16x16x32_bf16 v[40:43], v[136:139], v[168:171], v[40:43]
	v_mfma_f32_16x16x32_bf16 v[28:31], v[128:131], v[176:179], v[28:31]
	v_mfma_f32_16x16x32_bf16 v[24:27], v[136:139], v[176:179], v[24:27]
	v_mfma_f32_16x16x32_bf16 v[12:15], v[128:131], v[184:187], v[12:15]
	v_mfma_f32_16x16x32_bf16 v[8:11], v[136:139], v[184:187], v[8:11]
	v_mfma_f32_16x16x32_bf16 v[60:63], v[132:135], v[164:167], v[60:63]
	v_mfma_f32_16x16x32_bf16 v[56:59], v[140:143], v[164:167], v[56:59]
	v_mfma_f32_16x16x32_bf16 v[44:47], v[132:135], v[172:175], v[44:47]
	v_mfma_f32_16x16x32_bf16 v[40:43], v[140:143], v[172:175], v[40:43]
	v_mfma_f32_16x16x32_bf16 v[28:31], v[132:135], v[180:183], v[28:31]
	v_mfma_f32_16x16x32_bf16 v[24:27], v[140:143], v[180:183], v[24:27]
	v_mfma_f32_16x16x32_bf16 v[12:15], v[132:135], v[198:201], v[12:15]
	v_mfma_f32_16x16x32_bf16 v[8:11], v[140:143], v[198:201], v[8:11]
	v_mfma_f32_16x16x32_bf16 v[52:55], v[144:147], v[160:163], v[52:55]
	v_mfma_f32_16x16x32_bf16 v[48:51], v[152:155], v[160:163], v[48:51]
	v_mfma_f32_16x16x32_bf16 v[36:39], v[144:147], v[168:171], v[36:39]
	v_mfma_f32_16x16x32_bf16 v[32:35], v[152:155], v[168:171], v[32:35]
	v_mfma_f32_16x16x32_bf16 v[20:23], v[144:147], v[176:179], v[20:23]
	v_mfma_f32_16x16x32_bf16 v[16:19], v[152:155], v[176:179], v[16:19]
	v_mfma_f32_16x16x32_bf16 v[4:7], v[144:147], v[184:187], v[4:7]
	v_mfma_f32_16x16x32_bf16 v[0:3], v[152:155], v[184:187], v[0:3]
	v_mfma_f32_16x16x32_bf16 v[52:55], v[148:151], v[164:167], v[52:55]
	v_mfma_f32_16x16x32_bf16 v[48:51], v[156:159], v[164:167], v[48:51]
	v_mfma_f32_16x16x32_bf16 v[36:39], v[148:151], v[172:175], v[36:39]
	v_mfma_f32_16x16x32_bf16 v[32:35], v[156:159], v[172:175], v[32:35]
	v_mfma_f32_16x16x32_bf16 v[20:23], v[148:151], v[180:183], v[20:23]
	v_mfma_f32_16x16x32_bf16 v[16:19], v[156:159], v[180:183], v[16:19]
	v_mfma_f32_16x16x32_bf16 v[4:7], v[148:151], v[198:201], v[4:7]
	v_mfma_f32_16x16x32_bf16 v[0:3], v[156:159], v[198:201], v[0:3]
	s_barrier
	s_add_i32 s35, 0, 0x18000
	s_add_i32 s37, 0, 0x1c000
	v_add_u32_e32 v140, s35, v214
	v_add_u32_e32 v156, s37, v214
	ds_read_b128 v[128:131], v140
	ds_read_b128 v[132:135], v140 offset:1024
	ds_read_b128 v[136:139], v140 offset:2048
	ds_read_b128 v[140:143], v140 offset:3072
	ds_read_b128 v[144:147], v156
	ds_read_b128 v[148:151], v156 offset:1024
	ds_read_b128 v[152:155], v156 offset:2048
	ds_read_b128 v[156:159], v156 offset:3072
	s_add_u32 s8, s8, s10
	s_addc_u32 s9, s9, 0
	s_mov_b32 m0, s55
	v_lshl_add_u64 v[216:217], s[8:9], 0, v[192:193]
	ds_read_b128 v[160:163], v215 offset:32768
	ds_read_b128 v[164:167], v215 offset:33792
	ds_read_b128 v[168:171], v215 offset:34816
	ds_read_b128 v[172:175], v215 offset:35840
	ds_read_b128 v[176:179], v215 offset:36864
	ds_read_b128 v[180:183], v215 offset:37888
	ds_read_b128 v[184:187], v215 offset:38912
	ds_read_b128 v[198:201], v215 offset:39936
	global_load_lds_dwordx4 v[216:217], off
	v_lshl_add_u64 v[216:217], s[8:9], 0, v[190:191]
	s_mov_b32 m0, s56
	s_nop 0
	global_load_lds_dwordx4 v[216:217], off
	s_waitcnt vmcnt(8)
	s_waitcnt lgkmcnt(0)
	s_barrier
	s_waitcnt lgkmcnt(0)
	v_mfma_f32_16x16x32_bf16 v[124:127], v[128:131], v[160:163], v[124:127]
	v_mfma_f32_16x16x32_bf16 v[120:123], v[136:139], v[160:163], v[120:123]
	v_mfma_f32_16x16x32_bf16 v[108:111], v[128:131], v[168:171], v[108:111]
	v_mfma_f32_16x16x32_bf16 v[104:107], v[136:139], v[168:171], v[104:107]
	v_mfma_f32_16x16x32_bf16 v[92:95], v[128:131], v[176:179], v[92:95]
	v_mfma_f32_16x16x32_bf16 v[88:91], v[136:139], v[176:179], v[88:91]
	v_mfma_f32_16x16x32_bf16 v[76:79], v[128:131], v[184:187], v[76:79]
	v_mfma_f32_16x16x32_bf16 v[72:75], v[136:139], v[184:187], v[72:75]
	v_mfma_f32_16x16x32_bf16 v[124:127], v[132:135], v[164:167], v[124:127]
	v_mfma_f32_16x16x32_bf16 v[120:123], v[140:143], v[164:167], v[120:123]
	v_mfma_f32_16x16x32_bf16 v[108:111], v[132:135], v[172:175], v[108:111]
	v_mfma_f32_16x16x32_bf16 v[104:107], v[140:143], v[172:175], v[104:107]
	v_mfma_f32_16x16x32_bf16 v[92:95], v[132:135], v[180:183], v[92:95]
	v_mfma_f32_16x16x32_bf16 v[88:91], v[140:143], v[180:183], v[88:91]
	v_mfma_f32_16x16x32_bf16 v[76:79], v[132:135], v[198:201], v[76:79]
	v_mfma_f32_16x16x32_bf16 v[72:75], v[140:143], v[198:201], v[72:75]
	v_mfma_f32_16x16x32_bf16 v[116:119], v[144:147], v[160:163], v[116:119]
	v_mfma_f32_16x16x32_bf16 v[112:115], v[152:155], v[160:163], v[112:115]
	v_mfma_f32_16x16x32_bf16 v[100:103], v[144:147], v[168:171], v[100:103]
	v_mfma_f32_16x16x32_bf16 v[96:99], v[152:155], v[168:171], v[96:99]
	v_mfma_f32_16x16x32_bf16 v[84:87], v[144:147], v[176:179], v[84:87]
	v_mfma_f32_16x16x32_bf16 v[80:83], v[152:155], v[176:179], v[80:83]
	v_mfma_f32_16x16x32_bf16 v[68:71], v[144:147], v[184:187], v[68:71]
	v_mfma_f32_16x16x32_bf16 v[64:67], v[152:155], v[184:187], v[64:67]
	v_mfma_f32_16x16x32_bf16 v[116:119], v[148:151], v[164:167], v[116:119]
	v_mfma_f32_16x16x32_bf16 v[112:115], v[156:159], v[164:167], v[112:115]
	v_mfma_f32_16x16x32_bf16 v[100:103], v[148:151], v[172:175], v[100:103]
	v_mfma_f32_16x16x32_bf16 v[96:99], v[156:159], v[172:175], v[96:99]
	v_mfma_f32_16x16x32_bf16 v[84:87], v[148:151], v[180:183], v[84:87]
	v_mfma_f32_16x16x32_bf16 v[80:83], v[156:159], v[180:183], v[80:83]
	v_mfma_f32_16x16x32_bf16 v[68:71], v[148:151], v[198:201], v[68:71]
	v_mfma_f32_16x16x32_bf16 v[64:67], v[156:159], v[198:201], v[64:67]
	s_barrier
	s_add_i32 s8, s35, s50
	v_lshl_add_u64 v[202:203], v[202:203], 0, s[24:25]
	s_mov_b32 m0, s8
	ds_read_b128 v[160:163], v215 offset:49152
	ds_read_b128 v[164:167], v215 offset:50176
	ds_read_b128 v[168:171], v215 offset:51200
	ds_read_b128 v[172:175], v215 offset:52224
	ds_read_b128 v[176:179], v215 offset:53248
	ds_read_b128 v[180:183], v215 offset:54272
	ds_read_b128 v[184:187], v215 offset:55296
	ds_read_b128 v[198:201], v215 offset:56320
	global_load_lds_dwordx4 v[202:203], off
	v_lshl_add_u64 v[202:203], v[204:205], 0, s[24:25]
	s_add_i32 m0, s8, 0x2000
	s_add_i32 s8, s37, s50
	global_load_lds_dwordx4 v[202:203], off
	v_lshl_add_u64 v[202:203], v[206:207], 0, s[24:25]
	s_mov_b32 m0, s8
	s_nop 0
	global_load_lds_dwordx4 v[202:203], off
	v_lshl_add_u64 v[202:203], v[208:209], 0, s[24:25]
	s_add_i32 m0, s8, 0x2000
	s_nop 0
	global_load_lds_dwordx4 v[202:203], off
	v_lshl_add_u64 v[202:203], v[210:211], 0, s[24:25]
	s_mov_b32 m0, s57
	s_nop 0
	global_load_lds_dwordx4 v[202:203], off
	v_lshl_add_u64 v[202:203], v[212:213], 0, s[24:25]
	s_mov_b32 m0, s58
	s_nop 0
	global_load_lds_dwordx4 v[202:203], off
	s_waitcnt vmcnt(8)
	s_waitcnt lgkmcnt(0)
	s_barrier
	s_waitcnt lgkmcnt(0)
	v_mfma_f32_16x16x32_bf16 v[60:63], v[128:131], v[160:163], v[60:63]
	v_mfma_f32_16x16x32_bf16 v[56:59], v[136:139], v[160:163], v[56:59]
	v_mfma_f32_16x16x32_bf16 v[44:47], v[128:131], v[168:171], v[44:47]
	v_mfma_f32_16x16x32_bf16 v[40:43], v[136:139], v[168:171], v[40:43]
	v_mfma_f32_16x16x32_bf16 v[28:31], v[128:131], v[176:179], v[28:31]
	v_mfma_f32_16x16x32_bf16 v[24:27], v[136:139], v[176:179], v[24:27]
	v_mfma_f32_16x16x32_bf16 v[12:15], v[128:131], v[184:187], v[12:15]
	v_mfma_f32_16x16x32_bf16 v[8:11], v[136:139], v[184:187], v[8:11]
	v_mfma_f32_16x16x32_bf16 v[60:63], v[132:135], v[164:167], v[60:63]
	v_mfma_f32_16x16x32_bf16 v[56:59], v[140:143], v[164:167], v[56:59]
	v_mfma_f32_16x16x32_bf16 v[44:47], v[132:135], v[172:175], v[44:47]
	v_mfma_f32_16x16x32_bf16 v[40:43], v[140:143], v[172:175], v[40:43]
	v_mfma_f32_16x16x32_bf16 v[28:31], v[132:135], v[180:183], v[28:31]
	v_mfma_f32_16x16x32_bf16 v[24:27], v[140:143], v[180:183], v[24:27]
	v_mfma_f32_16x16x32_bf16 v[12:15], v[132:135], v[198:201], v[12:15]
	v_mfma_f32_16x16x32_bf16 v[8:11], v[140:143], v[198:201], v[8:11]
	v_mfma_f32_16x16x32_bf16 v[52:55], v[144:147], v[160:163], v[52:55]
	v_mfma_f32_16x16x32_bf16 v[48:51], v[152:155], v[160:163], v[48:51]
	v_mfma_f32_16x16x32_bf16 v[36:39], v[144:147], v[168:171], v[36:39]
	v_mfma_f32_16x16x32_bf16 v[32:35], v[152:155], v[168:171], v[32:35]
	v_mfma_f32_16x16x32_bf16 v[20:23], v[144:147], v[176:179], v[20:23]
	v_mfma_f32_16x16x32_bf16 v[16:19], v[152:155], v[176:179], v[16:19]
	v_mfma_f32_16x16x32_bf16 v[4:7], v[144:147], v[184:187], v[4:7]
	v_mfma_f32_16x16x32_bf16 v[0:3], v[152:155], v[184:187], v[0:3]
	v_mfma_f32_16x16x32_bf16 v[52:55], v[148:151], v[164:167], v[52:55]
	v_mfma_f32_16x16x32_bf16 v[48:51], v[156:159], v[164:167], v[48:51]
	v_mfma_f32_16x16x32_bf16 v[36:39], v[148:151], v[172:175], v[36:39]
	v_mfma_f32_16x16x32_bf16 v[32:35], v[156:159], v[172:175], v[32:35]
	v_mfma_f32_16x16x32_bf16 v[20:23], v[148:151], v[180:183], v[20:23]
	v_mfma_f32_16x16x32_bf16 v[16:19], v[156:159], v[180:183], v[16:19]
	v_mfma_f32_16x16x32_bf16 v[4:7], v[148:151], v[198:201], v[4:7]
	v_mfma_f32_16x16x32_bf16 v[0:3], v[156:159], v[198:201], v[0:3]
	s_barrier
	s_add_u32 s12, s12, 0x100
	s_addc_u32 s13, s13, 0
	s_add_u32 s30, s30, 0x100
	s_addc_u32 s31, s31, 0
	s_cmp_ge_i32 s33, s60
	s_mov_b32 s8, s33
	s_cbranch_scc0 .LBB0_1892
	v_readlane_b32 s64, v253, 21
	v_readlane_b32 s65, v253, 22

.LBB0_2049:
	s_add_i32 s48, s28, 2
	s_add_u32 s8, s12, 0x100
	s_addc_u32 s9, s13, 0
	s_add_i32 s49, 0, 0x10000
	s_cmp_eq_u32 s66, s28
	s_cselect_b32 s43, s7, s9
	s_cselect_b32 s42, s30, s8
	s_cselect_b32 s29, s31, s37
	s_cselect_b32 s28, s33, s35
	s_add_i32 s70, 0, 0x14000
	v_add_u32_e32 v140, s49, v248
	v_add_u32_e32 v156, s70, v248
	ds_read_b128 v[128:131], v140
	ds_read_b128 v[132:135], v140 offset:1024
	ds_read_b128 v[136:139], v140 offset:2048
	ds_read_b128 v[140:143], v140 offset:3072
	ds_read_b128 v[144:147], v156
	ds_read_b128 v[148:151], v156 offset:1024
	ds_read_b128 v[152:155], v156 offset:2048
	ds_read_b128 v[156:159], v156 offset:3072
	v_lshl_add_u64 v[192:193], s[12:13], 0, v[236:237]
	s_add_i32 m0, s55, 0xc000
	ds_read_b128 v[160:163], v249
	ds_read_b128 v[164:167], v249 offset:1024
	ds_read_b128 v[168:171], v249 offset:2048
	ds_read_b128 v[172:175], v249 offset:3072
	ds_read_b128 v[176:179], v249 offset:4096
	ds_read_b128 v[180:183], v249 offset:5120
	ds_read_b128 v[184:187], v249 offset:6144
	ds_read_b128 v[188:191], v249 offset:7168
	global_load_lds_dwordx4 v[192:193], off
	v_lshl_add_u64 v[192:193], s[12:13], 0, v[238:239]
	s_add_i32 m0, s55, 0xe000
	s_nop 0
	global_load_lds_dwordx4 v[192:193], off
	s_waitcnt vmcnt(8)
	s_waitcnt lgkmcnt(0)
	s_barrier
	s_waitcnt lgkmcnt(0)
	v_mfma_f32_16x16x32_bf16 v[100:103], v[128:131], v[160:163], v[100:103]
	v_mfma_f32_16x16x32_bf16 v[116:119], v[136:139], v[160:163], v[116:119]
	v_mfma_f32_16x16x32_bf16 v[96:99], v[128:131], v[168:171], v[96:99]
	v_mfma_f32_16x16x32_bf16 v[112:115], v[136:139], v[168:171], v[112:115]
	v_mfma_f32_16x16x32_bf16 v[104:107], v[128:131], v[176:179], v[104:107]
	v_mfma_f32_16x16x32_bf16 v[120:123], v[136:139], v[176:179], v[120:123]
	v_mfma_f32_16x16x32_bf16 v[108:111], v[128:131], v[184:187], v[108:111]
	v_mfma_f32_16x16x32_bf16 v[124:127], v[136:139], v[184:187], v[124:127]
	v_mfma_f32_16x16x32_bf16 v[100:103], v[132:135], v[164:167], v[100:103]
	v_mfma_f32_16x16x32_bf16 v[116:119], v[140:143], v[164:167], v[116:119]
	v_mfma_f32_16x16x32_bf16 v[96:99], v[132:135], v[172:175], v[96:99]
	v_mfma_f32_16x16x32_bf16 v[112:115], v[140:143], v[172:175], v[112:115]
	v_mfma_f32_16x16x32_bf16 v[104:107], v[132:135], v[180:183], v[104:107]
	v_mfma_f32_16x16x32_bf16 v[120:123], v[140:143], v[180:183], v[120:123]
	v_mfma_f32_16x16x32_bf16 v[108:111], v[132:135], v[188:191], v[108:111]
	v_mfma_f32_16x16x32_bf16 v[124:127], v[140:143], v[188:191], v[124:127]
	v_mfma_f32_16x16x32_bf16 v[84:87], v[144:147], v[160:163], v[84:87]
	v_mfma_f32_16x16x32_bf16 v[68:71], v[152:155], v[160:163], v[68:71]
	v_mfma_f32_16x16x32_bf16 v[80:83], v[144:147], v[168:171], v[80:83]
	v_mfma_f32_16x16x32_bf16 v[64:67], v[152:155], v[168:171], v[64:67]
	v_mfma_f32_16x16x32_bf16 v[88:91], v[144:147], v[176:179], v[88:91]
	v_mfma_f32_16x16x32_bf16 v[72:75], v[152:155], v[176:179], v[72:75]
	v_mfma_f32_16x16x32_bf16 v[92:95], v[144:147], v[184:187], v[92:95]
	v_mfma_f32_16x16x32_bf16 v[76:79], v[152:155], v[184:187], v[76:79]
	v_mfma_f32_16x16x32_bf16 v[84:87], v[148:151], v[164:167], v[84:87]
	v_mfma_f32_16x16x32_bf16 v[68:71], v[156:159], v[164:167], v[68:71]
	v_mfma_f32_16x16x32_bf16 v[80:83], v[148:151], v[172:175], v[80:83]
	v_mfma_f32_16x16x32_bf16 v[64:67], v[156:159], v[172:175], v[64:67]
	v_mfma_f32_16x16x32_bf16 v[88:91], v[148:151], v[180:183], v[88:91]
	v_mfma_f32_16x16x32_bf16 v[72:75], v[156:159], v[180:183], v[72:75]
	v_mfma_f32_16x16x32_bf16 v[92:95], v[148:151], v[188:191], v[92:95]
	v_mfma_f32_16x16x32_bf16 v[76:79], v[156:159], v[188:191], v[76:79]
	s_barrier
	s_add_i32 s12, s49, s53
	v_lshl_add_u64 v[192:193], s[28:29], 0, v[224:225]
	s_mov_b32 m0, s12
	ds_read_b128 v[160:163], v249 offset:16384
	ds_read_b128 v[164:167], v249 offset:17408
	ds_read_b128 v[168:171], v249 offset:18432
	ds_read_b128 v[172:175], v249 offset:19456
	ds_read_b128 v[176:179], v249 offset:20480
	ds_read_b128 v[180:183], v249 offset:21504
	ds_read_b128 v[184:187], v249 offset:22528
	ds_read_b128 v[188:191], v249 offset:23552
	global_load_lds_dwordx4 v[192:193], off
	s_add_i32 m0, s12, 0x2000
	s_add_u32 s12, s28, 0x80000
	v_lshl_add_u64 v[194:195], s[28:29], 0, v[230:231]
	s_addc_u32 s13, s29, 0
	s_add_i32 s49, s70, s53
	global_load_lds_dwordx4 v[194:195], off
	v_lshl_add_u64 v[196:197], s[12:13], 0, v[224:225]
	s_mov_b32 m0, s49
	v_lshl_add_u64 v[198:199], s[42:43], 0, v[232:233]
	global_load_lds_dwordx4 v[196:197], off
	v_lshl_add_u64 v[196:197], s[12:13], 0, v[230:231]
	s_add_i32 m0, s49, 0x2000
	s_nop 0
	global_load_lds_dwordx4 v[196:197], off
	v_lshl_add_u64 v[196:197], s[42:43], 0, v[234:235]
	s_mov_b32 m0, s55
	s_nop 0
	global_load_lds_dwordx4 v[196:197], off
	s_mov_b32 m0, s56
	s_nop 0
	global_load_lds_dwordx4 v[198:199], off
	s_waitcnt vmcnt(8)
	s_waitcnt lgkmcnt(0)
	s_barrier
	s_waitcnt lgkmcnt(0)
	v_mfma_f32_16x16x32_bf16 v[16:19], v[128:131], v[160:163], v[16:19]
	v_mfma_f32_16x16x32_bf16 v[44:47], v[136:139], v[160:163], v[44:47]
	v_mfma_f32_16x16x32_bf16 v[24:27], v[128:131], v[168:171], v[24:27]
	v_mfma_f32_16x16x32_bf16 v[52:55], v[136:139], v[168:171], v[52:55]
	v_mfma_f32_16x16x32_bf16 v[32:35], v[128:131], v[176:179], v[32:35]
	v_mfma_f32_16x16x32_bf16 v[56:59], v[136:139], v[176:179], v[56:59]
	v_mfma_f32_16x16x32_bf16 v[40:43], v[128:131], v[184:187], v[40:43]
	v_mfma_f32_16x16x32_bf16 v[60:63], v[136:139], v[184:187], v[60:63]
	v_mfma_f32_16x16x32_bf16 v[16:19], v[132:135], v[164:167], v[16:19]
	v_mfma_f32_16x16x32_bf16 v[44:47], v[140:143], v[164:167], v[44:47]
	v_mfma_f32_16x16x32_bf16 v[24:27], v[132:135], v[172:175], v[24:27]
	v_mfma_f32_16x16x32_bf16 v[52:55], v[140:143], v[172:175], v[52:55]
	v_mfma_f32_16x16x32_bf16 v[32:35], v[132:135], v[180:183], v[32:35]
	v_mfma_f32_16x16x32_bf16 v[56:59], v[140:143], v[180:183], v[56:59]
	v_mfma_f32_16x16x32_bf16 v[40:43], v[132:135], v[188:191], v[40:43]
	v_mfma_f32_16x16x32_bf16 v[60:63], v[140:143], v[188:191], v[60:63]
	v_mfma_f32_16x16x32_bf16 v[20:23], v[144:147], v[160:163], v[20:23]
	v_mfma_f32_16x16x32_bf16 v[4:7], v[152:155], v[160:163], v[4:7]
	v_mfma_f32_16x16x32_bf16 v[28:31], v[144:147], v[168:171], v[28:31]
	v_mfma_f32_16x16x32_bf16 v[0:3], v[152:155], v[168:171], v[0:3]
	v_mfma_f32_16x16x32_bf16 v[36:39], v[144:147], v[176:179], v[36:39]
	v_mfma_f32_16x16x32_bf16 v[8:11], v[152:155], v[176:179], v[8:11]
	v_mfma_f32_16x16x32_bf16 v[48:51], v[144:147], v[184:187], v[48:51]
	v_mfma_f32_16x16x32_bf16 v[12:15], v[152:155], v[184:187], v[12:15]
	v_mfma_f32_16x16x32_bf16 v[20:23], v[148:151], v[164:167], v[20:23]
	v_mfma_f32_16x16x32_bf16 v[4:7], v[156:159], v[164:167], v[4:7]
	v_mfma_f32_16x16x32_bf16 v[28:31], v[148:151], v[172:175], v[28:31]
	v_mfma_f32_16x16x32_bf16 v[0:3], v[156:159], v[172:175], v[0:3]
	v_mfma_f32_16x16x32_bf16 v[36:39], v[148:151], v[180:183], v[36:39]
	v_mfma_f32_16x16x32_bf16 v[8:11], v[156:159], v[180:183], v[8:11]
	v_mfma_f32_16x16x32_bf16 v[48:51], v[148:151], v[188:191], v[48:51]
	v_mfma_f32_16x16x32_bf16 v[12:15], v[156:159], v[188:191], v[12:15]
	s_barrier
	s_add_i32 s49, 0, 0x18000
	s_add_i32 s70, 0, 0x1c000
	v_add_u32_e32 v140, s49, v248
	v_add_u32_e32 v156, s70, v248
	ds_read_b128 v[128:131], v140
	ds_read_b128 v[132:135], v140 offset:1024
	ds_read_b128 v[136:139], v140 offset:2048
	ds_read_b128 v[140:143], v140 offset:3072
	ds_read_b128 v[144:147], v156
	ds_read_b128 v[148:151], v156 offset:1024
	ds_read_b128 v[152:155], v156 offset:2048
	ds_read_b128 v[156:159], v156 offset:3072
	s_add_u32 s12, s42, 0x80000
	s_addc_u32 s13, s43, 0
	s_mov_b32 m0, s57
	v_lshl_add_u64 v[200:201], s[12:13], 0, v[234:235]
	ds_read_b128 v[160:163], v249 offset:32768
	ds_read_b128 v[164:167], v249 offset:33792
	ds_read_b128 v[168:171], v249 offset:34816
	ds_read_b128 v[172:175], v249 offset:35840
	ds_read_b128 v[176:179], v249 offset:36864
	ds_read_b128 v[180:183], v249 offset:37888
	ds_read_b128 v[184:187], v249 offset:38912
	ds_read_b128 v[188:191], v249 offset:39936
	global_load_lds_dwordx4 v[200:201], off
	v_lshl_add_u64 v[200:201], s[12:13], 0, v[232:233]
	s_mov_b32 m0, s58
	s_nop 0
	global_load_lds_dwordx4 v[200:201], off
	s_waitcnt vmcnt(8)
	s_waitcnt lgkmcnt(0)
	s_barrier
	s_waitcnt lgkmcnt(0)
	v_mfma_f32_16x16x32_bf16 v[100:103], v[128:131], v[160:163], v[100:103]
	v_mfma_f32_16x16x32_bf16 v[116:119], v[136:139], v[160:163], v[116:119]
	v_mfma_f32_16x16x32_bf16 v[96:99], v[128:131], v[168:171], v[96:99]
	v_mfma_f32_16x16x32_bf16 v[112:115], v[136:139], v[168:171], v[112:115]
	v_mfma_f32_16x16x32_bf16 v[104:107], v[128:131], v[176:179], v[104:107]
	v_mfma_f32_16x16x32_bf16 v[120:123], v[136:139], v[176:179], v[120:123]
	v_mfma_f32_16x16x32_bf16 v[108:111], v[128:131], v[184:187], v[108:111]
	v_mfma_f32_16x16x32_bf16 v[124:127], v[136:139], v[184:187], v[124:127]
	v_mfma_f32_16x16x32_bf16 v[100:103], v[132:135], v[164:167], v[100:103]
	v_mfma_f32_16x16x32_bf16 v[116:119], v[140:143], v[164:167], v[116:119]
	v_mfma_f32_16x16x32_bf16 v[96:99], v[132:135], v[172:175], v[96:99]
	v_mfma_f32_16x16x32_bf16 v[112:115], v[140:143], v[172:175], v[112:115]
	v_mfma_f32_16x16x32_bf16 v[104:107], v[132:135], v[180:183], v[104:107]
	v_mfma_f32_16x16x32_bf16 v[120:123], v[140:143], v[180:183], v[120:123]
	v_mfma_f32_16x16x32_bf16 v[108:111], v[132:135], v[188:191], v[108:111]
	v_mfma_f32_16x16x32_bf16 v[124:127], v[140:143], v[188:191], v[124:127]
	v_mfma_f32_16x16x32_bf16 v[84:87], v[144:147], v[160:163], v[84:87]
	v_mfma_f32_16x16x32_bf16 v[68:71], v[152:155], v[160:163], v[68:71]
	v_mfma_f32_16x16x32_bf16 v[80:83], v[144:147], v[168:171], v[80:83]
	v_mfma_f32_16x16x32_bf16 v[64:67], v[152:155], v[168:171], v[64:67]
	v_mfma_f32_16x16x32_bf16 v[88:91], v[144:147], v[176:179], v[88:91]
	v_mfma_f32_16x16x32_bf16 v[72:75], v[152:155], v[176:179], v[72:75]
	v_mfma_f32_16x16x32_bf16 v[92:95], v[144:147], v[184:187], v[92:95]
	v_mfma_f32_16x16x32_bf16 v[76:79], v[152:155], v[184:187], v[76:79]
	v_mfma_f32_16x16x32_bf16 v[84:87], v[148:151], v[164:167], v[84:87]
	v_mfma_f32_16x16x32_bf16 v[68:71], v[156:159], v[164:167], v[68:71]
	v_mfma_f32_16x16x32_bf16 v[80:83], v[148:151], v[172:175], v[80:83]
	v_mfma_f32_16x16x32_bf16 v[64:67], v[156:159], v[172:175], v[64:67]
	v_mfma_f32_16x16x32_bf16 v[88:91], v[148:151], v[180:183], v[88:91]
	v_mfma_f32_16x16x32_bf16 v[72:75], v[156:159], v[180:183], v[72:75]
	v_mfma_f32_16x16x32_bf16 v[92:95], v[148:151], v[188:191], v[92:95]
	v_mfma_f32_16x16x32_bf16 v[76:79], v[156:159], v[188:191], v[76:79]
	s_barrier
	s_add_i32 s12, s49, s53
	v_lshl_add_u64 v[192:193], v[192:193], 0, s[24:25]
	s_mov_b32 m0, s12
	ds_read_b128 v[160:163], v249 offset:49152
	ds_read_b128 v[164:167], v249 offset:50176
	ds_read_b128 v[168:171], v249 offset:51200
	ds_read_b128 v[172:175], v249 offset:52224
	ds_read_b128 v[176:179], v249 offset:53248
	ds_read_b128 v[180:183], v249 offset:54272
	ds_read_b128 v[184:187], v249 offset:55296
	ds_read_b128 v[188:191], v249 offset:56320
	global_load_lds_dwordx4 v[192:193], off
	s_add_i32 m0, s12, 0x2000
	s_add_u32 s12, s28, 0x80080
	v_lshl_add_u64 v[192:193], v[194:195], 0, s[24:25]
	s_addc_u32 s13, s29, 0
	s_add_i32 s28, s70, s53
	global_load_lds_dwordx4 v[192:193], off
	v_lshl_add_u64 v[192:193], s[12:13], 0, v[224:225]
	s_mov_b32 m0, s28
	s_nop 0
	global_load_lds_dwordx4 v[192:193], off
	v_lshl_add_u64 v[192:193], s[12:13], 0, v[230:231]
	s_add_i32 m0, s28, 0x2000
	s_nop 0
	global_load_lds_dwordx4 v[192:193], off
	v_lshl_add_u64 v[192:193], v[196:197], 0, s[24:25]
	s_mov_b32 m0, s63
	s_nop 0
	global_load_lds_dwordx4 v[192:193], off
	v_lshl_add_u64 v[192:193], v[198:199], 0, s[24:25]
	s_mov_b32 m0, s64
	s_nop 0
	global_load_lds_dwordx4 v[192:193], off
	s_waitcnt vmcnt(8)
	s_waitcnt lgkmcnt(0)
	s_barrier
	s_waitcnt lgkmcnt(0)
	v_mfma_f32_16x16x32_bf16 v[16:19], v[128:131], v[160:163], v[16:19]
	v_mfma_f32_16x16x32_bf16 v[44:47], v[136:139], v[160:163], v[44:47]
	v_mfma_f32_16x16x32_bf16 v[24:27], v[128:131], v[168:171], v[24:27]
	v_mfma_f32_16x16x32_bf16 v[52:55], v[136:139], v[168:171], v[52:55]
	v_mfma_f32_16x16x32_bf16 v[32:35], v[128:131], v[176:179], v[32:35]
	v_mfma_f32_16x16x32_bf16 v[56:59], v[136:139], v[176:179], v[56:59]
	v_mfma_f32_16x16x32_bf16 v[40:43], v[128:131], v[184:187], v[40:43]
	v_mfma_f32_16x16x32_bf16 v[60:63], v[136:139], v[184:187], v[60:63]
	v_mfma_f32_16x16x32_bf16 v[16:19], v[132:135], v[164:167], v[16:19]
	v_mfma_f32_16x16x32_bf16 v[44:47], v[140:143], v[164:167], v[44:47]
	v_mfma_f32_16x16x32_bf16 v[24:27], v[132:135], v[172:175], v[24:27]
	v_mfma_f32_16x16x32_bf16 v[52:55], v[140:143], v[172:175], v[52:55]
	v_mfma_f32_16x16x32_bf16 v[32:35], v[132:135], v[180:183], v[32:35]
	v_mfma_f32_16x16x32_bf16 v[56:59], v[140:143], v[180:183], v[56:59]
	v_mfma_f32_16x16x32_bf16 v[40:43], v[132:135], v[188:191], v[40:43]
	v_mfma_f32_16x16x32_bf16 v[60:63], v[140:143], v[188:191], v[60:63]
	v_mfma_f32_16x16x32_bf16 v[20:23], v[144:147], v[160:163], v[20:23]
	v_mfma_f32_16x16x32_bf16 v[4:7], v[152:155], v[160:163], v[4:7]
	v_mfma_f32_16x16x32_bf16 v[28:31], v[144:147], v[168:171], v[28:31]
	v_mfma_f32_16x16x32_bf16 v[0:3], v[152:155], v[168:171], v[0:3]
	v_mfma_f32_16x16x32_bf16 v[36:39], v[144:147], v[176:179], v[36:39]
	v_mfma_f32_16x16x32_bf16 v[8:11], v[152:155], v[176:179], v[8:11]
	v_mfma_f32_16x16x32_bf16 v[48:51], v[144:147], v[184:187], v[48:51]
	v_mfma_f32_16x16x32_bf16 v[12:15], v[152:155], v[184:187], v[12:15]
	v_mfma_f32_16x16x32_bf16 v[20:23], v[148:151], v[164:167], v[20:23]
	v_mfma_f32_16x16x32_bf16 v[4:7], v[156:159], v[164:167], v[4:7]
	v_mfma_f32_16x16x32_bf16 v[28:31], v[148:151], v[172:175], v[28:31]
	v_mfma_f32_16x16x32_bf16 v[0:3], v[156:159], v[172:175], v[0:3]
	v_mfma_f32_16x16x32_bf16 v[36:39], v[148:151], v[180:183], v[36:39]
	v_mfma_f32_16x16x32_bf16 v[8:11], v[156:159], v[180:183], v[8:11]
	v_mfma_f32_16x16x32_bf16 v[48:51], v[148:151], v[188:191], v[48:51]
	v_mfma_f32_16x16x32_bf16 v[12:15], v[156:159], v[188:191], v[12:15]
	s_barrier
	s_add_u32 s35, s35, 0x100
	s_addc_u32 s37, s37, 0
	s_cmp_ge_i32 s48, s62
	s_mov_b64 s[12:13], s[8:9]
	s_mov_b32 s28, s48
	s_cbranch_scc0 .LBB0_2049

.LBB0_2092:
	s_add_i32 s58, s8, 2
	s_add_u32 s9, s12, 0xffff0080
	s_addc_u32 s28, s13, -1
	s_add_i32 s59, 0, 0x10000
	s_cmp_eq_u32 s50, s8
	s_cselect_b32 s29, s27, s28
	s_cselect_b32 s28, s35, s9
	s_cselect_b32 s9, s54, s57
	s_cselect_b32 s8, s55, s56
	s_add_i32 s62, 0, 0x14000
	v_add_u32_e32 v152, s59, v138
	v_add_u32_e32 v168, s62, v138
	ds_read_b128 v[140:143], v152
	ds_read_b128 v[144:147], v152 offset:1024
	ds_read_b128 v[148:151], v152 offset:2048
	ds_read_b128 v[152:155], v152 offset:3072
	ds_read_b128 v[156:159], v168
	ds_read_b128 v[160:163], v168 offset:1024
	ds_read_b128 v[164:167], v168 offset:2048
	ds_read_b128 v[168:171], v168 offset:3072
	v_lshl_add_u64 v[204:205], s[12:13], 0, v[134:135]
	s_add_i32 m0, s31, 0xc000
	ds_read_b128 v[172:175], v139
	ds_read_b128 v[176:179], v139 offset:1024
	ds_read_b128 v[180:183], v139 offset:2048
	ds_read_b128 v[184:187], v139 offset:3072
	ds_read_b128 v[188:191], v139 offset:4096
	ds_read_b128 v[192:195], v139 offset:5120
	ds_read_b128 v[196:199], v139 offset:6144
	ds_read_b128 v[200:203], v139 offset:7168
	global_load_lds_dwordx4 v[204:205], off
	v_lshl_add_u64 v[204:205], s[12:13], 0, v[136:137]
	s_add_i32 m0, s31, 0xe000
	s_nop 0
	global_load_lds_dwordx4 v[204:205], off
	s_waitcnt vmcnt(8)
	s_waitcnt lgkmcnt(0)
	s_barrier
	s_waitcnt lgkmcnt(0)
	v_mfma_f32_16x16x32_bf16 v[112:115], v[140:143], v[172:175], v[112:115]
	v_mfma_f32_16x16x32_bf16 v[116:119], v[148:151], v[172:175], v[116:119]
	v_mfma_f32_16x16x32_bf16 v[96:99], v[140:143], v[180:183], v[96:99]
	v_mfma_f32_16x16x32_bf16 v[100:103], v[148:151], v[180:183], v[100:103]
	v_mfma_f32_16x16x32_bf16 v[80:83], v[140:143], v[188:191], v[80:83]
	v_mfma_f32_16x16x32_bf16 v[84:87], v[148:151], v[188:191], v[84:87]
	v_mfma_f32_16x16x32_bf16 v[48:51], v[140:143], v[196:199], v[48:51]
	v_mfma_f32_16x16x32_bf16 v[52:55], v[148:151], v[196:199], v[52:55]
	v_mfma_f32_16x16x32_bf16 v[112:115], v[144:147], v[176:179], v[112:115]
	v_mfma_f32_16x16x32_bf16 v[116:119], v[152:155], v[176:179], v[116:119]
	v_mfma_f32_16x16x32_bf16 v[96:99], v[144:147], v[184:187], v[96:99]
	v_mfma_f32_16x16x32_bf16 v[100:103], v[152:155], v[184:187], v[100:103]
	v_mfma_f32_16x16x32_bf16 v[80:83], v[144:147], v[192:195], v[80:83]
	v_mfma_f32_16x16x32_bf16 v[84:87], v[152:155], v[192:195], v[84:87]
	v_mfma_f32_16x16x32_bf16 v[48:51], v[144:147], v[200:203], v[48:51]
	v_mfma_f32_16x16x32_bf16 v[52:55], v[152:155], v[200:203], v[52:55]
	v_mfma_f32_16x16x32_bf16 v[120:123], v[156:159], v[172:175], v[120:123]
	v_mfma_f32_16x16x32_bf16 v[124:127], v[164:167], v[172:175], v[124:127]
	v_mfma_f32_16x16x32_bf16 v[104:107], v[156:159], v[180:183], v[104:107]
	v_mfma_f32_16x16x32_bf16 v[108:111], v[164:167], v[180:183], v[108:111]
	v_mfma_f32_16x16x32_bf16 v[88:91], v[156:159], v[188:191], v[88:91]
	v_mfma_f32_16x16x32_bf16 v[92:95], v[164:167], v[188:191], v[92:95]
	v_mfma_f32_16x16x32_bf16 v[64:67], v[156:159], v[196:199], v[64:67]
	v_mfma_f32_16x16x32_bf16 v[68:71], v[164:167], v[196:199], v[68:71]
	v_mfma_f32_16x16x32_bf16 v[120:123], v[160:163], v[176:179], v[120:123]
	v_mfma_f32_16x16x32_bf16 v[124:127], v[168:171], v[176:179], v[124:127]
	v_mfma_f32_16x16x32_bf16 v[104:107], v[160:163], v[184:187], v[104:107]
	v_mfma_f32_16x16x32_bf16 v[108:111], v[168:171], v[184:187], v[108:111]
	v_mfma_f32_16x16x32_bf16 v[88:91], v[160:163], v[192:195], v[88:91]
	v_mfma_f32_16x16x32_bf16 v[92:95], v[168:171], v[192:195], v[92:95]
	v_mfma_f32_16x16x32_bf16 v[64:67], v[160:163], v[200:203], v[64:67]
	v_mfma_f32_16x16x32_bf16 v[68:71], v[168:171], v[200:203], v[68:71]
	s_barrier
	s_add_i32 s59, s59, s10
	v_lshl_add_u64 v[204:205], s[8:9], 0, v[224:225]
	s_mov_b32 m0, s59
	ds_read_b128 v[172:175], v139 offset:16384
	ds_read_b128 v[176:179], v139 offset:17408
	ds_read_b128 v[180:183], v139 offset:18432
	ds_read_b128 v[184:187], v139 offset:19456
	ds_read_b128 v[188:191], v139 offset:20480
	ds_read_b128 v[192:195], v139 offset:21504
	ds_read_b128 v[196:199], v139 offset:22528
	ds_read_b128 v[200:203], v139 offset:23552
	global_load_lds_dwordx4 v[204:205], off
	s_add_i32 m0, s59, 0x2000
	s_add_u32 s60, s8, 0x10000
	v_lshl_add_u64 v[206:207], s[8:9], 0, v[128:129]
	s_addc_u32 s61, s9, 0
	s_add_i32 s59, s62, s10
	global_load_lds_dwordx4 v[206:207], off
	v_lshl_add_u64 v[208:209], s[60:61], 0, v[224:225]
	s_mov_b32 m0, s59
	v_lshl_add_u64 v[210:211], s[28:29], 0, v[130:131]
	global_load_lds_dwordx4 v[208:209], off
	v_lshl_add_u64 v[208:209], s[60:61], 0, v[128:129]
	s_add_i32 m0, s59, 0x2000
	s_nop 0
	global_load_lds_dwordx4 v[208:209], off
	v_lshl_add_u64 v[208:209], s[28:29], 0, v[132:133]
	s_mov_b32 m0, s31
	s_nop 0
	global_load_lds_dwordx4 v[208:209], off
	s_mov_b32 m0, s33
	s_nop 0
	global_load_lds_dwordx4 v[210:211], off
	s_waitcnt vmcnt(8)
	s_waitcnt lgkmcnt(0)
	s_barrier
	s_waitcnt lgkmcnt(0)
	v_mfma_f32_16x16x32_bf16 v[56:59], v[140:143], v[172:175], v[56:59]
	v_mfma_f32_16x16x32_bf16 v[60:63], v[148:151], v[172:175], v[60:63]
	v_mfma_f32_16x16x32_bf16 v[32:35], v[140:143], v[180:183], v[32:35]
	v_mfma_f32_16x16x32_bf16 v[36:39], v[148:151], v[180:183], v[36:39]
	v_mfma_f32_16x16x32_bf16 v[16:19], v[140:143], v[188:191], v[16:19]
	v_mfma_f32_16x16x32_bf16 v[20:23], v[148:151], v[188:191], v[20:23]
	v_mfma_f32_16x16x32_bf16 v[0:3], v[140:143], v[196:199], v[0:3]
	v_mfma_f32_16x16x32_bf16 v[4:7], v[148:151], v[196:199], v[4:7]
	v_mfma_f32_16x16x32_bf16 v[56:59], v[144:147], v[176:179], v[56:59]
	v_mfma_f32_16x16x32_bf16 v[60:63], v[152:155], v[176:179], v[60:63]
	v_mfma_f32_16x16x32_bf16 v[32:35], v[144:147], v[184:187], v[32:35]
	v_mfma_f32_16x16x32_bf16 v[36:39], v[152:155], v[184:187], v[36:39]
	v_mfma_f32_16x16x32_bf16 v[16:19], v[144:147], v[192:195], v[16:19]
	v_mfma_f32_16x16x32_bf16 v[20:23], v[152:155], v[192:195], v[20:23]
	v_mfma_f32_16x16x32_bf16 v[0:3], v[144:147], v[200:203], v[0:3]
	v_mfma_f32_16x16x32_bf16 v[4:7], v[152:155], v[200:203], v[4:7]
	v_mfma_f32_16x16x32_bf16 v[72:75], v[156:159], v[172:175], v[72:75]
	v_mfma_f32_16x16x32_bf16 v[76:79], v[164:167], v[172:175], v[76:79]
	v_mfma_f32_16x16x32_bf16 v[40:43], v[156:159], v[180:183], v[40:43]
	v_mfma_f32_16x16x32_bf16 v[44:47], v[164:167], v[180:183], v[44:47]
	v_mfma_f32_16x16x32_bf16 v[24:27], v[156:159], v[188:191], v[24:27]
	v_mfma_f32_16x16x32_bf16 v[28:31], v[164:167], v[188:191], v[28:31]
	v_mfma_f32_16x16x32_bf16 v[8:11], v[156:159], v[196:199], v[8:11]
	v_mfma_f32_16x16x32_bf16 v[12:15], v[164:167], v[196:199], v[12:15]
	v_mfma_f32_16x16x32_bf16 v[72:75], v[160:163], v[176:179], v[72:75]
	v_mfma_f32_16x16x32_bf16 v[76:79], v[168:171], v[176:179], v[76:79]
	v_mfma_f32_16x16x32_bf16 v[40:43], v[160:163], v[184:187], v[40:43]
	v_mfma_f32_16x16x32_bf16 v[44:47], v[168:171], v[184:187], v[44:47]
	v_mfma_f32_16x16x32_bf16 v[24:27], v[160:163], v[192:195], v[24:27]
	v_mfma_f32_16x16x32_bf16 v[28:31], v[168:171], v[192:195], v[28:31]
	v_mfma_f32_16x16x32_bf16 v[8:11], v[160:163], v[200:203], v[8:11]
	v_mfma_f32_16x16x32_bf16 v[12:15], v[168:171], v[200:203], v[12:15]
	s_barrier
	s_add_i32 s59, 0, 0x18000
	s_add_i32 s60, 0, 0x1c000
	v_add_u32_e32 v152, s59, v138
	v_add_u32_e32 v168, s60, v138
	ds_read_b128 v[140:143], v152
	ds_read_b128 v[144:147], v152 offset:1024
	ds_read_b128 v[148:151], v152 offset:2048
	ds_read_b128 v[152:155], v152 offset:3072
	ds_read_b128 v[156:159], v168
	ds_read_b128 v[160:163], v168 offset:1024
	ds_read_b128 v[164:167], v168 offset:2048
	ds_read_b128 v[168:171], v168 offset:3072
	s_add_u32 s28, s28, 0x10000
	s_addc_u32 s29, s29, 0
	s_mov_b32 m0, s44
	v_lshl_add_u64 v[212:213], s[28:29], 0, v[132:133]
	ds_read_b128 v[172:175], v139 offset:32768
	ds_read_b128 v[176:179], v139 offset:33792
	ds_read_b128 v[180:183], v139 offset:34816
	ds_read_b128 v[184:187], v139 offset:35840
	ds_read_b128 v[188:191], v139 offset:36864
	ds_read_b128 v[192:195], v139 offset:37888
	ds_read_b128 v[196:199], v139 offset:38912
	ds_read_b128 v[200:203], v139 offset:39936
	global_load_lds_dwordx4 v[212:213], off
	v_lshl_add_u64 v[212:213], s[28:29], 0, v[130:131]
	s_mov_b32 m0, s45
	s_nop 0
	global_load_lds_dwordx4 v[212:213], off
	s_waitcnt vmcnt(8)
	s_waitcnt lgkmcnt(0)
	s_barrier
	s_waitcnt lgkmcnt(0)
	v_mfma_f32_16x16x32_bf16 v[112:115], v[140:143], v[172:175], v[112:115]
	v_mfma_f32_16x16x32_bf16 v[116:119], v[148:151], v[172:175], v[116:119]
	v_mfma_f32_16x16x32_bf16 v[96:99], v[140:143], v[180:183], v[96:99]
	v_mfma_f32_16x16x32_bf16 v[100:103], v[148:151], v[180:183], v[100:103]
	v_mfma_f32_16x16x32_bf16 v[80:83], v[140:143], v[188:191], v[80:83]
	v_mfma_f32_16x16x32_bf16 v[84:87], v[148:151], v[188:191], v[84:87]
	v_mfma_f32_16x16x32_bf16 v[48:51], v[140:143], v[196:199], v[48:51]
	v_mfma_f32_16x16x32_bf16 v[52:55], v[148:151], v[196:199], v[52:55]
	v_mfma_f32_16x16x32_bf16 v[112:115], v[144:147], v[176:179], v[112:115]
	v_mfma_f32_16x16x32_bf16 v[116:119], v[152:155], v[176:179], v[116:119]
	v_mfma_f32_16x16x32_bf16 v[96:99], v[144:147], v[184:187], v[96:99]
	v_mfma_f32_16x16x32_bf16 v[100:103], v[152:155], v[184:187], v[100:103]
	v_mfma_f32_16x16x32_bf16 v[80:83], v[144:147], v[192:195], v[80:83]
	v_mfma_f32_16x16x32_bf16 v[84:87], v[152:155], v[192:195], v[84:87]
	v_mfma_f32_16x16x32_bf16 v[48:51], v[144:147], v[200:203], v[48:51]
	v_mfma_f32_16x16x32_bf16 v[52:55], v[152:155], v[200:203], v[52:55]
	v_mfma_f32_16x16x32_bf16 v[120:123], v[156:159], v[172:175], v[120:123]
	v_mfma_f32_16x16x32_bf16 v[124:127], v[164:167], v[172:175], v[124:127]
	v_mfma_f32_16x16x32_bf16 v[104:107], v[156:159], v[180:183], v[104:107]
	v_mfma_f32_16x16x32_bf16 v[108:111], v[164:167], v[180:183], v[108:111]
	v_mfma_f32_16x16x32_bf16 v[88:91], v[156:159], v[188:191], v[88:91]
	v_mfma_f32_16x16x32_bf16 v[92:95], v[164:167], v[188:191], v[92:95]
	v_mfma_f32_16x16x32_bf16 v[64:67], v[156:159], v[196:199], v[64:67]
	v_mfma_f32_16x16x32_bf16 v[68:71], v[164:167], v[196:199], v[68:71]
	v_mfma_f32_16x16x32_bf16 v[120:123], v[160:163], v[176:179], v[120:123]
	v_mfma_f32_16x16x32_bf16 v[124:127], v[168:171], v[176:179], v[124:127]
	v_mfma_f32_16x16x32_bf16 v[104:107], v[160:163], v[184:187], v[104:107]
	v_mfma_f32_16x16x32_bf16 v[108:111], v[168:171], v[184:187], v[108:111]
	v_mfma_f32_16x16x32_bf16 v[88:91], v[160:163], v[192:195], v[88:91]
	v_mfma_f32_16x16x32_bf16 v[92:95], v[168:171], v[192:195], v[92:95]
	v_mfma_f32_16x16x32_bf16 v[64:67], v[160:163], v[200:203], v[64:67]
	v_mfma_f32_16x16x32_bf16 v[68:71], v[168:171], v[200:203], v[68:71]
	s_barrier
	s_add_i32 s28, s59, s10
	v_lshl_add_u64 v[204:205], v[204:205], 0, s[24:25]
	s_mov_b32 m0, s28
	ds_read_b128 v[172:175], v139 offset:49152
	ds_read_b128 v[176:179], v139 offset:50176
	ds_read_b128 v[180:183], v139 offset:51200
	ds_read_b128 v[184:187], v139 offset:52224
	ds_read_b128 v[188:191], v139 offset:53248
	ds_read_b128 v[192:195], v139 offset:54272
	ds_read_b128 v[196:199], v139 offset:55296
	ds_read_b128 v[200:203], v139 offset:56320
	global_load_lds_dwordx4 v[204:205], off
	s_add_i32 m0, s28, 0x2000
	s_add_u32 s8, s8, 0x10080
	v_lshl_add_u64 v[204:205], v[206:207], 0, s[24:25]
	s_addc_u32 s9, s9, 0
	s_add_i32 s28, s60, s10
	global_load_lds_dwordx4 v[204:205], off
	v_lshl_add_u64 v[204:205], s[8:9], 0, v[224:225]
	s_mov_b32 m0, s28
	s_nop 0
	global_load_lds_dwordx4 v[204:205], off
	v_lshl_add_u64 v[204:205], s[8:9], 0, v[128:129]
	s_add_i32 m0, s28, 0x2000
	s_nop 0
	global_load_lds_dwordx4 v[204:205], off
	v_lshl_add_u64 v[204:205], v[208:209], 0, s[24:25]
	s_mov_b32 m0, s48
	s_nop 0
	global_load_lds_dwordx4 v[204:205], off
	v_lshl_add_u64 v[204:205], v[210:211], 0, s[24:25]
	s_mov_b32 m0, s49
	s_nop 0
	global_load_lds_dwordx4 v[204:205], off
	s_waitcnt vmcnt(8)
	s_waitcnt lgkmcnt(0)
	s_barrier
	s_waitcnt lgkmcnt(0)
	v_mfma_f32_16x16x32_bf16 v[56:59], v[140:143], v[172:175], v[56:59]
	v_mfma_f32_16x16x32_bf16 v[60:63], v[148:151], v[172:175], v[60:63]
	v_mfma_f32_16x16x32_bf16 v[32:35], v[140:143], v[180:183], v[32:35]
	v_mfma_f32_16x16x32_bf16 v[36:39], v[148:151], v[180:183], v[36:39]
	v_mfma_f32_16x16x32_bf16 v[16:19], v[140:143], v[188:191], v[16:19]
	v_mfma_f32_16x16x32_bf16 v[20:23], v[148:151], v[188:191], v[20:23]
	v_mfma_f32_16x16x32_bf16 v[0:3], v[140:143], v[196:199], v[0:3]
	v_mfma_f32_16x16x32_bf16 v[4:7], v[148:151], v[196:199], v[4:7]
	v_mfma_f32_16x16x32_bf16 v[56:59], v[144:147], v[176:179], v[56:59]
	v_mfma_f32_16x16x32_bf16 v[60:63], v[152:155], v[176:179], v[60:63]
	v_mfma_f32_16x16x32_bf16 v[32:35], v[144:147], v[184:187], v[32:35]
	v_mfma_f32_16x16x32_bf16 v[36:39], v[152:155], v[184:187], v[36:39]
	v_mfma_f32_16x16x32_bf16 v[16:19], v[144:147], v[192:195], v[16:19]
	v_mfma_f32_16x16x32_bf16 v[20:23], v[152:155], v[192:195], v[20:23]
	v_mfma_f32_16x16x32_bf16 v[0:3], v[144:147], v[200:203], v[0:3]
	v_mfma_f32_16x16x32_bf16 v[4:7], v[152:155], v[200:203], v[4:7]
	v_mfma_f32_16x16x32_bf16 v[72:75], v[156:159], v[172:175], v[72:75]
	v_mfma_f32_16x16x32_bf16 v[76:79], v[164:167], v[172:175], v[76:79]
	v_mfma_f32_16x16x32_bf16 v[40:43], v[156:159], v[180:183], v[40:43]
	v_mfma_f32_16x16x32_bf16 v[44:47], v[164:167], v[180:183], v[44:47]
	v_mfma_f32_16x16x32_bf16 v[24:27], v[156:159], v[188:191], v[24:27]
	v_mfma_f32_16x16x32_bf16 v[28:31], v[164:167], v[188:191], v[28:31]
	v_mfma_f32_16x16x32_bf16 v[8:11], v[156:159], v[196:199], v[8:11]
	v_mfma_f32_16x16x32_bf16 v[12:15], v[164:167], v[196:199], v[12:15]
	v_mfma_f32_16x16x32_bf16 v[72:75], v[160:163], v[176:179], v[72:75]
	v_mfma_f32_16x16x32_bf16 v[76:79], v[168:171], v[176:179], v[76:79]
	v_mfma_f32_16x16x32_bf16 v[40:43], v[160:163], v[184:187], v[40:43]
	v_mfma_f32_16x16x32_bf16 v[44:47], v[168:171], v[184:187], v[44:47]
	v_mfma_f32_16x16x32_bf16 v[24:27], v[160:163], v[192:195], v[24:27]
	v_mfma_f32_16x16x32_bf16 v[28:31], v[168:171], v[192:195], v[28:31]
	v_mfma_f32_16x16x32_bf16 v[8:11], v[160:163], v[200:203], v[8:11]
	v_mfma_f32_16x16x32_bf16 v[12:15], v[168:171], v[200:203], v[12:15]
	s_barrier
	s_add_u32 s12, s12, 0x100
	s_addc_u32 s13, s13, 0
	s_add_u32 s56, s56, 0x100
	s_addc_u32 s57, s57, 0
	s_cmp_ge_i32 s58, s47
	s_mov_b32 s8, s58
	s_cbranch_scc0 .LBB0_2092
	s_mov_b64 s[56:57], 0x400000
	s_mov_b64 s[58:59], 0x3fffff
	s_mov_b64 s[60:61], 0x20000

.LBB0_2239:
	s_add_i32 s30, s28, 2
	s_add_u32 s8, s12, 0x100
	s_addc_u32 s9, s13, 0
	s_add_i32 s31, 0, 0x10000
	s_cmp_eq_u32 s63, s28
	s_cselect_b32 s49, s43, s9
	s_cselect_b32 s48, s42, s8
	s_cselect_b32 s29, s47, s7
	s_cselect_b32 s28, s46, s3
	s_add_i32 s33, 0, 0x14000
	v_add_u32_e32 v100, s31, v230
	v_add_u32_e32 v124, s33, v230
	ds_read_b128 v[84:87], v100
	ds_read_b128 v[88:91], v100 offset:1024
	ds_read_b128 v[96:99], v100 offset:2048
	ds_read_b128 v[100:103], v100 offset:3072
	ds_read_b128 v[112:115], v124
	ds_read_b128 v[116:119], v124 offset:1024
	ds_read_b128 v[120:123], v124 offset:2048
	ds_read_b128 v[124:127], v124 offset:3072
	v_lshl_add_u64 v[202:203], s[12:13], 0, v[198:199]
	s_add_i32 m0, s56, 0xc000
	ds_read_b128 v[160:163], v231
	ds_read_b128 v[164:167], v231 offset:1024
	ds_read_b128 v[168:171], v231 offset:2048
	ds_read_b128 v[172:175], v231 offset:3072
	ds_read_b128 v[176:179], v231 offset:4096
	ds_read_b128 v[180:183], v231 offset:5120
	ds_read_b128 v[184:187], v231 offset:6144
	ds_read_b128 v[188:191], v231 offset:7168
	global_load_lds_dwordx4 v[202:203], off
	v_lshl_add_u64 v[202:203], s[12:13], 0, v[200:201]
	s_add_i32 m0, s56, 0xe000
	s_nop 0
	global_load_lds_dwordx4 v[202:203], off
	s_waitcnt vmcnt(8)
	s_waitcnt lgkmcnt(0)
	s_barrier
	s_waitcnt lgkmcnt(0)
	v_mfma_f32_16x16x32_bf16 v[152:155], v[84:87], v[160:163], v[152:155]
	v_mfma_f32_16x16x32_bf16 v[156:159], v[96:99], v[160:163], v[156:159]
	v_mfma_f32_16x16x32_bf16 v[140:143], v[84:87], v[168:171], v[140:143]
	v_mfma_f32_16x16x32_bf16 v[136:139], v[96:99], v[168:171], v[136:139]
	v_mfma_f32_16x16x32_bf16 v[108:111], v[84:87], v[176:179], v[108:111]
	v_mfma_f32_16x16x32_bf16 v[104:107], v[96:99], v[176:179], v[104:107]
	v_mfma_f32_16x16x32_bf16 v[76:79], v[84:87], v[184:187], v[76:79]
	v_mfma_f32_16x16x32_bf16 v[72:75], v[96:99], v[184:187], v[72:75]
	v_mfma_f32_16x16x32_bf16 v[152:155], v[88:91], v[164:167], v[152:155]
	v_mfma_f32_16x16x32_bf16 v[156:159], v[100:103], v[164:167], v[156:159]
	v_mfma_f32_16x16x32_bf16 v[140:143], v[88:91], v[172:175], v[140:143]
	v_mfma_f32_16x16x32_bf16 v[136:139], v[100:103], v[172:175], v[136:139]
	v_mfma_f32_16x16x32_bf16 v[108:111], v[88:91], v[180:183], v[108:111]
	v_mfma_f32_16x16x32_bf16 v[104:107], v[100:103], v[180:183], v[104:107]
	v_mfma_f32_16x16x32_bf16 v[76:79], v[88:91], v[188:191], v[76:79]
	v_mfma_f32_16x16x32_bf16 v[72:75], v[100:103], v[188:191], v[72:75]
	v_mfma_f32_16x16x32_bf16 v[148:151], v[112:115], v[160:163], v[148:151]
	v_mfma_f32_16x16x32_bf16 v[144:147], v[120:123], v[160:163], v[144:147]
	v_mfma_f32_16x16x32_bf16 v[132:135], v[112:115], v[168:171], v[132:135]
	v_mfma_f32_16x16x32_bf16 v[128:131], v[120:123], v[168:171], v[128:131]
	v_mfma_f32_16x16x32_bf16 v[92:95], v[112:115], v[176:179], v[92:95]
	v_mfma_f32_16x16x32_bf16 v[80:83], v[120:123], v[176:179], v[80:83]
	v_mfma_f32_16x16x32_bf16 v[68:71], v[112:115], v[184:187], v[68:71]
	v_mfma_f32_16x16x32_bf16 v[64:67], v[120:123], v[184:187], v[64:67]
	v_mfma_f32_16x16x32_bf16 v[148:151], v[116:119], v[164:167], v[148:151]
	v_mfma_f32_16x16x32_bf16 v[144:147], v[124:127], v[164:167], v[144:147]
	v_mfma_f32_16x16x32_bf16 v[132:135], v[116:119], v[172:175], v[132:135]
	v_mfma_f32_16x16x32_bf16 v[128:131], v[124:127], v[172:175], v[128:131]
	v_mfma_f32_16x16x32_bf16 v[92:95], v[116:119], v[180:183], v[92:95]
	v_mfma_f32_16x16x32_bf16 v[80:83], v[124:127], v[180:183], v[80:83]
	v_mfma_f32_16x16x32_bf16 v[68:71], v[116:119], v[188:191], v[68:71]
	v_mfma_f32_16x16x32_bf16 v[64:67], v[124:127], v[188:191], v[64:67]
	s_barrier
	s_add_i32 s12, s31, s54
	v_lshl_add_u64 v[202:203], s[28:29], 0, v[224:225]
	s_mov_b32 m0, s12
	ds_read_b128 v[160:163], v231 offset:16384
	ds_read_b128 v[164:167], v231 offset:17408
	ds_read_b128 v[168:171], v231 offset:18432
	ds_read_b128 v[172:175], v231 offset:19456
	ds_read_b128 v[176:179], v231 offset:20480
	ds_read_b128 v[180:183], v231 offset:21504
	ds_read_b128 v[184:187], v231 offset:22528
	ds_read_b128 v[188:191], v231 offset:23552
	global_load_lds_dwordx4 v[202:203], off
	s_add_i32 m0, s12, 0x2000
	s_add_u32 s12, s28, 0x158000
	v_lshl_add_u64 v[204:205], s[28:29], 0, v[192:193]
	s_addc_u32 s13, s29, 0
	s_add_i32 s31, s33, s54
	global_load_lds_dwordx4 v[204:205], off
	v_lshl_add_u64 v[206:207], s[12:13], 0, v[224:225]
	s_mov_b32 m0, s31
	v_lshl_add_u64 v[208:209], s[48:49], 0, v[194:195]
	global_load_lds_dwordx4 v[206:207], off
	v_lshl_add_u64 v[206:207], s[12:13], 0, v[192:193]
	s_add_i32 m0, s31, 0x2000
	s_nop 0
	global_load_lds_dwordx4 v[206:207], off
	v_lshl_add_u64 v[206:207], s[48:49], 0, v[196:197]
	s_mov_b32 m0, s56
	s_nop 0
	global_load_lds_dwordx4 v[206:207], off
	s_mov_b32 m0, s57
	s_nop 0
	global_load_lds_dwordx4 v[208:209], off
	s_waitcnt vmcnt(8)
	s_waitcnt lgkmcnt(0)
	s_barrier
	s_waitcnt lgkmcnt(0)
	v_mfma_f32_16x16x32_bf16 v[60:63], v[84:87], v[160:163], v[60:63]
	v_mfma_f32_16x16x32_bf16 v[56:59], v[96:99], v[160:163], v[56:59]
	v_mfma_f32_16x16x32_bf16 v[44:47], v[84:87], v[168:171], v[44:47]
	v_mfma_f32_16x16x32_bf16 v[40:43], v[96:99], v[168:171], v[40:43]
	v_mfma_f32_16x16x32_bf16 v[28:31], v[84:87], v[176:179], v[28:31]
	v_mfma_f32_16x16x32_bf16 v[24:27], v[96:99], v[176:179], v[24:27]
	v_mfma_f32_16x16x32_bf16 v[12:15], v[84:87], v[184:187], v[12:15]
	v_mfma_f32_16x16x32_bf16 v[8:11], v[96:99], v[184:187], v[8:11]
	v_mfma_f32_16x16x32_bf16 v[60:63], v[88:91], v[164:167], v[60:63]
	v_mfma_f32_16x16x32_bf16 v[56:59], v[100:103], v[164:167], v[56:59]
	v_mfma_f32_16x16x32_bf16 v[44:47], v[88:91], v[172:175], v[44:47]
	v_mfma_f32_16x16x32_bf16 v[40:43], v[100:103], v[172:175], v[40:43]
	v_mfma_f32_16x16x32_bf16 v[28:31], v[88:91], v[180:183], v[28:31]
	v_mfma_f32_16x16x32_bf16 v[24:27], v[100:103], v[180:183], v[24:27]
	v_mfma_f32_16x16x32_bf16 v[12:15], v[88:91], v[188:191], v[12:15]
	v_mfma_f32_16x16x32_bf16 v[8:11], v[100:103], v[188:191], v[8:11]
	v_mfma_f32_16x16x32_bf16 v[52:55], v[112:115], v[160:163], v[52:55]
	v_mfma_f32_16x16x32_bf16 v[48:51], v[120:123], v[160:163], v[48:51]
	v_mfma_f32_16x16x32_bf16 v[36:39], v[112:115], v[168:171], v[36:39]
	v_mfma_f32_16x16x32_bf16 v[32:35], v[120:123], v[168:171], v[32:35]
	v_mfma_f32_16x16x32_bf16 v[20:23], v[112:115], v[176:179], v[20:23]
	v_mfma_f32_16x16x32_bf16 v[16:19], v[120:123], v[176:179], v[16:19]
	v_mfma_f32_16x16x32_bf16 v[4:7], v[112:115], v[184:187], v[4:7]
	v_mfma_f32_16x16x32_bf16 v[0:3], v[120:123], v[184:187], v[0:3]
	v_mfma_f32_16x16x32_bf16 v[52:55], v[116:119], v[164:167], v[52:55]
	v_mfma_f32_16x16x32_bf16 v[48:51], v[124:127], v[164:167], v[48:51]
	v_mfma_f32_16x16x32_bf16 v[36:39], v[116:119], v[172:175], v[36:39]
	v_mfma_f32_16x16x32_bf16 v[32:35], v[124:127], v[172:175], v[32:35]
	v_mfma_f32_16x16x32_bf16 v[20:23], v[116:119], v[180:183], v[20:23]
	v_mfma_f32_16x16x32_bf16 v[16:19], v[124:127], v[180:183], v[16:19]
	v_mfma_f32_16x16x32_bf16 v[4:7], v[116:119], v[188:191], v[4:7]
	v_mfma_f32_16x16x32_bf16 v[0:3], v[124:127], v[188:191], v[0:3]
	s_barrier
	s_add_i32 s31, 0, 0x18000
	s_add_i32 s33, 0, 0x1c000
	v_add_u32_e32 v100, s31, v230
	v_add_u32_e32 v124, s33, v230
	ds_read_b128 v[84:87], v100
	ds_read_b128 v[88:91], v100 offset:1024
	ds_read_b128 v[96:99], v100 offset:2048
	ds_read_b128 v[100:103], v100 offset:3072
	ds_read_b128 v[112:115], v124
	ds_read_b128 v[116:119], v124 offset:1024
	ds_read_b128 v[120:123], v124 offset:2048
	ds_read_b128 v[124:127], v124 offset:3072
	s_add_u32 s12, s48, 0x158000
	s_addc_u32 s13, s49, 0
	s_mov_b32 m0, s58
	v_lshl_add_u64 v[210:211], s[12:13], 0, v[196:197]
	ds_read_b128 v[160:163], v231 offset:32768
	ds_read_b128 v[164:167], v231 offset:33792
	ds_read_b128 v[168:171], v231 offset:34816
	ds_read_b128 v[172:175], v231 offset:35840
	ds_read_b128 v[176:179], v231 offset:36864
	ds_read_b128 v[180:183], v231 offset:37888
	ds_read_b128 v[184:187], v231 offset:38912
	ds_read_b128 v[188:191], v231 offset:39936
	global_load_lds_dwordx4 v[210:211], off
	v_lshl_add_u64 v[210:211], s[12:13], 0, v[194:195]
	s_mov_b32 m0, s59
	s_nop 0
	global_load_lds_dwordx4 v[210:211], off
	s_waitcnt vmcnt(8)
	s_waitcnt lgkmcnt(0)
	s_barrier
	s_waitcnt lgkmcnt(0)
	v_mfma_f32_16x16x32_bf16 v[152:155], v[84:87], v[160:163], v[152:155]
	v_mfma_f32_16x16x32_bf16 v[156:159], v[96:99], v[160:163], v[156:159]
	v_mfma_f32_16x16x32_bf16 v[140:143], v[84:87], v[168:171], v[140:143]
	v_mfma_f32_16x16x32_bf16 v[136:139], v[96:99], v[168:171], v[136:139]
	v_mfma_f32_16x16x32_bf16 v[108:111], v[84:87], v[176:179], v[108:111]
	v_mfma_f32_16x16x32_bf16 v[104:107], v[96:99], v[176:179], v[104:107]
	v_mfma_f32_16x16x32_bf16 v[76:79], v[84:87], v[184:187], v[76:79]
	v_mfma_f32_16x16x32_bf16 v[72:75], v[96:99], v[184:187], v[72:75]
	v_mfma_f32_16x16x32_bf16 v[152:155], v[88:91], v[164:167], v[152:155]
	v_mfma_f32_16x16x32_bf16 v[156:159], v[100:103], v[164:167], v[156:159]
	v_mfma_f32_16x16x32_bf16 v[140:143], v[88:91], v[172:175], v[140:143]
	v_mfma_f32_16x16x32_bf16 v[136:139], v[100:103], v[172:175], v[136:139]
	v_mfma_f32_16x16x32_bf16 v[108:111], v[88:91], v[180:183], v[108:111]
	v_mfma_f32_16x16x32_bf16 v[104:107], v[100:103], v[180:183], v[104:107]
	v_mfma_f32_16x16x32_bf16 v[76:79], v[88:91], v[188:191], v[76:79]
	v_mfma_f32_16x16x32_bf16 v[72:75], v[100:103], v[188:191], v[72:75]
	v_mfma_f32_16x16x32_bf16 v[148:151], v[112:115], v[160:163], v[148:151]
	v_mfma_f32_16x16x32_bf16 v[144:147], v[120:123], v[160:163], v[144:147]
	v_mfma_f32_16x16x32_bf16 v[132:135], v[112:115], v[168:171], v[132:135]
	v_mfma_f32_16x16x32_bf16 v[128:131], v[120:123], v[168:171], v[128:131]
	v_mfma_f32_16x16x32_bf16 v[92:95], v[112:115], v[176:179], v[92:95]
	v_mfma_f32_16x16x32_bf16 v[80:83], v[120:123], v[176:179], v[80:83]
	v_mfma_f32_16x16x32_bf16 v[68:71], v[112:115], v[184:187], v[68:71]
	v_mfma_f32_16x16x32_bf16 v[64:67], v[120:123], v[184:187], v[64:67]
	v_mfma_f32_16x16x32_bf16 v[148:151], v[116:119], v[164:167], v[148:151]
	v_mfma_f32_16x16x32_bf16 v[144:147], v[124:127], v[164:167], v[144:147]
	v_mfma_f32_16x16x32_bf16 v[132:135], v[116:119], v[172:175], v[132:135]
	v_mfma_f32_16x16x32_bf16 v[128:131], v[124:127], v[172:175], v[128:131]
	v_mfma_f32_16x16x32_bf16 v[92:95], v[116:119], v[180:183], v[92:95]
	v_mfma_f32_16x16x32_bf16 v[80:83], v[124:127], v[180:183], v[80:83]
	v_mfma_f32_16x16x32_bf16 v[68:71], v[116:119], v[188:191], v[68:71]
	v_mfma_f32_16x16x32_bf16 v[64:67], v[124:127], v[188:191], v[64:67]
	s_barrier
	s_add_i32 s12, s31, s54
	v_lshl_add_u64 v[202:203], v[202:203], 0, s[24:25]
	s_mov_b32 m0, s12
	ds_read_b128 v[160:163], v231 offset:49152
	ds_read_b128 v[164:167], v231 offset:50176
	ds_read_b128 v[168:171], v231 offset:51200
	ds_read_b128 v[172:175], v231 offset:52224
	ds_read_b128 v[176:179], v231 offset:53248
	ds_read_b128 v[180:183], v231 offset:54272
	ds_read_b128 v[184:187], v231 offset:55296
	ds_read_b128 v[188:191], v231 offset:56320
	global_load_lds_dwordx4 v[202:203], off
	s_add_i32 m0, s12, 0x2000
	s_add_u32 s12, s28, 0x158080
	v_lshl_add_u64 v[202:203], v[204:205], 0, s[24:25]
	s_addc_u32 s13, s29, 0
	s_add_i32 s28, s33, s54
	global_load_lds_dwordx4 v[202:203], off
	v_lshl_add_u64 v[202:203], s[12:13], 0, v[224:225]
	s_mov_b32 m0, s28
	s_nop 0
	global_load_lds_dwordx4 v[202:203], off
	v_lshl_add_u64 v[202:203], s[12:13], 0, v[192:193]
	s_add_i32 m0, s28, 0x2000
	s_nop 0
	global_load_lds_dwordx4 v[202:203], off
	v_lshl_add_u64 v[202:203], v[206:207], 0, s[24:25]
	s_mov_b32 m0, s61
	s_nop 0
	global_load_lds_dwordx4 v[202:203], off
	v_lshl_add_u64 v[202:203], v[208:209], 0, s[24:25]
	s_mov_b32 m0, s62
	s_nop 0
	global_load_lds_dwordx4 v[202:203], off
	s_waitcnt vmcnt(8)
	s_waitcnt lgkmcnt(0)
	s_barrier
	s_waitcnt lgkmcnt(0)
	v_mfma_f32_16x16x32_bf16 v[60:63], v[84:87], v[160:163], v[60:63]
	v_mfma_f32_16x16x32_bf16 v[56:59], v[96:99], v[160:163], v[56:59]
	v_mfma_f32_16x16x32_bf16 v[44:47], v[84:87], v[168:171], v[44:47]
	v_mfma_f32_16x16x32_bf16 v[40:43], v[96:99], v[168:171], v[40:43]
	v_mfma_f32_16x16x32_bf16 v[28:31], v[84:87], v[176:179], v[28:31]
	v_mfma_f32_16x16x32_bf16 v[24:27], v[96:99], v[176:179], v[24:27]
	v_mfma_f32_16x16x32_bf16 v[12:15], v[84:87], v[184:187], v[12:15]
	v_mfma_f32_16x16x32_bf16 v[8:11], v[96:99], v[184:187], v[8:11]
	v_mfma_f32_16x16x32_bf16 v[60:63], v[88:91], v[164:167], v[60:63]
	v_mfma_f32_16x16x32_bf16 v[56:59], v[100:103], v[164:167], v[56:59]
	v_mfma_f32_16x16x32_bf16 v[44:47], v[88:91], v[172:175], v[44:47]
	v_mfma_f32_16x16x32_bf16 v[40:43], v[100:103], v[172:175], v[40:43]
	v_mfma_f32_16x16x32_bf16 v[28:31], v[88:91], v[180:183], v[28:31]
	v_mfma_f32_16x16x32_bf16 v[24:27], v[100:103], v[180:183], v[24:27]
	v_mfma_f32_16x16x32_bf16 v[12:15], v[88:91], v[188:191], v[12:15]
	v_mfma_f32_16x16x32_bf16 v[8:11], v[100:103], v[188:191], v[8:11]
	v_mfma_f32_16x16x32_bf16 v[52:55], v[112:115], v[160:163], v[52:55]
	v_mfma_f32_16x16x32_bf16 v[48:51], v[120:123], v[160:163], v[48:51]
	v_mfma_f32_16x16x32_bf16 v[36:39], v[112:115], v[168:171], v[36:39]
	v_mfma_f32_16x16x32_bf16 v[32:35], v[120:123], v[168:171], v[32:35]
	v_mfma_f32_16x16x32_bf16 v[20:23], v[112:115], v[176:179], v[20:23]
	v_mfma_f32_16x16x32_bf16 v[16:19], v[120:123], v[176:179], v[16:19]
	v_mfma_f32_16x16x32_bf16 v[4:7], v[112:115], v[184:187], v[4:7]
	v_mfma_f32_16x16x32_bf16 v[0:3], v[120:123], v[184:187], v[0:3]
	v_mfma_f32_16x16x32_bf16 v[52:55], v[116:119], v[164:167], v[52:55]
	v_mfma_f32_16x16x32_bf16 v[48:51], v[124:127], v[164:167], v[48:51]
	v_mfma_f32_16x16x32_bf16 v[36:39], v[116:119], v[172:175], v[36:39]
	v_mfma_f32_16x16x32_bf16 v[32:35], v[124:127], v[172:175], v[32:35]
	v_mfma_f32_16x16x32_bf16 v[20:23], v[116:119], v[180:183], v[20:23]
	v_mfma_f32_16x16x32_bf16 v[16:19], v[124:127], v[180:183], v[16:19]
	v_mfma_f32_16x16x32_bf16 v[4:7], v[116:119], v[188:191], v[4:7]
	v_mfma_f32_16x16x32_bf16 v[0:3], v[124:127], v[188:191], v[0:3]
	s_barrier
	s_add_u32 s3, s3, 0x100
	s_addc_u32 s7, s7, 0
	s_cmp_ge_i32 s30, s60
	s_mov_b64 s[12:13], s[8:9]
	s_mov_b32 s28, s30
	s_cbranch_scc0 .LBB0_2239
	v_readlane_b32 s48, v253, 35
	v_readlane_b32 s49, v253, 36
	s_and_b64 vcc, exec, s[44:45]
	s_cbranch_vccnz .LBB0_2244
	s_branch .LBB0_2245

.LBB0_2404:
	s_add_i32 s40, s8, 2
	s_add_u32 s9, s12, 0xfff80080
	s_addc_u32 s16, s13, -1
	s_add_i32 s41, 0, 0x10000
	s_cmp_eq_u32 s93, s8
	s_cselect_b32 s17, s7, s16
	s_cselect_b32 s16, s22, s9
	s_cselect_b32 s9, s23, s33
	s_cselect_b32 s8, s30, s31
	s_add_i32 s71, 0, 0x14000
	v_add_u32_e32 v52, s41, v202
	v_add_u32_e32 v156, s71, v202
	ds_read_b128 v[40:43], v52
	ds_read_b128 v[44:47], v52 offset:1024
	ds_read_b128 v[48:51], v52 offset:2048
	ds_read_b128 v[52:55], v52 offset:3072
	ds_read_b128 v[80:83], v156
	ds_read_b128 v[84:87], v156 offset:1024
	ds_read_b128 v[152:155], v156 offset:2048
	ds_read_b128 v[156:159], v156 offset:3072
	v_lshl_add_u64 v[204:205], s[12:13], 0, v[182:183]
	s_add_i32 m0, s84, 0xc000
	ds_read_b128 v[160:163], v203
	ds_read_b128 v[164:167], v203 offset:1024
	ds_read_b128 v[168:171], v203 offset:2048
	ds_read_b128 v[172:175], v203 offset:3072
	ds_read_b128 v[186:189], v203 offset:4096
	ds_read_b128 v[190:193], v203 offset:5120
	ds_read_b128 v[194:197], v203 offset:6144
	ds_read_b128 v[198:201], v203 offset:7168
	global_load_lds_dwordx4 v[204:205], off
	v_lshl_add_u64 v[204:205], s[12:13], 0, v[184:185]
	s_add_i32 m0, s84, 0xe000
	s_nop 0
	global_load_lds_dwordx4 v[204:205], off
	s_waitcnt vmcnt(8)
	s_waitcnt lgkmcnt(0)
	s_barrier
	s_waitcnt lgkmcnt(0)
	v_mfma_f32_16x16x32_bf16 v[76:79], v[40:43], v[160:163], v[76:79]
	v_mfma_f32_16x16x32_bf16 v[72:75], v[48:51], v[160:163], v[72:75]
	v_mfma_f32_16x16x32_bf16 v[140:143], v[40:43], v[168:171], v[140:143]
	v_mfma_f32_16x16x32_bf16 v[136:139], v[48:51], v[168:171], v[136:139]
	v_mfma_f32_16x16x32_bf16 v[124:127], v[40:43], v[186:189], v[124:127]
	v_mfma_f32_16x16x32_bf16 v[120:123], v[48:51], v[186:189], v[120:123]
	v_mfma_f32_16x16x32_bf16 v[108:111], v[40:43], v[194:197], v[108:111]
	v_mfma_f32_16x16x32_bf16 v[104:107], v[48:51], v[194:197], v[104:107]
	v_mfma_f32_16x16x32_bf16 v[76:79], v[44:47], v[164:167], v[76:79]
	v_mfma_f32_16x16x32_bf16 v[72:75], v[52:55], v[164:167], v[72:75]
	v_mfma_f32_16x16x32_bf16 v[140:143], v[44:47], v[172:175], v[140:143]
	v_mfma_f32_16x16x32_bf16 v[136:139], v[52:55], v[172:175], v[136:139]
	v_mfma_f32_16x16x32_bf16 v[124:127], v[44:47], v[190:193], v[124:127]
	v_mfma_f32_16x16x32_bf16 v[120:123], v[52:55], v[190:193], v[120:123]
	v_mfma_f32_16x16x32_bf16 v[108:111], v[44:47], v[198:201], v[108:111]
	v_mfma_f32_16x16x32_bf16 v[104:107], v[52:55], v[198:201], v[104:107]
	v_mfma_f32_16x16x32_bf16 v[148:151], v[80:83], v[160:163], v[148:151]
	v_mfma_f32_16x16x32_bf16 v[144:147], v[152:155], v[160:163], v[144:147]
	v_mfma_f32_16x16x32_bf16 v[132:135], v[80:83], v[168:171], v[132:135]
	v_mfma_f32_16x16x32_bf16 v[128:131], v[152:155], v[168:171], v[128:131]
	v_mfma_f32_16x16x32_bf16 v[116:119], v[80:83], v[186:189], v[116:119]
	v_mfma_f32_16x16x32_bf16 v[112:115], v[152:155], v[186:189], v[112:115]
	v_mfma_f32_16x16x32_bf16 v[100:103], v[80:83], v[194:197], v[100:103]
	v_mfma_f32_16x16x32_bf16 v[96:99], v[152:155], v[194:197], v[96:99]
	v_mfma_f32_16x16x32_bf16 v[148:151], v[84:87], v[164:167], v[148:151]
	v_mfma_f32_16x16x32_bf16 v[144:147], v[156:159], v[164:167], v[144:147]
	v_mfma_f32_16x16x32_bf16 v[132:135], v[84:87], v[172:175], v[132:135]
	v_mfma_f32_16x16x32_bf16 v[128:131], v[156:159], v[172:175], v[128:131]
	v_mfma_f32_16x16x32_bf16 v[116:119], v[84:87], v[190:193], v[116:119]
	v_mfma_f32_16x16x32_bf16 v[112:115], v[156:159], v[190:193], v[112:115]
	v_mfma_f32_16x16x32_bf16 v[100:103], v[84:87], v[198:201], v[100:103]
	v_mfma_f32_16x16x32_bf16 v[96:99], v[156:159], v[198:201], v[96:99]
	s_barrier
	s_add_i32 s41, s41, s28
	v_lshl_add_u64 v[204:205], s[8:9], 0, v[224:225]
	s_mov_b32 m0, s41
	ds_read_b128 v[160:163], v203 offset:16384
	ds_read_b128 v[164:167], v203 offset:17408
	ds_read_b128 v[168:171], v203 offset:18432
	ds_read_b128 v[172:175], v203 offset:19456
	ds_read_b128 v[186:189], v203 offset:20480
	ds_read_b128 v[190:193], v203 offset:21504
	ds_read_b128 v[194:197], v203 offset:22528
	ds_read_b128 v[198:201], v203 offset:23552
	global_load_lds_dwordx4 v[204:205], off
	s_add_i32 m0, s41, 0x2000
	s_add_u32 s42, s8, 0x80000
	v_lshl_add_u64 v[206:207], s[8:9], 0, v[176:177]
	s_addc_u32 s43, s9, 0
	s_add_i32 s41, s71, s28
	global_load_lds_dwordx4 v[206:207], off
	v_lshl_add_u64 v[208:209], s[42:43], 0, v[224:225]
	s_mov_b32 m0, s41
	v_lshl_add_u64 v[210:211], s[16:17], 0, v[178:179]
	global_load_lds_dwordx4 v[208:209], off
	v_lshl_add_u64 v[208:209], s[42:43], 0, v[176:177]
	s_add_i32 m0, s41, 0x2000
	s_nop 0
	global_load_lds_dwordx4 v[208:209], off
	v_lshl_add_u64 v[208:209], s[16:17], 0, v[180:181]
	s_mov_b32 m0, s84
	s_nop 0
	global_load_lds_dwordx4 v[208:209], off
	s_mov_b32 m0, s85
	s_nop 0
	global_load_lds_dwordx4 v[210:211], off
	s_waitcnt vmcnt(8)
	s_waitcnt lgkmcnt(0)
	s_barrier
	s_waitcnt lgkmcnt(0)
	v_mfma_f32_16x16x32_bf16 v[92:95], v[40:43], v[160:163], v[92:95]
	v_mfma_f32_16x16x32_bf16 v[88:91], v[48:51], v[160:163], v[88:91]
	v_mfma_f32_16x16x32_bf16 v[60:63], v[40:43], v[168:171], v[60:63]
	v_mfma_f32_16x16x32_bf16 v[56:59], v[48:51], v[168:171], v[56:59]
	v_mfma_f32_16x16x32_bf16 v[28:31], v[40:43], v[186:189], v[28:31]
	v_mfma_f32_16x16x32_bf16 v[24:27], v[48:51], v[186:189], v[24:27]
	v_mfma_f32_16x16x32_bf16 v[12:15], v[40:43], v[194:197], v[12:15]
	v_mfma_f32_16x16x32_bf16 v[8:11], v[48:51], v[194:197], v[8:11]
	v_mfma_f32_16x16x32_bf16 v[92:95], v[44:47], v[164:167], v[92:95]
	v_mfma_f32_16x16x32_bf16 v[88:91], v[52:55], v[164:167], v[88:91]
	v_mfma_f32_16x16x32_bf16 v[60:63], v[44:47], v[172:175], v[60:63]
	v_mfma_f32_16x16x32_bf16 v[56:59], v[52:55], v[172:175], v[56:59]
	v_mfma_f32_16x16x32_bf16 v[28:31], v[44:47], v[190:193], v[28:31]
	v_mfma_f32_16x16x32_bf16 v[24:27], v[52:55], v[190:193], v[24:27]
	v_mfma_f32_16x16x32_bf16 v[12:15], v[44:47], v[198:201], v[12:15]
	v_mfma_f32_16x16x32_bf16 v[8:11], v[52:55], v[198:201], v[8:11]
	v_mfma_f32_16x16x32_bf16 v[36:39], v[80:83], v[168:171], v[36:39]
	v_mfma_f32_16x16x32_bf16 v[32:35], v[152:155], v[168:171], v[32:35]
	v_mfma_f32_16x16x32_bf16 v[20:23], v[80:83], v[186:189], v[20:23]
	v_mfma_f32_16x16x32_bf16 v[16:19], v[152:155], v[186:189], v[16:19]
	v_mfma_f32_16x16x32_bf16 v[4:7], v[80:83], v[194:197], v[4:7]
	v_mfma_f32_16x16x32_bf16 v[0:3], v[152:155], v[194:197], v[0:3]
	v_mfma_f32_16x16x32_bf16 v[40:43], v[80:83], v[160:163], v[68:71]
	v_mfma_f32_16x16x32_bf16 v[44:47], v[152:155], v[160:163], v[64:67]
	v_mfma_f32_16x16x32_bf16 v[36:39], v[84:87], v[172:175], v[36:39]
	v_mfma_f32_16x16x32_bf16 v[32:35], v[156:159], v[172:175], v[32:35]
	v_mfma_f32_16x16x32_bf16 v[20:23], v[84:87], v[190:193], v[20:23]
	v_mfma_f32_16x16x32_bf16 v[16:19], v[156:159], v[190:193], v[16:19]
	v_mfma_f32_16x16x32_bf16 v[4:7], v[84:87], v[198:201], v[4:7]
	v_mfma_f32_16x16x32_bf16 v[0:3], v[156:159], v[198:201], v[0:3]
	v_mfma_f32_16x16x32_bf16 v[40:43], v[84:87], v[164:167], v[40:43]
	v_mfma_f32_16x16x32_bf16 v[44:47], v[156:159], v[164:167], v[44:47]
	s_barrier
	s_add_i32 s41, 0, 0x18000
	s_add_i32 s42, 0, 0x1c000
	v_add_u32_e32 v68, s41, v202
	v_add_u32_e32 v156, s42, v202
	ds_read_b128 v[48:51], v68
	ds_read_b128 v[52:55], v68 offset:1024
	ds_read_b128 v[64:67], v68 offset:2048
	ds_read_b128 v[68:71], v68 offset:3072
	ds_read_b128 v[80:83], v156
	ds_read_b128 v[84:87], v156 offset:1024
	ds_read_b128 v[152:155], v156 offset:2048
	ds_read_b128 v[156:159], v156 offset:3072
	s_add_u32 s16, s16, 0x80000
	s_addc_u32 s17, s17, 0
	s_mov_b32 m0, s86
	v_lshl_add_u64 v[212:213], s[16:17], 0, v[180:181]
	ds_read_b128 v[160:163], v203 offset:32768
	ds_read_b128 v[164:167], v203 offset:33792
	ds_read_b128 v[168:171], v203 offset:34816
	ds_read_b128 v[172:175], v203 offset:35840
	ds_read_b128 v[186:189], v203 offset:36864
	ds_read_b128 v[190:193], v203 offset:37888
	ds_read_b128 v[194:197], v203 offset:38912
	ds_read_b128 v[198:201], v203 offset:39936
	global_load_lds_dwordx4 v[212:213], off
	v_lshl_add_u64 v[212:213], s[16:17], 0, v[178:179]
	s_mov_b32 m0, s87
	s_nop 0
	global_load_lds_dwordx4 v[212:213], off
	s_waitcnt vmcnt(8)
	s_waitcnt lgkmcnt(0)
	s_barrier
	s_waitcnt lgkmcnt(0)
	v_mfma_f32_16x16x32_bf16 v[76:79], v[48:51], v[160:163], v[76:79]
	v_mfma_f32_16x16x32_bf16 v[72:75], v[64:67], v[160:163], v[72:75]
	v_mfma_f32_16x16x32_bf16 v[140:143], v[48:51], v[168:171], v[140:143]
	v_mfma_f32_16x16x32_bf16 v[136:139], v[64:67], v[168:171], v[136:139]
	v_mfma_f32_16x16x32_bf16 v[124:127], v[48:51], v[186:189], v[124:127]
	v_mfma_f32_16x16x32_bf16 v[120:123], v[64:67], v[186:189], v[120:123]
	v_mfma_f32_16x16x32_bf16 v[108:111], v[48:51], v[194:197], v[108:111]
	v_mfma_f32_16x16x32_bf16 v[104:107], v[64:67], v[194:197], v[104:107]
	v_mfma_f32_16x16x32_bf16 v[76:79], v[52:55], v[164:167], v[76:79]
	v_mfma_f32_16x16x32_bf16 v[72:75], v[68:71], v[164:167], v[72:75]
	v_mfma_f32_16x16x32_bf16 v[140:143], v[52:55], v[172:175], v[140:143]
	v_mfma_f32_16x16x32_bf16 v[136:139], v[68:71], v[172:175], v[136:139]
	v_mfma_f32_16x16x32_bf16 v[124:127], v[52:55], v[190:193], v[124:127]
	v_mfma_f32_16x16x32_bf16 v[120:123], v[68:71], v[190:193], v[120:123]
	v_mfma_f32_16x16x32_bf16 v[108:111], v[52:55], v[198:201], v[108:111]
	v_mfma_f32_16x16x32_bf16 v[104:107], v[68:71], v[198:201], v[104:107]
	v_mfma_f32_16x16x32_bf16 v[148:151], v[80:83], v[160:163], v[148:151]
	v_mfma_f32_16x16x32_bf16 v[144:147], v[152:155], v[160:163], v[144:147]
	v_mfma_f32_16x16x32_bf16 v[132:135], v[80:83], v[168:171], v[132:135]
	v_mfma_f32_16x16x32_bf16 v[128:131], v[152:155], v[168:171], v[128:131]
	v_mfma_f32_16x16x32_bf16 v[116:119], v[80:83], v[186:189], v[116:119]
	v_mfma_f32_16x16x32_bf16 v[112:115], v[152:155], v[186:189], v[112:115]
	v_mfma_f32_16x16x32_bf16 v[100:103], v[80:83], v[194:197], v[100:103]
	v_mfma_f32_16x16x32_bf16 v[96:99], v[152:155], v[194:197], v[96:99]
	v_mfma_f32_16x16x32_bf16 v[148:151], v[84:87], v[164:167], v[148:151]
	v_mfma_f32_16x16x32_bf16 v[144:147], v[156:159], v[164:167], v[144:147]
	v_mfma_f32_16x16x32_bf16 v[132:135], v[84:87], v[172:175], v[132:135]
	v_mfma_f32_16x16x32_bf16 v[128:131], v[156:159], v[172:175], v[128:131]
	v_mfma_f32_16x16x32_bf16 v[116:119], v[84:87], v[190:193], v[116:119]
	v_mfma_f32_16x16x32_bf16 v[112:115], v[156:159], v[190:193], v[112:115]
	v_mfma_f32_16x16x32_bf16 v[100:103], v[84:87], v[198:201], v[100:103]
	v_mfma_f32_16x16x32_bf16 v[96:99], v[156:159], v[198:201], v[96:99]
	s_barrier
	s_add_i32 s16, s41, s28
	v_lshl_add_u64 v[204:205], v[204:205], 0, s[24:25]
	s_mov_b32 m0, s16
	ds_read_b128 v[160:163], v203 offset:49152
	ds_read_b128 v[164:167], v203 offset:50176
	ds_read_b128 v[168:171], v203 offset:51200
	ds_read_b128 v[172:175], v203 offset:52224
	ds_read_b128 v[186:189], v203 offset:53248
	ds_read_b128 v[190:193], v203 offset:54272
	ds_read_b128 v[194:197], v203 offset:55296
	ds_read_b128 v[198:201], v203 offset:56320
	global_load_lds_dwordx4 v[204:205], off
	s_add_i32 m0, s16, 0x2000
	s_add_u32 s8, s8, 0x80080
	v_lshl_add_u64 v[204:205], v[206:207], 0, s[24:25]
	s_addc_u32 s9, s9, 0
	s_add_i32 s16, s42, s28
	global_load_lds_dwordx4 v[204:205], off
	v_lshl_add_u64 v[204:205], s[8:9], 0, v[224:225]
	s_mov_b32 m0, s16
	s_nop 0
	global_load_lds_dwordx4 v[204:205], off
	v_lshl_add_u64 v[204:205], s[8:9], 0, v[176:177]
	s_add_i32 m0, s16, 0x2000
	s_nop 0
	global_load_lds_dwordx4 v[204:205], off
	v_lshl_add_u64 v[204:205], v[208:209], 0, s[24:25]
	s_mov_b32 m0, s18
	s_nop 0
	global_load_lds_dwordx4 v[204:205], off
	v_lshl_add_u64 v[204:205], v[210:211], 0, s[24:25]
	s_mov_b32 m0, s19
	s_nop 0
	global_load_lds_dwordx4 v[204:205], off
	s_waitcnt vmcnt(8)
	s_waitcnt lgkmcnt(0)
	s_barrier
	s_waitcnt lgkmcnt(0)
	v_mfma_f32_16x16x32_bf16 v[92:95], v[48:51], v[160:163], v[92:95]
	v_mfma_f32_16x16x32_bf16 v[88:91], v[64:67], v[160:163], v[88:91]
	v_mfma_f32_16x16x32_bf16 v[60:63], v[48:51], v[168:171], v[60:63]
	v_mfma_f32_16x16x32_bf16 v[56:59], v[64:67], v[168:171], v[56:59]
	v_mfma_f32_16x16x32_bf16 v[28:31], v[48:51], v[186:189], v[28:31]
	v_mfma_f32_16x16x32_bf16 v[24:27], v[64:67], v[186:189], v[24:27]
	v_mfma_f32_16x16x32_bf16 v[12:15], v[48:51], v[194:197], v[12:15]
	v_mfma_f32_16x16x32_bf16 v[8:11], v[64:67], v[194:197], v[8:11]
	v_mfma_f32_16x16x32_bf16 v[92:95], v[52:55], v[164:167], v[92:95]
	v_mfma_f32_16x16x32_bf16 v[88:91], v[68:71], v[164:167], v[88:91]
	v_mfma_f32_16x16x32_bf16 v[60:63], v[52:55], v[172:175], v[60:63]
	v_mfma_f32_16x16x32_bf16 v[56:59], v[68:71], v[172:175], v[56:59]
	v_mfma_f32_16x16x32_bf16 v[28:31], v[52:55], v[190:193], v[28:31]
	v_mfma_f32_16x16x32_bf16 v[24:27], v[68:71], v[190:193], v[24:27]
	v_mfma_f32_16x16x32_bf16 v[12:15], v[52:55], v[198:201], v[12:15]
	v_mfma_f32_16x16x32_bf16 v[8:11], v[68:71], v[198:201], v[8:11]
	v_mfma_f32_16x16x32_bf16 v[40:43], v[80:83], v[160:163], v[40:43]
	v_mfma_f32_16x16x32_bf16 v[68:71], v[84:87], v[164:167], v[40:43]
	v_mfma_f32_16x16x32_bf16 v[40:43], v[152:155], v[160:163], v[44:47]
	v_mfma_f32_16x16x32_bf16 v[36:39], v[80:83], v[168:171], v[36:39]
	v_mfma_f32_16x16x32_bf16 v[32:35], v[152:155], v[168:171], v[32:35]
	v_mfma_f32_16x16x32_bf16 v[20:23], v[80:83], v[186:189], v[20:23]
	v_mfma_f32_16x16x32_bf16 v[16:19], v[152:155], v[186:189], v[16:19]
	v_mfma_f32_16x16x32_bf16 v[4:7], v[80:83], v[194:197], v[4:7]
	v_mfma_f32_16x16x32_bf16 v[0:3], v[152:155], v[194:197], v[0:3]
	v_mfma_f32_16x16x32_bf16 v[64:67], v[156:159], v[164:167], v[40:43]
	v_mfma_f32_16x16x32_bf16 v[36:39], v[84:87], v[172:175], v[36:39]
	v_mfma_f32_16x16x32_bf16 v[32:35], v[156:159], v[172:175], v[32:35]
	v_mfma_f32_16x16x32_bf16 v[20:23], v[84:87], v[190:193], v[20:23]
	v_mfma_f32_16x16x32_bf16 v[16:19], v[156:159], v[190:193], v[16:19]
	v_mfma_f32_16x16x32_bf16 v[4:7], v[84:87], v[198:201], v[4:7]
	v_mfma_f32_16x16x32_bf16 v[0:3], v[156:159], v[198:201], v[0:3]
	s_barrier
	s_add_u32 s12, s12, 0x100
	s_addc_u32 s13, s13, 0
	s_add_u32 s31, s31, 0x100
	s_addc_u32 s33, s33, 0
	s_cmp_ge_i32 s40, s27
	s_mov_b32 s8, s40
	s_cbranch_scc0 .LBB0_2404
